# conv phase item mapping: adjacent waves of a workgroup take vertically adjacent row groups of the same channel range so the shared halo rows of A hit in cache (A traffic 2x -> ~1.5x)
# baseline (speedup 1.0000x reference)
; __device__ __forceinline__ void phase_conv(KP p, int l, int tid) {
;     ...
;   for (int it = blockIdx.x * NTH + tid; it < total; it += gridDim.x * NTH) {
;     const int cc = it % 1408; const int rs = it / 1408; const int sgm = rs & 3, r0 = (rs >> 2) * RB; const int c0 = cc * 4;
;     f32x4 w[9];
; #pragma unroll
;     for (int k = 0; k < 9; ++k) w[k] = *(const f32x4*)(cw + k * DFF + c0);
;     const f32x4 bsv = *(const f32x4*)(cbias + c0);
;     const bf16_t* rowp[RB + 2]; bool rv[RB + 2];
; #pragma unroll
;     for (int di = 0; di < RB + 2; ++di) { const int rr = r0 + di - 1; rv[di] = (rr >= 0) && (rr < 256); const int rc = rr < 0 ? 0 : (rr > 255 ? 255 : rr); rowp[di] = A + (size_t)(rc * 64) * DFF + c0; }
;     float win[3][RB + 2][4];
;     const int j0 = sgm * 16;
;     {
;       u32x2 ra[2][RB + 2];
; #pragma unroll
;       for (int s = 0; s < 2; ++s) { const int col = j0 - 1 + s; const int cl = col < 0 ? 0 : col;
; #pragma unroll
;         for (int di = 0; di < RB + 2; ++di) ra[s][di] = *(const u32x2*)(rowp[di] + (size_t)cl * DFF); }
; #pragma unroll
;       for (int s = 0; s < 2; ++s) { const int col = j0 - 1 + s;
; #pragma unroll
;         for (int di = 0; di < RB + 2; ++di) { const bool ok = rv[di] && (col >= 0); unpack4(ra[s][di], win[s][di]);
; #pragma unroll
;           for (int k = 0; k < 4; ++k) win[s][di][k] = ok ? win[s][di][k] : 0.f; } }
;     }
; #pragma unroll 1
;     for (int jb = j0; jb < j0 + 16; jb += CB) {
;       u32x2 an[CB][RB + 2], ur[CB][RB];
; #pragma unroll
;       for (int q = 0; q < CB; ++q) { const int col = jb + q + 1; const int cl = col > 63 ? 63 : col;
; #pragma unroll
;         for (int di = 0; di < RB + 2; ++di) an[q][di] = *(const u32x2*)(rowp[di] + (size_t)cl * DFF);
; #pragma unroll
;         for (int rr = 0; rr < RB; ++rr) ur[q][rr] = *(const u32x2*)(U + (size_t)((r0 + rr) * 64 + jb + q) * DFF + c0); }
.Lcv_item:
	v_lshrrev_b32_e32 v222, 7, v142
	v_mul_u32_u24_e32 v223, 0xba3, v222
	v_lshrrev_b32_e32 v223, 16, v223
	v_mul_u32_u24_e32 v224, 22, v223
	v_sub_u32_e32 v224, v222, v224
	v_and_b32_e32 v225, 63, v142
	v_lshl_add_u32 v224, v224, 6, v225
	v_bfe_u32 v225, v142, 6, 1
	v_lshrrev_b32_e32 v222, 2, v223
	v_lshl_add_u32 v222, v222, 1, v225
	v_and_b32_e32 v225, 3, v223
	v_lshl_or_b32 v222, v222, 2, v225
	v_lshlrev_b32_e32 v223, 3, v224
	v_lshlrev_b32_e32 v224, 4, v224
	global_load_dwordx4 v[0:3], v224, s[20:21]
	v_add_u32_e32 v225, 0x5800, v224
	global_load_dwordx4 v[4:7], v225, s[20:21]
	v_add_u32_e32 v225, 0xb000, v224
	global_load_dwordx4 v[8:11], v225, s[20:21]
	v_add_u32_e32 v225, 0x10800, v224
	global_load_dwordx4 v[12:15], v225, s[20:21]
	v_add_u32_e32 v225, 0x16000, v224
	global_load_dwordx4 v[16:19], v225, s[20:21]
	v_add_u32_e32 v225, 0x1b800, v224
	global_load_dwordx4 v[20:23], v225, s[20:21]
	v_add_u32_e32 v225, 0x21000, v224
	global_load_dwordx4 v[24:27], v225, s[20:21]
	v_add_u32_e32 v225, 0x26800, v224
	global_load_dwordx4 v[28:31], v225, s[20:21]
	v_add_u32_e32 v225, 0x2c000, v224
	global_load_dwordx4 v[32:35], v225, s[20:21]
	global_load_dwordx4 v[36:39], v224, s[22:23]
	v_and_b32_e32 v224, 3, v222
	v_lshrrev_b32_e32 v222, 1, v222
	v_and_b32_e32 v222, -2, v222
	v_cmp_lt_u32_e32 vcc, 0, v222
	s_nop 1
	v_cndmask_b32_e32 v200, 0, v186, vcc
	v_mov_b32_e32 v201, v200
	v_cmp_gt_u32_e32 vcc, 0xfe, v222
	s_nop 1
	v_cndmask_b32_e32 v202, 0, v186, vcc
	v_mov_b32_e32 v203, v202
	v_sub_u32_e64 v225, v222, 1 clamp
	v_mul_u32_u24_e32 v206, 0xb0000, v225
	v_mul_u32_u24_e32 v207, 0xb0000, v222
	v_add_u32_e32 v208, 0xb0000, v207
	v_add_u32_e32 v225, 2, v222
	v_min_u32_e32 v225, 0xff, v225
	v_mul_u32_u24_e32 v209, 0xb0000, v225
	v_add_u32_e32 v206, v206, v223
	v_add_u32_e32 v207, v207, v223
	v_add_u32_e32 v208, v208, v223
	v_add_u32_e32 v209, v209, v223
	v_lshlrev_b32_e32 v224, 4, v224
	v_mul_u32_u24_e32 v210, 0x2c00, v224
	v_cmp_lt_u32_e32 vcc, 0, v224
	s_nop 1
	v_cndmask_b32_e32 v204, 0, v186, vcc
	v_mov_b32_e32 v205, v204
	v_sub_u32_e64 v225, v224, 1 clamp
	v_mul_u32_u24_e32 v225, 0x2c00, v225
	v_add_u32_e32 v212, v206, v225
	global_load_dwordx2 v[96:97], v212, s[6:7]
	v_add_u32_e32 v213, v207, v225
	global_load_dwordx2 v[98:99], v213, s[6:7]
	v_add_u32_e32 v214, v208, v225
	global_load_dwordx2 v[100:101], v214, s[6:7]
	v_add_u32_e32 v215, v209, v225
	global_load_dwordx2 v[102:103], v215, s[6:7]
	v_add_u32_e32 v212, v206, v210
	global_load_dwordx2 v[88:89], v212, s[6:7]
	v_add_u32_e32 v213, v207, v210
	global_load_dwordx2 v[90:91], v213, s[6:7]
	v_add_u32_e32 v214, v208, v210
	global_load_dwordx2 v[92:93], v214, s[6:7]
	v_add_u32_e32 v215, v209, v210
	global_load_dwordx2 v[94:95], v215, s[6:7]
	s_waitcnt vmcnt(0)
	v_lshlrev_b32_e32 v40, 16, v96
	v_and_b32_e32 v41, 0xffff0000, v96
	v_lshlrev_b32_e32 v42, 16, v97
	v_and_b32_e32 v43, 0xffff0000, v97
	v_lshlrev_b32_e32 v44, 16, v98
	v_and_b32_e32 v45, 0xffff0000, v98
	v_lshlrev_b32_e32 v46, 16, v99
	v_and_b32_e32 v47, 0xffff0000, v99
	v_lshlrev_b32_e32 v48, 16, v100
	v_and_b32_e32 v49, 0xffff0000, v100
	v_lshlrev_b32_e32 v50, 16, v101
	v_and_b32_e32 v51, 0xffff0000, v101
	v_lshlrev_b32_e32 v52, 16, v102
	v_and_b32_e32 v53, 0xffff0000, v102
	v_lshlrev_b32_e32 v54, 16, v103
	v_and_b32_e32 v55, 0xffff0000, v103
	v_pk_mul_f32 v[40:41], v[40:41], v[200:201]
	v_pk_mul_f32 v[42:43], v[42:43], v[200:201]
	v_pk_mul_f32 v[52:53], v[52:53], v[202:203]
	v_pk_mul_f32 v[54:55], v[54:55], v[202:203]
	v_pk_mul_f32 v[40:41], v[40:41], v[204:205]
	v_pk_mul_f32 v[42:43], v[42:43], v[204:205]
	v_pk_mul_f32 v[44:45], v[44:45], v[204:205]
	v_pk_mul_f32 v[46:47], v[46:47], v[204:205]
	v_pk_mul_f32 v[48:49], v[48:49], v[204:205]
	v_pk_mul_f32 v[50:51], v[50:51], v[204:205]
	v_pk_mul_f32 v[52:53], v[52:53], v[204:205]
	v_pk_mul_f32 v[54:55], v[54:55], v[204:205]
	v_lshlrev_b32_e32 v56, 16, v88
	v_and_b32_e32 v57, 0xffff0000, v88
	v_lshlrev_b32_e32 v58, 16, v89
	v_and_b32_e32 v59, 0xffff0000, v89
	v_lshlrev_b32_e32 v60, 16, v90
	v_and_b32_e32 v61, 0xffff0000, v90
	v_lshlrev_b32_e32 v62, 16, v91
	v_and_b32_e32 v63, 0xffff0000, v91
	v_lshlrev_b32_e32 v64, 16, v92
	v_and_b32_e32 v65, 0xffff0000, v92
	v_lshlrev_b32_e32 v66, 16, v93
	v_and_b32_e32 v67, 0xffff0000, v93
	v_lshlrev_b32_e32 v68, 16, v94
	v_and_b32_e32 v69, 0xffff0000, v94
	v_lshlrev_b32_e32 v70, 16, v95
	v_and_b32_e32 v71, 0xffff0000, v95
	v_pk_mul_f32 v[56:57], v[56:57], v[200:201]
	v_pk_mul_f32 v[58:59], v[58:59], v[200:201]
	v_pk_mul_f32 v[68:69], v[68:69], v[202:203]
	v_pk_mul_f32 v[70:71], v[70:71], v[202:203]
	v_add_u32_e32 v211, 0x2c00, v210
	v_add_u32_e32 v212, v206, v211
	global_load_dwordx2 v[88:89], v212, s[6:7]
	v_add_u32_e32 v213, v207, v211
	global_load_dwordx2 v[90:91], v213, s[6:7]
	v_add_u32_e32 v214, v208, v211
	global_load_dwordx2 v[92:93], v214, s[6:7]
	v_add_u32_e32 v215, v209, v211
	global_load_dwordx2 v[94:95], v215, s[6:7]
	v_add_u32_e32 v216, v207, v210
	global_load_dwordx2 v[112:113], v216, s[8:9]
	v_add_u32_e32 v217, v208, v210
	global_load_dwordx2 v[114:115], v217, s[8:9]
	v_add_u32_e32 v210, 0x2c00, v210
	v_add_u32_e32 v211, 0x2c00, v210
	v_add_u32_e32 v212, v206, v211
	global_load_dwordx2 v[96:97], v212, s[6:7]
	v_add_u32_e32 v213, v207, v211
	global_load_dwordx2 v[98:99], v213, s[6:7]
	v_add_u32_e32 v214, v208, v211
	global_load_dwordx2 v[100:101], v214, s[6:7]
	v_add_u32_e32 v215, v209, v211
	global_load_dwordx2 v[102:103], v215, s[6:7]
	v_add_u32_e32 v218, v207, v210
	global_load_dwordx2 v[116:117], v218, s[8:9]
	v_add_u32_e32 v219, v208, v210
	global_load_dwordx2 v[118:119], v219, s[8:9]
	v_cmp_gt_u32_e32 vcc, 48, v224
	s_nop 1
	v_cndmask_b32_e32 v204, 0, v186, vcc
	v_mov_b32_e32 v205, v204
	v_add_u32_e32 v210, 0x2c00, v210
	v_add_u32_e32 v211, 0x2c00, v210
	v_add_u32_e32 v212, v206, v211
	global_load_dwordx2 v[104:105], v212, s[6:7]
	v_add_u32_e32 v213, v207, v211
	global_load_dwordx2 v[106:107], v213, s[6:7]
	v_add_u32_e32 v214, v208, v211
	global_load_dwordx2 v[108:109], v214, s[6:7]
	v_add_u32_e32 v215, v209, v211
	global_load_dwordx2 v[110:111], v215, s[6:7]
	v_add_u32_e32 v220, v207, v210
	global_load_dwordx2 v[120:121], v220, s[8:9]
	v_add_u32_e32 v221, v208, v210
	global_load_dwordx2 v[122:123], v221, s[8:9]
	s_waitcnt vmcnt(12)
; __device__ __forceinline__ float gelu_as(float v) {
;   const float av = fabsf(v); const float t = __builtin_amdgcn_rcpf(av * 0.2316418882f + 1.0f);
;   float q = t * 0.5307027145f + (-0.7265760135f); q = q * t + 0.7107068705f; q = q * t + (-0.142248368f); q = q * t + 0.127414796f; q = q * t;
;   const float e = __builtin_amdgcn_exp2f((v * v) * (-0.72134752044f));
;   const float m = v * (q * e);
;   return v < 0.f ? m : v - m;
; }
; __device__ __forceinline__ void phase_conv(KP p, int l, int tid) {
;     ...
;         for (int di = 0; di < RB + 2; ++di) { const bool ok = rv[di] && (col < 64); unpack4(an[q][di], win[2][di]);
; #pragma unroll
;           for (int k = 0; k < 4; ++k) win[2][di][k] = ok ? win[2][di][k] : 0.f; }
; #pragma unroll
;         for (int rr = 0; rr < RB; ++rr) {
;           float uv[4]; unpack4(ur[q][rr], uv);
;           float o[4];
; #pragma unroll
;           for (int k = 0; k < 4; ++k) {
;             float a = bsv[k];
; #pragma unroll
;             for (int di = 0; di < 3; ++di)
; #pragma unroll
;               for (int dj = 0; dj < 3; ++dj) a += win[dj][rr + di][k] * w[di * 3 + dj][k];
;             o[k] = gelu_as(a) * uv[k];
	v_lshlrev_b32_e32 v72, 16, v88
	v_and_b32_e32 v73, 0xffff0000, v88
	v_lshlrev_b32_e32 v74, 16, v89
	v_and_b32_e32 v75, 0xffff0000, v89
	v_lshlrev_b32_e32 v76, 16, v90
	v_and_b32_e32 v77, 0xffff0000, v90
	v_lshlrev_b32_e32 v78, 16, v91
	v_and_b32_e32 v79, 0xffff0000, v91
	v_lshlrev_b32_e32 v80, 16, v92
	v_and_b32_e32 v81, 0xffff0000, v92
	v_lshlrev_b32_e32 v82, 16, v93
	v_and_b32_e32 v83, 0xffff0000, v93
	v_lshlrev_b32_e32 v84, 16, v94
	v_and_b32_e32 v85, 0xffff0000, v94
	v_lshlrev_b32_e32 v86, 16, v95
	v_and_b32_e32 v87, 0xffff0000, v95
	v_pk_mul_f32 v[72:73], v[72:73], v[200:201]
	v_pk_mul_f32 v[74:75], v[74:75], v[200:201]
	v_pk_mul_f32 v[84:85], v[84:85], v[202:203]
	v_pk_mul_f32 v[86:87], v[86:87], v[202:203]
	v_lshlrev_b32_e32 v124, 16, v112
	v_and_b32_e32 v125, 0xffff0000, v112
	v_lshlrev_b32_e32 v126, 16, v113
	v_and_b32_e32 v127, 0xffff0000, v113
	v_lshlrev_b32_e32 v128, 16, v114
	v_and_b32_e32 v129, 0xffff0000, v114
	v_lshlrev_b32_e32 v130, 16, v115
	v_and_b32_e32 v131, 0xffff0000, v115
	v_pk_fma_f32 v[148:149], v[40:41], v[0:1], v[36:37]
	v_pk_fma_f32 v[150:151], v[42:43], v[2:3], v[38:39]
	v_pk_fma_f32 v[152:153], v[44:45], v[0:1], v[36:37]
	v_pk_fma_f32 v[154:155], v[46:47], v[2:3], v[38:39]
	v_pk_fma_f32 v[148:149], v[56:57], v[4:5], v[148:149]
	v_pk_fma_f32 v[150:151], v[58:59], v[6:7], v[150:151]
	v_pk_fma_f32 v[152:153], v[60:61], v[4:5], v[152:153]
	v_pk_fma_f32 v[154:155], v[62:63], v[6:7], v[154:155]
	v_pk_fma_f32 v[148:149], v[72:73], v[8:9], v[148:149]
	v_pk_fma_f32 v[150:151], v[74:75], v[10:11], v[150:151]
	v_pk_fma_f32 v[152:153], v[76:77], v[8:9], v[152:153]
	v_pk_fma_f32 v[154:155], v[78:79], v[10:11], v[154:155]
	v_pk_fma_f32 v[148:149], v[44:45], v[12:13], v[148:149]
	v_pk_fma_f32 v[150:151], v[46:47], v[14:15], v[150:151]
	v_pk_fma_f32 v[152:153], v[48:49], v[12:13], v[152:153]
	v_pk_fma_f32 v[154:155], v[50:51], v[14:15], v[154:155]
	v_pk_fma_f32 v[148:149], v[60:61], v[16:17], v[148:149]
	v_pk_fma_f32 v[150:151], v[62:63], v[18:19], v[150:151]
	v_pk_fma_f32 v[152:153], v[64:65], v[16:17], v[152:153]
	v_pk_fma_f32 v[154:155], v[66:67], v[18:19], v[154:155]
	v_pk_fma_f32 v[148:149], v[76:77], v[20:21], v[148:149]
	v_pk_fma_f32 v[150:151], v[78:79], v[22:23], v[150:151]
	v_pk_fma_f32 v[152:153], v[80:81], v[20:21], v[152:153]
	v_pk_fma_f32 v[154:155], v[82:83], v[22:23], v[154:155]
	v_pk_fma_f32 v[148:149], v[48:49], v[24:25], v[148:149]
	v_pk_fma_f32 v[150:151], v[50:51], v[26:27], v[150:151]
	v_pk_fma_f32 v[152:153], v[52:53], v[24:25], v[152:153]
	v_pk_fma_f32 v[154:155], v[54:55], v[26:27], v[154:155]
	v_pk_fma_f32 v[148:149], v[64:65], v[28:29], v[148:149]
	v_pk_fma_f32 v[150:151], v[66:67], v[30:31], v[150:151]
	v_pk_fma_f32 v[152:153], v[68:69], v[28:29], v[152:153]
	v_pk_fma_f32 v[154:155], v[70:71], v[30:31], v[154:155]
	v_pk_fma_f32 v[148:149], v[80:81], v[32:33], v[148:149]
	v_pk_fma_f32 v[150:151], v[82:83], v[34:35], v[150:151]
	v_pk_fma_f32 v[152:153], v[84:85], v[32:33], v[152:153]
	v_pk_fma_f32 v[154:155], v[86:87], v[34:35], v[154:155]
	v_and_b32_e32 v156, 0x7fffffff, v148
	v_and_b32_e32 v157, 0x7fffffff, v149
	v_and_b32_e32 v158, 0x7fffffff, v150
	v_and_b32_e32 v159, 0x7fffffff, v151
	v_and_b32_e32 v160, 0x7fffffff, v152
	v_and_b32_e32 v161, 0x7fffffff, v153
	v_and_b32_e32 v162, 0x7fffffff, v154
	v_and_b32_e32 v163, 0x7fffffff, v155
	v_pk_fma_f32 v[164:165], v[156:157], v[184:185], v[186:187]
	v_pk_fma_f32 v[166:167], v[158:159], v[184:185], v[186:187]
	v_pk_fma_f32 v[168:169], v[160:161], v[184:185], v[186:187]
	v_pk_fma_f32 v[170:171], v[162:163], v[184:185], v[186:187]
	v_rcp_f32_e32 v164, v164
	v_rcp_f32_e32 v165, v165
	v_rcp_f32_e32 v166, v166
	v_rcp_f32_e32 v167, v167
	v_rcp_f32_e32 v168, v168
	v_rcp_f32_e32 v169, v169
	v_rcp_f32_e32 v170, v170
	v_rcp_f32_e32 v171, v171
	v_pk_fma_f32 v[172:173], v[164:165], v[188:189], v[190:191]
	v_pk_fma_f32 v[174:175], v[166:167], v[188:189], v[190:191]
	v_pk_fma_f32 v[176:177], v[168:169], v[188:189], v[190:191]
	v_pk_fma_f32 v[178:179], v[170:171], v[188:189], v[190:191]
	v_pk_fma_f32 v[172:173], v[172:173], v[164:165], v[192:193]
	v_pk_fma_f32 v[174:175], v[174:175], v[166:167], v[192:193]
	v_pk_fma_f32 v[176:177], v[176:177], v[168:169], v[192:193]
	v_pk_fma_f32 v[178:179], v[178:179], v[170:171], v[192:193]
	v_pk_fma_f32 v[172:173], v[172:173], v[164:165], v[194:195]
	v_pk_fma_f32 v[174:175], v[174:175], v[166:167], v[194:195]
	v_pk_fma_f32 v[176:177], v[176:177], v[168:169], v[194:195]
	v_pk_fma_f32 v[178:179], v[178:179], v[170:171], v[194:195]
	v_pk_fma_f32 v[172:173], v[172:173], v[164:165], v[196:197]
	v_pk_fma_f32 v[174:175], v[174:175], v[166:167], v[196:197]
	v_pk_fma_f32 v[176:177], v[176:177], v[168:169], v[196:197]
	v_pk_fma_f32 v[178:179], v[178:179], v[170:171], v[196:197]
	v_pk_mul_f32 v[172:173], v[172:173], v[164:165]
	v_pk_mul_f32 v[174:175], v[174:175], v[166:167]
	v_pk_mul_f32 v[176:177], v[176:177], v[168:169]
	v_pk_mul_f32 v[178:179], v[178:179], v[170:171]
	v_pk_mul_f32 v[164:165], v[148:149], v[148:149]
	v_pk_mul_f32 v[166:167], v[150:151], v[150:151]
	v_pk_mul_f32 v[168:169], v[152:153], v[152:153]
	v_pk_mul_f32 v[170:171], v[154:155], v[154:155]
	v_pk_mul_f32 v[164:165], v[164:165], v[198:199]
	v_pk_mul_f32 v[166:167], v[166:167], v[198:199]
	v_pk_mul_f32 v[168:169], v[168:169], v[198:199]
	v_pk_mul_f32 v[170:171], v[170:171], v[198:199]
	v_exp_f32_e32 v164, v164
	v_exp_f32_e32 v165, v165
	v_exp_f32_e32 v166, v166
	v_exp_f32_e32 v167, v167
	v_exp_f32_e32 v168, v168
	v_exp_f32_e32 v169, v169
	v_exp_f32_e32 v170, v170
	v_exp_f32_e32 v171, v171
	v_pk_mul_f32 v[172:173], v[172:173], v[164:165]
	v_pk_mul_f32 v[174:175], v[174:175], v[166:167]
; __device__ __forceinline__ unsigned cvt_pk_bf16(float lo, float hi) { unsigned r; asm volatile("v_cvt_pk_bf16_f32 %0, %1, %2" : "=v"(r) : "v"(lo), "v"(hi)); return r; }
; __device__ __forceinline__ float gelu_as(float v) {
;   const float av = fabsf(v); const float t = __builtin_amdgcn_rcpf(av * 0.2316418882f + 1.0f);
;   float q = t * 0.5307027145f + (-0.7265760135f); q = q * t + 0.7107068705f; q = q * t + (-0.142248368f); q = q * t + 0.127414796f; q = q * t;
;   const float e = __builtin_amdgcn_exp2f((v * v) * (-0.72134752044f));
;   const float m = v * (q * e);
;   return v < 0.f ? m : v - m;
; }
; __device__ __forceinline__ void phase_conv(KP p, int l, int tid) {
;     ...
;         for (int di = 0; di < RB + 2; ++di) { const bool ok = rv[di] && (col < 64); unpack4(an[q][di], win[2][di]);
; #pragma unroll
;           for (int k = 0; k < 4; ++k) win[2][di][k] = ok ? win[2][di][k] : 0.f; }
; #pragma unroll
;         for (int rr = 0; rr < RB; ++rr) {
;           float uv[4]; unpack4(ur[q][rr], uv);
;           float o[4];
; #pragma unroll
;           for (int k = 0; k < 4; ++k) {
;             float a = bsv[k];
; #pragma unroll
;             for (int di = 0; di < 3; ++di)
; #pragma unroll
;               for (int dj = 0; dj < 3; ++dj) a += win[dj][rr + di][k] * w[di * 3 + dj][k];
;             o[k] = gelu_as(a) * uv[k];
;           }
;           u32x2 ow; ow.x = cvt_pk_bf16(o[0], o[1]); ow.y = cvt_pk_bf16(o[2], o[3]);
;           *(u32x2*)(G + (size_t)((r0 + rr) * 64 + jb + q) * DFF + c0) = ow;
;         }
; #pragma unroll
;         for (int di = 0; di < RB + 2; ++di)
; #pragma unroll
;           for (int k = 0; k < 4; ++k) { win[0][di][k] = win[1][di][k]; win[1][di][k] = win[2][di][k]; }
	v_pk_mul_f32 v[176:177], v[176:177], v[168:169]
	v_pk_mul_f32 v[178:179], v[178:179], v[170:171]
	v_pk_mul_f32 v[172:173], v[156:157], v[172:173]
	v_pk_mul_f32 v[174:175], v[158:159], v[174:175]
	v_pk_mul_f32 v[176:177], v[160:161], v[176:177]
	v_pk_mul_f32 v[178:179], v[162:163], v[178:179]
	v_max_f32_e32 v164, 0, v148
	v_max_f32_e32 v165, 0, v149
	v_max_f32_e32 v166, 0, v150
	v_max_f32_e32 v167, 0, v151
	v_max_f32_e32 v168, 0, v152
	v_max_f32_e32 v169, 0, v153
	v_max_f32_e32 v170, 0, v154
	v_max_f32_e32 v171, 0, v155
	v_pk_add_f32 v[164:165], v[164:165], v[172:173] neg_lo:[0,1] neg_hi:[0,1]
	v_pk_add_f32 v[166:167], v[166:167], v[174:175] neg_lo:[0,1] neg_hi:[0,1]
	v_pk_add_f32 v[168:169], v[168:169], v[176:177] neg_lo:[0,1] neg_hi:[0,1]
	v_pk_add_f32 v[170:171], v[170:171], v[178:179] neg_lo:[0,1] neg_hi:[0,1]
	v_pk_mul_f32 v[164:165], v[164:165], v[124:125]
	v_pk_mul_f32 v[166:167], v[166:167], v[126:127]
	v_pk_mul_f32 v[168:169], v[168:169], v[128:129]
	v_pk_mul_f32 v[170:171], v[170:171], v[130:131]
	v_cvt_pk_bf16_f32 v156, v164, v165
	v_cvt_pk_bf16_f32 v157, v166, v167
	v_cvt_pk_bf16_f32 v158, v168, v169
	v_cvt_pk_bf16_f32 v159, v170, v171
	global_store_dwordx2 v216, v[156:157], s[10:11]
	global_store_dwordx2 v217, v[158:159], s[10:11]
	v_add_u32_e32 v210, 0x2c00, v210
	v_add_u32_e32 v211, 0x2c00, v210
	v_add_u32_e32 v212, v206, v211
	global_load_dwordx2 v[88:89], v212, s[6:7]
	v_add_u32_e32 v213, v207, v211
	global_load_dwordx2 v[90:91], v213, s[6:7]
	v_add_u32_e32 v214, v208, v211
	global_load_dwordx2 v[92:93], v214, s[6:7]
	v_add_u32_e32 v215, v209, v211
	global_load_dwordx2 v[94:95], v215, s[6:7]
	v_add_u32_e32 v216, v207, v210
	global_load_dwordx2 v[112:113], v216, s[8:9]
	v_add_u32_e32 v217, v208, v210
	global_load_dwordx2 v[114:115], v217, s[8:9]
	s_waitcnt vmcnt(14)
	v_lshlrev_b32_e32 v40, 16, v96
	v_and_b32_e32 v41, 0xffff0000, v96
	v_lshlrev_b32_e32 v42, 16, v97
	v_and_b32_e32 v43, 0xffff0000, v97
	v_lshlrev_b32_e32 v44, 16, v98
	v_and_b32_e32 v45, 0xffff0000, v98
	v_lshlrev_b32_e32 v46, 16, v99
	v_and_b32_e32 v47, 0xffff0000, v99
	v_lshlrev_b32_e32 v48, 16, v100
	v_and_b32_e32 v49, 0xffff0000, v100
	v_lshlrev_b32_e32 v50, 16, v101
	v_and_b32_e32 v51, 0xffff0000, v101
	v_lshlrev_b32_e32 v52, 16, v102
	v_and_b32_e32 v53, 0xffff0000, v102
	v_lshlrev_b32_e32 v54, 16, v103
	v_and_b32_e32 v55, 0xffff0000, v103
	v_pk_mul_f32 v[40:41], v[40:41], v[200:201]
	v_pk_mul_f32 v[42:43], v[42:43], v[200:201]
	v_pk_mul_f32 v[52:53], v[52:53], v[202:203]
	v_pk_mul_f32 v[54:55], v[54:55], v[202:203]
	v_lshlrev_b32_e32 v124, 16, v116
	v_and_b32_e32 v125, 0xffff0000, v116
	v_lshlrev_b32_e32 v126, 16, v117
	v_and_b32_e32 v127, 0xffff0000, v117
	v_lshlrev_b32_e32 v128, 16, v118
	v_and_b32_e32 v129, 0xffff0000, v118
	v_lshlrev_b32_e32 v130, 16, v119
	v_and_b32_e32 v131, 0xffff0000, v119
	v_pk_fma_f32 v[148:149], v[56:57], v[0:1], v[36:37]
	v_pk_fma_f32 v[150:151], v[58:59], v[2:3], v[38:39]
	v_pk_fma_f32 v[152:153], v[60:61], v[0:1], v[36:37]
	v_pk_fma_f32 v[154:155], v[62:63], v[2:3], v[38:39]
	v_pk_fma_f32 v[148:149], v[72:73], v[4:5], v[148:149]
	v_pk_fma_f32 v[150:151], v[74:75], v[6:7], v[150:151]
	v_pk_fma_f32 v[152:153], v[76:77], v[4:5], v[152:153]
	v_pk_fma_f32 v[154:155], v[78:79], v[6:7], v[154:155]
	v_pk_fma_f32 v[148:149], v[40:41], v[8:9], v[148:149]
	v_pk_fma_f32 v[150:151], v[42:43], v[10:11], v[150:151]
	v_pk_fma_f32 v[152:153], v[44:45], v[8:9], v[152:153]
	v_pk_fma_f32 v[154:155], v[46:47], v[10:11], v[154:155]
	v_pk_fma_f32 v[148:149], v[60:61], v[12:13], v[148:149]
	v_pk_fma_f32 v[150:151], v[62:63], v[14:15], v[150:151]
	v_pk_fma_f32 v[152:153], v[64:65], v[12:13], v[152:153]
	v_pk_fma_f32 v[154:155], v[66:67], v[14:15], v[154:155]
	v_pk_fma_f32 v[148:149], v[76:77], v[16:17], v[148:149]
	v_pk_fma_f32 v[150:151], v[78:79], v[18:19], v[150:151]
	v_pk_fma_f32 v[152:153], v[80:81], v[16:17], v[152:153]
	v_pk_fma_f32 v[154:155], v[82:83], v[18:19], v[154:155]
	v_pk_fma_f32 v[148:149], v[44:45], v[20:21], v[148:149]
	v_pk_fma_f32 v[150:151], v[46:47], v[22:23], v[150:151]
	v_pk_fma_f32 v[152:153], v[48:49], v[20:21], v[152:153]
	v_pk_fma_f32 v[154:155], v[50:51], v[22:23], v[154:155]
	v_pk_fma_f32 v[148:149], v[64:65], v[24:25], v[148:149]
	v_pk_fma_f32 v[150:151], v[66:67], v[26:27], v[150:151]
	v_pk_fma_f32 v[152:153], v[68:69], v[24:25], v[152:153]
	v_pk_fma_f32 v[154:155], v[70:71], v[26:27], v[154:155]
	v_pk_fma_f32 v[148:149], v[80:81], v[28:29], v[148:149]
	v_pk_fma_f32 v[150:151], v[82:83], v[30:31], v[150:151]
	v_pk_fma_f32 v[152:153], v[84:85], v[28:29], v[152:153]
	v_pk_fma_f32 v[154:155], v[86:87], v[30:31], v[154:155]
	v_pk_fma_f32 v[148:149], v[48:49], v[32:33], v[148:149]
	v_pk_fma_f32 v[150:151], v[50:51], v[34:35], v[150:151]
	v_pk_fma_f32 v[152:153], v[52:53], v[32:33], v[152:153]
	v_pk_fma_f32 v[154:155], v[54:55], v[34:35], v[154:155]
	v_and_b32_e32 v156, 0x7fffffff, v148
	v_and_b32_e32 v157, 0x7fffffff, v149
	v_and_b32_e32 v158, 0x7fffffff, v150
	v_and_b32_e32 v159, 0x7fffffff, v151
	v_and_b32_e32 v160, 0x7fffffff, v152
	v_and_b32_e32 v161, 0x7fffffff, v153
	v_and_b32_e32 v162, 0x7fffffff, v154
	v_and_b32_e32 v163, 0x7fffffff, v155
	v_pk_fma_f32 v[164:165], v[156:157], v[184:185], v[186:187]
	v_pk_fma_f32 v[166:167], v[158:159], v[184:185], v[186:187]
	v_pk_fma_f32 v[168:169], v[160:161], v[184:185], v[186:187]
	v_pk_fma_f32 v[170:171], v[162:163], v[184:185], v[186:187]
	v_rcp_f32_e32 v164, v164
	v_rcp_f32_e32 v165, v165
	v_rcp_f32_e32 v166, v166
	v_rcp_f32_e32 v167, v167
	v_rcp_f32_e32 v168, v168
	v_rcp_f32_e32 v169, v169
	v_rcp_f32_e32 v170, v170
	v_rcp_f32_e32 v171, v171
; __device__ __forceinline__ unsigned cvt_pk_bf16(float lo, float hi) { unsigned r; asm volatile("v_cvt_pk_bf16_f32 %0, %1, %2" : "=v"(r) : "v"(lo), "v"(hi)); return r; }
; __device__ __forceinline__ float gelu_as(float v) {
;   const float av = fabsf(v); const float t = __builtin_amdgcn_rcpf(av * 0.2316418882f + 1.0f);
;   float q = t * 0.5307027145f + (-0.7265760135f); q = q * t + 0.7107068705f; q = q * t + (-0.142248368f); q = q * t + 0.127414796f; q = q * t;
;   const float e = __builtin_amdgcn_exp2f((v * v) * (-0.72134752044f));
;   const float m = v * (q * e);
;   return v < 0.f ? m : v - m;
; }
; __device__ __forceinline__ void phase_conv(KP p, int l, int tid) {
;     ...
;         for (int di = 0; di < RB + 2; ++di) { const bool ok = rv[di] && (col < 64); unpack4(an[q][di], win[2][di]);
; #pragma unroll
;           for (int k = 0; k < 4; ++k) win[2][di][k] = ok ? win[2][di][k] : 0.f; }
; #pragma unroll
;         for (int rr = 0; rr < RB; ++rr) {
;           float uv[4]; unpack4(ur[q][rr], uv);
;           float o[4];
; #pragma unroll
;           for (int k = 0; k < 4; ++k) {
;             float a = bsv[k];
; #pragma unroll
;             for (int di = 0; di < 3; ++di)
; #pragma unroll
;               for (int dj = 0; dj < 3; ++dj) a += win[dj][rr + di][k] * w[di * 3 + dj][k];
;             o[k] = gelu_as(a) * uv[k];
;           }
;           u32x2 ow; ow.x = cvt_pk_bf16(o[0], o[1]); ow.y = cvt_pk_bf16(o[2], o[3]);
;           *(u32x2*)(G + (size_t)((r0 + rr) * 64 + jb + q) * DFF + c0) = ow;
;         }
; #pragma unroll
;         for (int di = 0; di < RB + 2; ++di)
; #pragma unroll
;           for (int k = 0; k < 4; ++k) { win[0][di][k] = win[1][di][k]; win[1][di][k] = win[2][di][k]; }
	v_pk_fma_f32 v[172:173], v[164:165], v[188:189], v[190:191]
	v_pk_fma_f32 v[174:175], v[166:167], v[188:189], v[190:191]
	v_pk_fma_f32 v[176:177], v[168:169], v[188:189], v[190:191]
	v_pk_fma_f32 v[178:179], v[170:171], v[188:189], v[190:191]
	v_pk_fma_f32 v[172:173], v[172:173], v[164:165], v[192:193]
	v_pk_fma_f32 v[174:175], v[174:175], v[166:167], v[192:193]
	v_pk_fma_f32 v[176:177], v[176:177], v[168:169], v[192:193]
	v_pk_fma_f32 v[178:179], v[178:179], v[170:171], v[192:193]
	v_pk_fma_f32 v[172:173], v[172:173], v[164:165], v[194:195]
	v_pk_fma_f32 v[174:175], v[174:175], v[166:167], v[194:195]
	v_pk_fma_f32 v[176:177], v[176:177], v[168:169], v[194:195]
	v_pk_fma_f32 v[178:179], v[178:179], v[170:171], v[194:195]
	v_pk_fma_f32 v[172:173], v[172:173], v[164:165], v[196:197]
	v_pk_fma_f32 v[174:175], v[174:175], v[166:167], v[196:197]
	v_pk_fma_f32 v[176:177], v[176:177], v[168:169], v[196:197]
	v_pk_fma_f32 v[178:179], v[178:179], v[170:171], v[196:197]
	v_pk_mul_f32 v[172:173], v[172:173], v[164:165]
	v_pk_mul_f32 v[174:175], v[174:175], v[166:167]
	v_pk_mul_f32 v[176:177], v[176:177], v[168:169]
	v_pk_mul_f32 v[178:179], v[178:179], v[170:171]
	v_pk_mul_f32 v[164:165], v[148:149], v[148:149]
	v_pk_mul_f32 v[166:167], v[150:151], v[150:151]
	v_pk_mul_f32 v[168:169], v[152:153], v[152:153]
	v_pk_mul_f32 v[170:171], v[154:155], v[154:155]
	v_pk_mul_f32 v[164:165], v[164:165], v[198:199]
	v_pk_mul_f32 v[166:167], v[166:167], v[198:199]
	v_pk_mul_f32 v[168:169], v[168:169], v[198:199]
	v_pk_mul_f32 v[170:171], v[170:171], v[198:199]
	v_exp_f32_e32 v164, v164
	v_exp_f32_e32 v165, v165
	v_exp_f32_e32 v166, v166
	v_exp_f32_e32 v167, v167
	v_exp_f32_e32 v168, v168
	v_exp_f32_e32 v169, v169
	v_exp_f32_e32 v170, v170
	v_exp_f32_e32 v171, v171
	v_pk_mul_f32 v[172:173], v[172:173], v[164:165]
	v_pk_mul_f32 v[174:175], v[174:175], v[166:167]
	v_pk_mul_f32 v[176:177], v[176:177], v[168:169]
	v_pk_mul_f32 v[178:179], v[178:179], v[170:171]
	v_pk_mul_f32 v[172:173], v[156:157], v[172:173]
	v_pk_mul_f32 v[174:175], v[158:159], v[174:175]
	v_pk_mul_f32 v[176:177], v[160:161], v[176:177]
	v_pk_mul_f32 v[178:179], v[162:163], v[178:179]
	v_max_f32_e32 v164, 0, v148
	v_max_f32_e32 v165, 0, v149
	v_max_f32_e32 v166, 0, v150
	v_max_f32_e32 v167, 0, v151
	v_max_f32_e32 v168, 0, v152
	v_max_f32_e32 v169, 0, v153
	v_max_f32_e32 v170, 0, v154
	v_max_f32_e32 v171, 0, v155
	v_pk_add_f32 v[164:165], v[164:165], v[172:173] neg_lo:[0,1] neg_hi:[0,1]
	v_pk_add_f32 v[166:167], v[166:167], v[174:175] neg_lo:[0,1] neg_hi:[0,1]
	v_pk_add_f32 v[168:169], v[168:169], v[176:177] neg_lo:[0,1] neg_hi:[0,1]
	v_pk_add_f32 v[170:171], v[170:171], v[178:179] neg_lo:[0,1] neg_hi:[0,1]
	v_pk_mul_f32 v[164:165], v[164:165], v[124:125]
	v_pk_mul_f32 v[166:167], v[166:167], v[126:127]
	v_pk_mul_f32 v[168:169], v[168:169], v[128:129]
	v_pk_mul_f32 v[170:171], v[170:171], v[130:131]
	v_cvt_pk_bf16_f32 v156, v164, v165
	v_cvt_pk_bf16_f32 v157, v166, v167
	v_cvt_pk_bf16_f32 v158, v168, v169
	v_cvt_pk_bf16_f32 v159, v170, v171
	global_store_dwordx2 v218, v[156:157], s[10:11]
	global_store_dwordx2 v219, v[158:159], s[10:11]
	v_add_u32_e32 v210, 0x2c00, v210
	v_add_u32_e32 v211, 0x2c00, v210
	v_add_u32_e32 v212, v206, v211
	global_load_dwordx2 v[96:97], v212, s[6:7]
	v_add_u32_e32 v213, v207, v211
	global_load_dwordx2 v[98:99], v213, s[6:7]
	v_add_u32_e32 v214, v208, v211
	global_load_dwordx2 v[100:101], v214, s[6:7]
	v_add_u32_e32 v215, v209, v211
	global_load_dwordx2 v[102:103], v215, s[6:7]
	v_add_u32_e32 v218, v207, v210
	global_load_dwordx2 v[116:117], v218, s[8:9]
	v_add_u32_e32 v219, v208, v210
	global_load_dwordx2 v[118:119], v219, s[8:9]
	s_waitcnt vmcnt(16)
	v_lshlrev_b32_e32 v56, 16, v104
	v_and_b32_e32 v57, 0xffff0000, v104
	v_lshlrev_b32_e32 v58, 16, v105
	v_and_b32_e32 v59, 0xffff0000, v105
	v_lshlrev_b32_e32 v60, 16, v106
	v_and_b32_e32 v61, 0xffff0000, v106
	v_lshlrev_b32_e32 v62, 16, v107
	v_and_b32_e32 v63, 0xffff0000, v107
	v_lshlrev_b32_e32 v64, 16, v108
	v_and_b32_e32 v65, 0xffff0000, v108
	v_lshlrev_b32_e32 v66, 16, v109
	v_and_b32_e32 v67, 0xffff0000, v109
	v_lshlrev_b32_e32 v68, 16, v110
	v_and_b32_e32 v69, 0xffff0000, v110
	v_lshlrev_b32_e32 v70, 16, v111
	v_and_b32_e32 v71, 0xffff0000, v111
	v_pk_mul_f32 v[56:57], v[56:57], v[200:201]
	v_pk_mul_f32 v[58:59], v[58:59], v[200:201]
	v_pk_mul_f32 v[68:69], v[68:69], v[202:203]
	v_pk_mul_f32 v[70:71], v[70:71], v[202:203]
	v_lshlrev_b32_e32 v124, 16, v120
	v_and_b32_e32 v125, 0xffff0000, v120
	v_lshlrev_b32_e32 v126, 16, v121
	v_and_b32_e32 v127, 0xffff0000, v121
	v_lshlrev_b32_e32 v128, 16, v122
	v_and_b32_e32 v129, 0xffff0000, v122
	v_lshlrev_b32_e32 v130, 16, v123
	v_and_b32_e32 v131, 0xffff0000, v123
	v_pk_fma_f32 v[148:149], v[72:73], v[0:1], v[36:37]
	v_pk_fma_f32 v[150:151], v[74:75], v[2:3], v[38:39]
	v_pk_fma_f32 v[152:153], v[76:77], v[0:1], v[36:37]
	v_pk_fma_f32 v[154:155], v[78:79], v[2:3], v[38:39]
	v_pk_fma_f32 v[148:149], v[40:41], v[4:5], v[148:149]
	v_pk_fma_f32 v[150:151], v[42:43], v[6:7], v[150:151]
	v_pk_fma_f32 v[152:153], v[44:45], v[4:5], v[152:153]
	v_pk_fma_f32 v[154:155], v[46:47], v[6:7], v[154:155]
	v_pk_fma_f32 v[148:149], v[56:57], v[8:9], v[148:149]
	v_pk_fma_f32 v[150:151], v[58:59], v[10:11], v[150:151]
	v_pk_fma_f32 v[152:153], v[60:61], v[8:9], v[152:153]
	v_pk_fma_f32 v[154:155], v[62:63], v[10:11], v[154:155]
	v_pk_fma_f32 v[148:149], v[76:77], v[12:13], v[148:149]
	v_pk_fma_f32 v[150:151], v[78:79], v[14:15], v[150:151]
	v_pk_fma_f32 v[152:153], v[80:81], v[12:13], v[152:153]
	v_pk_fma_f32 v[154:155], v[82:83], v[14:15], v[154:155]
	v_pk_fma_f32 v[148:149], v[44:45], v[16:17], v[148:149]
; __device__ __forceinline__ unsigned cvt_pk_bf16(float lo, float hi) { unsigned r; asm volatile("v_cvt_pk_bf16_f32 %0, %1, %2" : "=v"(r) : "v"(lo), "v"(hi)); return r; }
; __device__ __forceinline__ float gelu_as(float v) {
;   const float av = fabsf(v); const float t = __builtin_amdgcn_rcpf(av * 0.2316418882f + 1.0f);
;   float q = t * 0.5307027145f + (-0.7265760135f); q = q * t + 0.7107068705f; q = q * t + (-0.142248368f); q = q * t + 0.127414796f; q = q * t;
;   const float e = __builtin_amdgcn_exp2f((v * v) * (-0.72134752044f));
;   const float m = v * (q * e);
;   return v < 0.f ? m : v - m;
; }
; __device__ __forceinline__ void phase_conv(KP p, int l, int tid) {
;     ...
;       for (int q = 0; q < CB; ++q) {
;         const int col = jb + q + 1;
; #pragma unroll
;         for (int di = 0; di < RB + 2; ++di) { const bool ok = rv[di] && (col < 64); unpack4(an[q][di], win[2][di]);
; #pragma unroll
;           for (int k = 0; k < 4; ++k) win[2][di][k] = ok ? win[2][di][k] : 0.f; }
; #pragma unroll
;         for (int rr = 0; rr < RB; ++rr) {
;           float uv[4]; unpack4(ur[q][rr], uv);
;           float o[4];
; #pragma unroll
;           for (int k = 0; k < 4; ++k) {
;             float a = bsv[k];
; #pragma unroll
;             for (int di = 0; di < 3; ++di)
; #pragma unroll
;               for (int dj = 0; dj < 3; ++dj) a += win[dj][rr + di][k] * w[di * 3 + dj][k];
;             o[k] = gelu_as(a) * uv[k];
;           }
;           u32x2 ow; ow.x = cvt_pk_bf16(o[0], o[1]); ow.y = cvt_pk_bf16(o[2], o[3]);
;           *(u32x2*)(G + (size_t)((r0 + rr) * 64 + jb + q) * DFF + c0) = ow;
;         }
; #pragma unroll
;         for (int di = 0; di < RB + 2; ++di)
; #pragma unroll
;           for (int k = 0; k < 4; ++k) { win[0][di][k] = win[1][di][k]; win[1][di][k] = win[2][di][k]; }
	v_pk_fma_f32 v[150:151], v[46:47], v[18:19], v[150:151]
	v_pk_fma_f32 v[152:153], v[48:49], v[16:17], v[152:153]
	v_pk_fma_f32 v[154:155], v[50:51], v[18:19], v[154:155]
	v_pk_fma_f32 v[148:149], v[60:61], v[20:21], v[148:149]
	v_pk_fma_f32 v[150:151], v[62:63], v[22:23], v[150:151]
	v_pk_fma_f32 v[152:153], v[64:65], v[20:21], v[152:153]
	v_pk_fma_f32 v[154:155], v[66:67], v[22:23], v[154:155]
	v_pk_fma_f32 v[148:149], v[80:81], v[24:25], v[148:149]
	v_pk_fma_f32 v[150:151], v[82:83], v[26:27], v[150:151]
	v_pk_fma_f32 v[152:153], v[84:85], v[24:25], v[152:153]
	v_pk_fma_f32 v[154:155], v[86:87], v[26:27], v[154:155]
	v_pk_fma_f32 v[148:149], v[48:49], v[28:29], v[148:149]
	v_pk_fma_f32 v[150:151], v[50:51], v[30:31], v[150:151]
	v_pk_fma_f32 v[152:153], v[52:53], v[28:29], v[152:153]
	v_pk_fma_f32 v[154:155], v[54:55], v[30:31], v[154:155]
	v_pk_fma_f32 v[148:149], v[64:65], v[32:33], v[148:149]
	v_pk_fma_f32 v[150:151], v[66:67], v[34:35], v[150:151]
	v_pk_fma_f32 v[152:153], v[68:69], v[32:33], v[152:153]
	v_pk_fma_f32 v[154:155], v[70:71], v[34:35], v[154:155]
	v_and_b32_e32 v156, 0x7fffffff, v148
	v_and_b32_e32 v157, 0x7fffffff, v149
	v_and_b32_e32 v158, 0x7fffffff, v150
	v_and_b32_e32 v159, 0x7fffffff, v151
	v_and_b32_e32 v160, 0x7fffffff, v152
	v_and_b32_e32 v161, 0x7fffffff, v153
	v_and_b32_e32 v162, 0x7fffffff, v154
	v_and_b32_e32 v163, 0x7fffffff, v155
	v_pk_fma_f32 v[164:165], v[156:157], v[184:185], v[186:187]
	v_pk_fma_f32 v[166:167], v[158:159], v[184:185], v[186:187]
	v_pk_fma_f32 v[168:169], v[160:161], v[184:185], v[186:187]
	v_pk_fma_f32 v[170:171], v[162:163], v[184:185], v[186:187]
	v_rcp_f32_e32 v164, v164
	v_rcp_f32_e32 v165, v165
	v_rcp_f32_e32 v166, v166
	v_rcp_f32_e32 v167, v167
	v_rcp_f32_e32 v168, v168
	v_rcp_f32_e32 v169, v169
	v_rcp_f32_e32 v170, v170
	v_rcp_f32_e32 v171, v171
	v_pk_fma_f32 v[172:173], v[164:165], v[188:189], v[190:191]
	v_pk_fma_f32 v[174:175], v[166:167], v[188:189], v[190:191]
	v_pk_fma_f32 v[176:177], v[168:169], v[188:189], v[190:191]
	v_pk_fma_f32 v[178:179], v[170:171], v[188:189], v[190:191]
	v_pk_fma_f32 v[172:173], v[172:173], v[164:165], v[192:193]
	v_pk_fma_f32 v[174:175], v[174:175], v[166:167], v[192:193]
	v_pk_fma_f32 v[176:177], v[176:177], v[168:169], v[192:193]
	v_pk_fma_f32 v[178:179], v[178:179], v[170:171], v[192:193]
	v_pk_fma_f32 v[172:173], v[172:173], v[164:165], v[194:195]
	v_pk_fma_f32 v[174:175], v[174:175], v[166:167], v[194:195]
	v_pk_fma_f32 v[176:177], v[176:177], v[168:169], v[194:195]
	v_pk_fma_f32 v[178:179], v[178:179], v[170:171], v[194:195]
	v_pk_fma_f32 v[172:173], v[172:173], v[164:165], v[196:197]
	v_pk_fma_f32 v[174:175], v[174:175], v[166:167], v[196:197]
	v_pk_fma_f32 v[176:177], v[176:177], v[168:169], v[196:197]
	v_pk_fma_f32 v[178:179], v[178:179], v[170:171], v[196:197]
	v_pk_mul_f32 v[172:173], v[172:173], v[164:165]
	v_pk_mul_f32 v[174:175], v[174:175], v[166:167]
	v_pk_mul_f32 v[176:177], v[176:177], v[168:169]
	v_pk_mul_f32 v[178:179], v[178:179], v[170:171]
	v_pk_mul_f32 v[164:165], v[148:149], v[148:149]
	v_pk_mul_f32 v[166:167], v[150:151], v[150:151]
	v_pk_mul_f32 v[168:169], v[152:153], v[152:153]
	v_pk_mul_f32 v[170:171], v[154:155], v[154:155]
	v_pk_mul_f32 v[164:165], v[164:165], v[198:199]
	v_pk_mul_f32 v[166:167], v[166:167], v[198:199]
	v_pk_mul_f32 v[168:169], v[168:169], v[198:199]
	v_pk_mul_f32 v[170:171], v[170:171], v[198:199]
	v_exp_f32_e32 v164, v164
	v_exp_f32_e32 v165, v165
	v_exp_f32_e32 v166, v166
	v_exp_f32_e32 v167, v167
	v_exp_f32_e32 v168, v168
	v_exp_f32_e32 v169, v169
	v_exp_f32_e32 v170, v170
	v_exp_f32_e32 v171, v171
	v_pk_mul_f32 v[172:173], v[172:173], v[164:165]
	v_pk_mul_f32 v[174:175], v[174:175], v[166:167]
	v_pk_mul_f32 v[176:177], v[176:177], v[168:169]
	v_pk_mul_f32 v[178:179], v[178:179], v[170:171]
	v_pk_mul_f32 v[172:173], v[156:157], v[172:173]
	v_pk_mul_f32 v[174:175], v[158:159], v[174:175]
	v_pk_mul_f32 v[176:177], v[160:161], v[176:177]
	v_pk_mul_f32 v[178:179], v[162:163], v[178:179]
	v_max_f32_e32 v164, 0, v148
	v_max_f32_e32 v165, 0, v149
	v_max_f32_e32 v166, 0, v150
	v_max_f32_e32 v167, 0, v151
	v_max_f32_e32 v168, 0, v152
	v_max_f32_e32 v169, 0, v153
	v_max_f32_e32 v170, 0, v154
	v_max_f32_e32 v171, 0, v155
	v_pk_add_f32 v[164:165], v[164:165], v[172:173] neg_lo:[0,1] neg_hi:[0,1]
	v_pk_add_f32 v[166:167], v[166:167], v[174:175] neg_lo:[0,1] neg_hi:[0,1]
	v_pk_add_f32 v[168:169], v[168:169], v[176:177] neg_lo:[0,1] neg_hi:[0,1]
	v_pk_add_f32 v[170:171], v[170:171], v[178:179] neg_lo:[0,1] neg_hi:[0,1]
	v_pk_mul_f32 v[164:165], v[164:165], v[124:125]
	v_pk_mul_f32 v[166:167], v[166:167], v[126:127]
	v_pk_mul_f32 v[168:169], v[168:169], v[128:129]
	v_pk_mul_f32 v[170:171], v[170:171], v[130:131]
	v_cvt_pk_bf16_f32 v156, v164, v165
	v_cvt_pk_bf16_f32 v157, v166, v167
	v_cvt_pk_bf16_f32 v158, v168, v169
	v_cvt_pk_bf16_f32 v159, v170, v171
	global_store_dwordx2 v220, v[156:157], s[10:11]
	global_store_dwordx2 v221, v[158:159], s[10:11]
	v_add_u32_e32 v210, 0x2c00, v210
	v_add_u32_e32 v211, 0x2c00, v210
	v_add_u32_e32 v212, v206, v211
	global_load_dwordx2 v[104:105], v212, s[6:7]
	v_add_u32_e32 v213, v207, v211
	global_load_dwordx2 v[106:107], v213, s[6:7]
	v_add_u32_e32 v214, v208, v211
	global_load_dwordx2 v[108:109], v214, s[6:7]
	v_add_u32_e32 v215, v209, v211
	global_load_dwordx2 v[110:111], v215, s[6:7]
	v_add_u32_e32 v220, v207, v210
	global_load_dwordx2 v[120:121], v220, s[8:9]
	v_add_u32_e32 v221, v208, v210
	global_load_dwordx2 v[122:123], v221, s[8:9]
	s_waitcnt vmcnt(16)
; __device__ __forceinline__ unsigned cvt_pk_bf16(float lo, float hi) { unsigned r; asm volatile("v_cvt_pk_bf16_f32 %0, %1, %2" : "=v"(r) : "v"(lo), "v"(hi)); return r; }
; __device__ __forceinline__ float gelu_as(float v) {
;   const float av = fabsf(v); const float t = __builtin_amdgcn_rcpf(av * 0.2316418882f + 1.0f);
;   float q = t * 0.5307027145f + (-0.7265760135f); q = q * t + 0.7107068705f; q = q * t + (-0.142248368f); q = q * t + 0.127414796f; q = q * t;
;   const float e = __builtin_amdgcn_exp2f((v * v) * (-0.72134752044f));
;   const float m = v * (q * e);
;   return v < 0.f ? m : v - m;
; }
; __device__ __forceinline__ void phase_conv(KP p, int l, int tid) {
;     ...
;       for (int q = 0; q < CB; ++q) {
;         const int col = jb + q + 1;
; #pragma unroll
;         for (int di = 0; di < RB + 2; ++di) { const bool ok = rv[di] && (col < 64); unpack4(an[q][di], win[2][di]);
; #pragma unroll
;           for (int k = 0; k < 4; ++k) win[2][di][k] = ok ? win[2][di][k] : 0.f; }
; #pragma unroll
;         for (int rr = 0; rr < RB; ++rr) {
;           float uv[4]; unpack4(ur[q][rr], uv);
;           float o[4];
; #pragma unroll
;           for (int k = 0; k < 4; ++k) {
;             float a = bsv[k];
; #pragma unroll
;             for (int di = 0; di < 3; ++di)
; #pragma unroll
;               for (int dj = 0; dj < 3; ++dj) a += win[dj][rr + di][k] * w[di * 3 + dj][k];
;             o[k] = gelu_as(a) * uv[k];
;           }
;           u32x2 ow; ow.x = cvt_pk_bf16(o[0], o[1]); ow.y = cvt_pk_bf16(o[2], o[3]);
;           *(u32x2*)(G + (size_t)((r0 + rr) * 64 + jb + q) * DFF + c0) = ow;
;         }
; #pragma unroll
;         for (int di = 0; di < RB + 2; ++di)
; #pragma unroll
;           for (int k = 0; k < 4; ++k) { win[0][di][k] = win[1][di][k]; win[1][di][k] = win[2][di][k]; }
	v_lshlrev_b32_e32 v72, 16, v88
	v_and_b32_e32 v73, 0xffff0000, v88
	v_lshlrev_b32_e32 v74, 16, v89
	v_and_b32_e32 v75, 0xffff0000, v89
	v_lshlrev_b32_e32 v76, 16, v90
	v_and_b32_e32 v77, 0xffff0000, v90
	v_lshlrev_b32_e32 v78, 16, v91
	v_and_b32_e32 v79, 0xffff0000, v91
	v_lshlrev_b32_e32 v80, 16, v92
	v_and_b32_e32 v81, 0xffff0000, v92
	v_lshlrev_b32_e32 v82, 16, v93
	v_and_b32_e32 v83, 0xffff0000, v93
	v_lshlrev_b32_e32 v84, 16, v94
	v_and_b32_e32 v85, 0xffff0000, v94
	v_lshlrev_b32_e32 v86, 16, v95
	v_and_b32_e32 v87, 0xffff0000, v95
	v_pk_mul_f32 v[72:73], v[72:73], v[200:201]
	v_pk_mul_f32 v[74:75], v[74:75], v[200:201]
	v_pk_mul_f32 v[84:85], v[84:85], v[202:203]
	v_pk_mul_f32 v[86:87], v[86:87], v[202:203]
	v_lshlrev_b32_e32 v124, 16, v112
	v_and_b32_e32 v125, 0xffff0000, v112
	v_lshlrev_b32_e32 v126, 16, v113
	v_and_b32_e32 v127, 0xffff0000, v113
	v_lshlrev_b32_e32 v128, 16, v114
	v_and_b32_e32 v129, 0xffff0000, v114
	v_lshlrev_b32_e32 v130, 16, v115
	v_and_b32_e32 v131, 0xffff0000, v115
	v_pk_fma_f32 v[148:149], v[40:41], v[0:1], v[36:37]
	v_pk_fma_f32 v[150:151], v[42:43], v[2:3], v[38:39]
	v_pk_fma_f32 v[152:153], v[44:45], v[0:1], v[36:37]
	v_pk_fma_f32 v[154:155], v[46:47], v[2:3], v[38:39]
	v_pk_fma_f32 v[148:149], v[56:57], v[4:5], v[148:149]
	v_pk_fma_f32 v[150:151], v[58:59], v[6:7], v[150:151]
	v_pk_fma_f32 v[152:153], v[60:61], v[4:5], v[152:153]
	v_pk_fma_f32 v[154:155], v[62:63], v[6:7], v[154:155]
	v_pk_fma_f32 v[148:149], v[72:73], v[8:9], v[148:149]
	v_pk_fma_f32 v[150:151], v[74:75], v[10:11], v[150:151]
	v_pk_fma_f32 v[152:153], v[76:77], v[8:9], v[152:153]
	v_pk_fma_f32 v[154:155], v[78:79], v[10:11], v[154:155]
	v_pk_fma_f32 v[148:149], v[44:45], v[12:13], v[148:149]
	v_pk_fma_f32 v[150:151], v[46:47], v[14:15], v[150:151]
	v_pk_fma_f32 v[152:153], v[48:49], v[12:13], v[152:153]
	v_pk_fma_f32 v[154:155], v[50:51], v[14:15], v[154:155]
	v_pk_fma_f32 v[148:149], v[60:61], v[16:17], v[148:149]
	v_pk_fma_f32 v[150:151], v[62:63], v[18:19], v[150:151]
	v_pk_fma_f32 v[152:153], v[64:65], v[16:17], v[152:153]
	v_pk_fma_f32 v[154:155], v[66:67], v[18:19], v[154:155]
	v_pk_fma_f32 v[148:149], v[76:77], v[20:21], v[148:149]
	v_pk_fma_f32 v[150:151], v[78:79], v[22:23], v[150:151]
	v_pk_fma_f32 v[152:153], v[80:81], v[20:21], v[152:153]
	v_pk_fma_f32 v[154:155], v[82:83], v[22:23], v[154:155]
	v_pk_fma_f32 v[148:149], v[48:49], v[24:25], v[148:149]
	v_pk_fma_f32 v[150:151], v[50:51], v[26:27], v[150:151]
	v_pk_fma_f32 v[152:153], v[52:53], v[24:25], v[152:153]
	v_pk_fma_f32 v[154:155], v[54:55], v[26:27], v[154:155]
	v_pk_fma_f32 v[148:149], v[64:65], v[28:29], v[148:149]
	v_pk_fma_f32 v[150:151], v[66:67], v[30:31], v[150:151]
	v_pk_fma_f32 v[152:153], v[68:69], v[28:29], v[152:153]
	v_pk_fma_f32 v[154:155], v[70:71], v[30:31], v[154:155]
	v_pk_fma_f32 v[148:149], v[80:81], v[32:33], v[148:149]
	v_pk_fma_f32 v[150:151], v[82:83], v[34:35], v[150:151]
	v_pk_fma_f32 v[152:153], v[84:85], v[32:33], v[152:153]
	v_pk_fma_f32 v[154:155], v[86:87], v[34:35], v[154:155]
	v_and_b32_e32 v156, 0x7fffffff, v148
	v_and_b32_e32 v157, 0x7fffffff, v149
	v_and_b32_e32 v158, 0x7fffffff, v150
	v_and_b32_e32 v159, 0x7fffffff, v151
	v_and_b32_e32 v160, 0x7fffffff, v152
	v_and_b32_e32 v161, 0x7fffffff, v153
	v_and_b32_e32 v162, 0x7fffffff, v154
	v_and_b32_e32 v163, 0x7fffffff, v155
	v_pk_fma_f32 v[164:165], v[156:157], v[184:185], v[186:187]
	v_pk_fma_f32 v[166:167], v[158:159], v[184:185], v[186:187]
	v_pk_fma_f32 v[168:169], v[160:161], v[184:185], v[186:187]
	v_pk_fma_f32 v[170:171], v[162:163], v[184:185], v[186:187]
	v_rcp_f32_e32 v164, v164
	v_rcp_f32_e32 v165, v165
	v_rcp_f32_e32 v166, v166
	v_rcp_f32_e32 v167, v167
	v_rcp_f32_e32 v168, v168
	v_rcp_f32_e32 v169, v169
	v_rcp_f32_e32 v170, v170
	v_rcp_f32_e32 v171, v171
	v_pk_fma_f32 v[172:173], v[164:165], v[188:189], v[190:191]
	v_pk_fma_f32 v[174:175], v[166:167], v[188:189], v[190:191]
	v_pk_fma_f32 v[176:177], v[168:169], v[188:189], v[190:191]
	v_pk_fma_f32 v[178:179], v[170:171], v[188:189], v[190:191]
	v_pk_fma_f32 v[172:173], v[172:173], v[164:165], v[192:193]
	v_pk_fma_f32 v[174:175], v[174:175], v[166:167], v[192:193]
	v_pk_fma_f32 v[176:177], v[176:177], v[168:169], v[192:193]
	v_pk_fma_f32 v[178:179], v[178:179], v[170:171], v[192:193]
	v_pk_fma_f32 v[172:173], v[172:173], v[164:165], v[194:195]
	v_pk_fma_f32 v[174:175], v[174:175], v[166:167], v[194:195]
	v_pk_fma_f32 v[176:177], v[176:177], v[168:169], v[194:195]
	v_pk_fma_f32 v[178:179], v[178:179], v[170:171], v[194:195]
	v_pk_fma_f32 v[172:173], v[172:173], v[164:165], v[196:197]
	v_pk_fma_f32 v[174:175], v[174:175], v[166:167], v[196:197]
	v_pk_fma_f32 v[176:177], v[176:177], v[168:169], v[196:197]
	v_pk_fma_f32 v[178:179], v[178:179], v[170:171], v[196:197]
	v_pk_mul_f32 v[172:173], v[172:173], v[164:165]
	v_pk_mul_f32 v[174:175], v[174:175], v[166:167]
	v_pk_mul_f32 v[176:177], v[176:177], v[168:169]
	v_pk_mul_f32 v[178:179], v[178:179], v[170:171]
	v_pk_mul_f32 v[164:165], v[148:149], v[148:149]
	v_pk_mul_f32 v[166:167], v[150:151], v[150:151]
	v_pk_mul_f32 v[168:169], v[152:153], v[152:153]
	v_pk_mul_f32 v[170:171], v[154:155], v[154:155]
	v_pk_mul_f32 v[164:165], v[164:165], v[198:199]
	v_pk_mul_f32 v[166:167], v[166:167], v[198:199]
	v_pk_mul_f32 v[168:169], v[168:169], v[198:199]
	v_pk_mul_f32 v[170:171], v[170:171], v[198:199]
	v_exp_f32_e32 v164, v164
	v_exp_f32_e32 v165, v165
	v_exp_f32_e32 v166, v166
	v_exp_f32_e32 v167, v167
	v_exp_f32_e32 v168, v168
	v_exp_f32_e32 v169, v169
	v_exp_f32_e32 v170, v170
	v_exp_f32_e32 v171, v171
	v_pk_mul_f32 v[172:173], v[172:173], v[164:165]
	v_pk_mul_f32 v[174:175], v[174:175], v[166:167]
; __device__ __forceinline__ unsigned cvt_pk_bf16(float lo, float hi) { unsigned r; asm volatile("v_cvt_pk_bf16_f32 %0, %1, %2" : "=v"(r) : "v"(lo), "v"(hi)); return r; }
; __device__ __forceinline__ float gelu_as(float v) {
;   const float av = fabsf(v); const float t = __builtin_amdgcn_rcpf(av * 0.2316418882f + 1.0f);
;   float q = t * 0.5307027145f + (-0.7265760135f); q = q * t + 0.7107068705f; q = q * t + (-0.142248368f); q = q * t + 0.127414796f; q = q * t;
;   const float e = __builtin_amdgcn_exp2f((v * v) * (-0.72134752044f));
;   const float m = v * (q * e);
;   return v < 0.f ? m : v - m;
; }
; __device__ __forceinline__ void phase_conv(KP p, int l, int tid) {
;     ...
;       for (int q = 0; q < CB; ++q) {
;         const int col = jb + q + 1;
; #pragma unroll
;         for (int di = 0; di < RB + 2; ++di) { const bool ok = rv[di] && (col < 64); unpack4(an[q][di], win[2][di]);
; #pragma unroll
;           for (int k = 0; k < 4; ++k) win[2][di][k] = ok ? win[2][di][k] : 0.f; }
; #pragma unroll
;         for (int rr = 0; rr < RB; ++rr) {
;           float uv[4]; unpack4(ur[q][rr], uv);
;           float o[4];
; #pragma unroll
;           for (int k = 0; k < 4; ++k) {
;             float a = bsv[k];
; #pragma unroll
;             for (int di = 0; di < 3; ++di)
; #pragma unroll
;               for (int dj = 0; dj < 3; ++dj) a += win[dj][rr + di][k] * w[di * 3 + dj][k];
;             o[k] = gelu_as(a) * uv[k];
;           }
;           u32x2 ow; ow.x = cvt_pk_bf16(o[0], o[1]); ow.y = cvt_pk_bf16(o[2], o[3]);
;           *(u32x2*)(G + (size_t)((r0 + rr) * 64 + jb + q) * DFF + c0) = ow;
;         }
; #pragma unroll
;         for (int di = 0; di < RB + 2; ++di)
; #pragma unroll
;           for (int k = 0; k < 4; ++k) { win[0][di][k] = win[1][di][k]; win[1][di][k] = win[2][di][k]; }
	v_pk_mul_f32 v[176:177], v[176:177], v[168:169]
	v_pk_mul_f32 v[178:179], v[178:179], v[170:171]
	v_pk_mul_f32 v[172:173], v[156:157], v[172:173]
	v_pk_mul_f32 v[174:175], v[158:159], v[174:175]
	v_pk_mul_f32 v[176:177], v[160:161], v[176:177]
	v_pk_mul_f32 v[178:179], v[162:163], v[178:179]
	v_max_f32_e32 v164, 0, v148
	v_max_f32_e32 v165, 0, v149
	v_max_f32_e32 v166, 0, v150
	v_max_f32_e32 v167, 0, v151
	v_max_f32_e32 v168, 0, v152
	v_max_f32_e32 v169, 0, v153
	v_max_f32_e32 v170, 0, v154
	v_max_f32_e32 v171, 0, v155
	v_pk_add_f32 v[164:165], v[164:165], v[172:173] neg_lo:[0,1] neg_hi:[0,1]
	v_pk_add_f32 v[166:167], v[166:167], v[174:175] neg_lo:[0,1] neg_hi:[0,1]
	v_pk_add_f32 v[168:169], v[168:169], v[176:177] neg_lo:[0,1] neg_hi:[0,1]
	v_pk_add_f32 v[170:171], v[170:171], v[178:179] neg_lo:[0,1] neg_hi:[0,1]
	v_pk_mul_f32 v[164:165], v[164:165], v[124:125]
	v_pk_mul_f32 v[166:167], v[166:167], v[126:127]
	v_pk_mul_f32 v[168:169], v[168:169], v[128:129]
	v_pk_mul_f32 v[170:171], v[170:171], v[130:131]
	v_cvt_pk_bf16_f32 v156, v164, v165
	v_cvt_pk_bf16_f32 v157, v166, v167
	v_cvt_pk_bf16_f32 v158, v168, v169
	v_cvt_pk_bf16_f32 v159, v170, v171
	global_store_dwordx2 v216, v[156:157], s[10:11]
	global_store_dwordx2 v217, v[158:159], s[10:11]
	v_add_u32_e32 v210, 0x2c00, v210
	v_add_u32_e32 v211, 0x2c00, v210
	v_add_u32_e32 v212, v206, v211
	global_load_dwordx2 v[88:89], v212, s[6:7]
	v_add_u32_e32 v213, v207, v211
	global_load_dwordx2 v[90:91], v213, s[6:7]
	v_add_u32_e32 v214, v208, v211
	global_load_dwordx2 v[92:93], v214, s[6:7]
	v_add_u32_e32 v215, v209, v211
	global_load_dwordx2 v[94:95], v215, s[6:7]
	v_add_u32_e32 v216, v207, v210
	global_load_dwordx2 v[112:113], v216, s[8:9]
	v_add_u32_e32 v217, v208, v210
	global_load_dwordx2 v[114:115], v217, s[8:9]
	s_waitcnt vmcnt(16)
	v_lshlrev_b32_e32 v40, 16, v96
	v_and_b32_e32 v41, 0xffff0000, v96
	v_lshlrev_b32_e32 v42, 16, v97
	v_and_b32_e32 v43, 0xffff0000, v97
	v_lshlrev_b32_e32 v44, 16, v98
	v_and_b32_e32 v45, 0xffff0000, v98
	v_lshlrev_b32_e32 v46, 16, v99
	v_and_b32_e32 v47, 0xffff0000, v99
	v_lshlrev_b32_e32 v48, 16, v100
	v_and_b32_e32 v49, 0xffff0000, v100
	v_lshlrev_b32_e32 v50, 16, v101
	v_and_b32_e32 v51, 0xffff0000, v101
	v_lshlrev_b32_e32 v52, 16, v102
	v_and_b32_e32 v53, 0xffff0000, v102
	v_lshlrev_b32_e32 v54, 16, v103
	v_and_b32_e32 v55, 0xffff0000, v103
	v_pk_mul_f32 v[40:41], v[40:41], v[200:201]
	v_pk_mul_f32 v[42:43], v[42:43], v[200:201]
	v_pk_mul_f32 v[52:53], v[52:53], v[202:203]
	v_pk_mul_f32 v[54:55], v[54:55], v[202:203]
	v_lshlrev_b32_e32 v124, 16, v116
	v_and_b32_e32 v125, 0xffff0000, v116
	v_lshlrev_b32_e32 v126, 16, v117
	v_and_b32_e32 v127, 0xffff0000, v117
	v_lshlrev_b32_e32 v128, 16, v118
	v_and_b32_e32 v129, 0xffff0000, v118
	v_lshlrev_b32_e32 v130, 16, v119
	v_and_b32_e32 v131, 0xffff0000, v119
	v_pk_fma_f32 v[148:149], v[56:57], v[0:1], v[36:37]
	v_pk_fma_f32 v[150:151], v[58:59], v[2:3], v[38:39]
	v_pk_fma_f32 v[152:153], v[60:61], v[0:1], v[36:37]
	v_pk_fma_f32 v[154:155], v[62:63], v[2:3], v[38:39]
	v_pk_fma_f32 v[148:149], v[72:73], v[4:5], v[148:149]
	v_pk_fma_f32 v[150:151], v[74:75], v[6:7], v[150:151]
	v_pk_fma_f32 v[152:153], v[76:77], v[4:5], v[152:153]
	v_pk_fma_f32 v[154:155], v[78:79], v[6:7], v[154:155]
	v_pk_fma_f32 v[148:149], v[40:41], v[8:9], v[148:149]
	v_pk_fma_f32 v[150:151], v[42:43], v[10:11], v[150:151]
	v_pk_fma_f32 v[152:153], v[44:45], v[8:9], v[152:153]
	v_pk_fma_f32 v[154:155], v[46:47], v[10:11], v[154:155]
	v_pk_fma_f32 v[148:149], v[60:61], v[12:13], v[148:149]
	v_pk_fma_f32 v[150:151], v[62:63], v[14:15], v[150:151]
	v_pk_fma_f32 v[152:153], v[64:65], v[12:13], v[152:153]
	v_pk_fma_f32 v[154:155], v[66:67], v[14:15], v[154:155]
	v_pk_fma_f32 v[148:149], v[76:77], v[16:17], v[148:149]
	v_pk_fma_f32 v[150:151], v[78:79], v[18:19], v[150:151]
	v_pk_fma_f32 v[152:153], v[80:81], v[16:17], v[152:153]
	v_pk_fma_f32 v[154:155], v[82:83], v[18:19], v[154:155]
	v_pk_fma_f32 v[148:149], v[44:45], v[20:21], v[148:149]
	v_pk_fma_f32 v[150:151], v[46:47], v[22:23], v[150:151]
	v_pk_fma_f32 v[152:153], v[48:49], v[20:21], v[152:153]
	v_pk_fma_f32 v[154:155], v[50:51], v[22:23], v[154:155]
	v_pk_fma_f32 v[148:149], v[64:65], v[24:25], v[148:149]
	v_pk_fma_f32 v[150:151], v[66:67], v[26:27], v[150:151]
	v_pk_fma_f32 v[152:153], v[68:69], v[24:25], v[152:153]
	v_pk_fma_f32 v[154:155], v[70:71], v[26:27], v[154:155]
	v_pk_fma_f32 v[148:149], v[80:81], v[28:29], v[148:149]
	v_pk_fma_f32 v[150:151], v[82:83], v[30:31], v[150:151]
	v_pk_fma_f32 v[152:153], v[84:85], v[28:29], v[152:153]
	v_pk_fma_f32 v[154:155], v[86:87], v[30:31], v[154:155]
	v_pk_fma_f32 v[148:149], v[48:49], v[32:33], v[148:149]
	v_pk_fma_f32 v[150:151], v[50:51], v[34:35], v[150:151]
	v_pk_fma_f32 v[152:153], v[52:53], v[32:33], v[152:153]
	v_pk_fma_f32 v[154:155], v[54:55], v[34:35], v[154:155]
	v_and_b32_e32 v156, 0x7fffffff, v148
	v_and_b32_e32 v157, 0x7fffffff, v149
	v_and_b32_e32 v158, 0x7fffffff, v150
	v_and_b32_e32 v159, 0x7fffffff, v151
	v_and_b32_e32 v160, 0x7fffffff, v152
	v_and_b32_e32 v161, 0x7fffffff, v153
	v_and_b32_e32 v162, 0x7fffffff, v154
	v_and_b32_e32 v163, 0x7fffffff, v155
	v_pk_fma_f32 v[164:165], v[156:157], v[184:185], v[186:187]
	v_pk_fma_f32 v[166:167], v[158:159], v[184:185], v[186:187]
	v_pk_fma_f32 v[168:169], v[160:161], v[184:185], v[186:187]
	v_pk_fma_f32 v[170:171], v[162:163], v[184:185], v[186:187]
	v_rcp_f32_e32 v164, v164
	v_rcp_f32_e32 v165, v165
	v_rcp_f32_e32 v166, v166
	v_rcp_f32_e32 v167, v167
	v_rcp_f32_e32 v168, v168
	v_rcp_f32_e32 v169, v169
	v_rcp_f32_e32 v170, v170
	v_rcp_f32_e32 v171, v171
; __device__ __forceinline__ unsigned cvt_pk_bf16(float lo, float hi) { unsigned r; asm volatile("v_cvt_pk_bf16_f32 %0, %1, %2" : "=v"(r) : "v"(lo), "v"(hi)); return r; }
; __device__ __forceinline__ float gelu_as(float v) {
;   const float av = fabsf(v); const float t = __builtin_amdgcn_rcpf(av * 0.2316418882f + 1.0f);
;   float q = t * 0.5307027145f + (-0.7265760135f); q = q * t + 0.7107068705f; q = q * t + (-0.142248368f); q = q * t + 0.127414796f; q = q * t;
;   const float e = __builtin_amdgcn_exp2f((v * v) * (-0.72134752044f));
;   const float m = v * (q * e);
;   return v < 0.f ? m : v - m;
; }
; __device__ __forceinline__ void phase_conv(KP p, int l, int tid) {
;     ...
;       for (int q = 0; q < CB; ++q) {
;         const int col = jb + q + 1;
; #pragma unroll
;         for (int di = 0; di < RB + 2; ++di) { const bool ok = rv[di] && (col < 64); unpack4(an[q][di], win[2][di]);
; #pragma unroll
;           for (int k = 0; k < 4; ++k) win[2][di][k] = ok ? win[2][di][k] : 0.f; }
; #pragma unroll
;         for (int rr = 0; rr < RB; ++rr) {
;           float uv[4]; unpack4(ur[q][rr], uv);
;           float o[4];
; #pragma unroll
;           for (int k = 0; k < 4; ++k) {
;             float a = bsv[k];
; #pragma unroll
;             for (int di = 0; di < 3; ++di)
; #pragma unroll
;               for (int dj = 0; dj < 3; ++dj) a += win[dj][rr + di][k] * w[di * 3 + dj][k];
;             o[k] = gelu_as(a) * uv[k];
;           }
;           u32x2 ow; ow.x = cvt_pk_bf16(o[0], o[1]); ow.y = cvt_pk_bf16(o[2], o[3]);
;           *(u32x2*)(G + (size_t)((r0 + rr) * 64 + jb + q) * DFF + c0) = ow;
;         }
; #pragma unroll
;         for (int di = 0; di < RB + 2; ++di)
; #pragma unroll
;           for (int k = 0; k < 4; ++k) { win[0][di][k] = win[1][di][k]; win[1][di][k] = win[2][di][k]; }
	v_pk_fma_f32 v[172:173], v[164:165], v[188:189], v[190:191]
	v_pk_fma_f32 v[174:175], v[166:167], v[188:189], v[190:191]
	v_pk_fma_f32 v[176:177], v[168:169], v[188:189], v[190:191]
	v_pk_fma_f32 v[178:179], v[170:171], v[188:189], v[190:191]
	v_pk_fma_f32 v[172:173], v[172:173], v[164:165], v[192:193]
	v_pk_fma_f32 v[174:175], v[174:175], v[166:167], v[192:193]
	v_pk_fma_f32 v[176:177], v[176:177], v[168:169], v[192:193]
	v_pk_fma_f32 v[178:179], v[178:179], v[170:171], v[192:193]
	v_pk_fma_f32 v[172:173], v[172:173], v[164:165], v[194:195]
	v_pk_fma_f32 v[174:175], v[174:175], v[166:167], v[194:195]
	v_pk_fma_f32 v[176:177], v[176:177], v[168:169], v[194:195]
	v_pk_fma_f32 v[178:179], v[178:179], v[170:171], v[194:195]
	v_pk_fma_f32 v[172:173], v[172:173], v[164:165], v[196:197]
	v_pk_fma_f32 v[174:175], v[174:175], v[166:167], v[196:197]
	v_pk_fma_f32 v[176:177], v[176:177], v[168:169], v[196:197]
	v_pk_fma_f32 v[178:179], v[178:179], v[170:171], v[196:197]
	v_pk_mul_f32 v[172:173], v[172:173], v[164:165]
	v_pk_mul_f32 v[174:175], v[174:175], v[166:167]
	v_pk_mul_f32 v[176:177], v[176:177], v[168:169]
	v_pk_mul_f32 v[178:179], v[178:179], v[170:171]
	v_pk_mul_f32 v[164:165], v[148:149], v[148:149]
	v_pk_mul_f32 v[166:167], v[150:151], v[150:151]
	v_pk_mul_f32 v[168:169], v[152:153], v[152:153]
	v_pk_mul_f32 v[170:171], v[154:155], v[154:155]
	v_pk_mul_f32 v[164:165], v[164:165], v[198:199]
	v_pk_mul_f32 v[166:167], v[166:167], v[198:199]
	v_pk_mul_f32 v[168:169], v[168:169], v[198:199]
	v_pk_mul_f32 v[170:171], v[170:171], v[198:199]
	v_exp_f32_e32 v164, v164
	v_exp_f32_e32 v165, v165
	v_exp_f32_e32 v166, v166
	v_exp_f32_e32 v167, v167
	v_exp_f32_e32 v168, v168
	v_exp_f32_e32 v169, v169
	v_exp_f32_e32 v170, v170
	v_exp_f32_e32 v171, v171
	v_pk_mul_f32 v[172:173], v[172:173], v[164:165]
	v_pk_mul_f32 v[174:175], v[174:175], v[166:167]
	v_pk_mul_f32 v[176:177], v[176:177], v[168:169]
	v_pk_mul_f32 v[178:179], v[178:179], v[170:171]
	v_pk_mul_f32 v[172:173], v[156:157], v[172:173]
	v_pk_mul_f32 v[174:175], v[158:159], v[174:175]
	v_pk_mul_f32 v[176:177], v[160:161], v[176:177]
	v_pk_mul_f32 v[178:179], v[162:163], v[178:179]
	v_max_f32_e32 v164, 0, v148
	v_max_f32_e32 v165, 0, v149
	v_max_f32_e32 v166, 0, v150
	v_max_f32_e32 v167, 0, v151
	v_max_f32_e32 v168, 0, v152
	v_max_f32_e32 v169, 0, v153
	v_max_f32_e32 v170, 0, v154
	v_max_f32_e32 v171, 0, v155
	v_pk_add_f32 v[164:165], v[164:165], v[172:173] neg_lo:[0,1] neg_hi:[0,1]
	v_pk_add_f32 v[166:167], v[166:167], v[174:175] neg_lo:[0,1] neg_hi:[0,1]
	v_pk_add_f32 v[168:169], v[168:169], v[176:177] neg_lo:[0,1] neg_hi:[0,1]
	v_pk_add_f32 v[170:171], v[170:171], v[178:179] neg_lo:[0,1] neg_hi:[0,1]
	v_pk_mul_f32 v[164:165], v[164:165], v[124:125]
	v_pk_mul_f32 v[166:167], v[166:167], v[126:127]
	v_pk_mul_f32 v[168:169], v[168:169], v[128:129]
	v_pk_mul_f32 v[170:171], v[170:171], v[130:131]
	v_cvt_pk_bf16_f32 v156, v164, v165
	v_cvt_pk_bf16_f32 v157, v166, v167
	v_cvt_pk_bf16_f32 v158, v168, v169
	v_cvt_pk_bf16_f32 v159, v170, v171
	global_store_dwordx2 v218, v[156:157], s[10:11]
	global_store_dwordx2 v219, v[158:159], s[10:11]
	v_add_u32_e32 v210, 0x2c00, v210
	v_add_u32_e32 v211, 0x2c00, v210
	v_add_u32_e32 v212, v206, v211
	global_load_dwordx2 v[96:97], v212, s[6:7]
	v_add_u32_e32 v213, v207, v211
	global_load_dwordx2 v[98:99], v213, s[6:7]
	v_add_u32_e32 v214, v208, v211
	global_load_dwordx2 v[100:101], v214, s[6:7]
	v_add_u32_e32 v215, v209, v211
	global_load_dwordx2 v[102:103], v215, s[6:7]
	v_add_u32_e32 v218, v207, v210
	global_load_dwordx2 v[116:117], v218, s[8:9]
	v_add_u32_e32 v219, v208, v210
	global_load_dwordx2 v[118:119], v219, s[8:9]
	s_waitcnt vmcnt(16)
	v_lshlrev_b32_e32 v56, 16, v104
	v_and_b32_e32 v57, 0xffff0000, v104
	v_lshlrev_b32_e32 v58, 16, v105
	v_and_b32_e32 v59, 0xffff0000, v105
	v_lshlrev_b32_e32 v60, 16, v106
	v_and_b32_e32 v61, 0xffff0000, v106
	v_lshlrev_b32_e32 v62, 16, v107
	v_and_b32_e32 v63, 0xffff0000, v107
	v_lshlrev_b32_e32 v64, 16, v108
	v_and_b32_e32 v65, 0xffff0000, v108
	v_lshlrev_b32_e32 v66, 16, v109
	v_and_b32_e32 v67, 0xffff0000, v109
	v_lshlrev_b32_e32 v68, 16, v110
	v_and_b32_e32 v69, 0xffff0000, v110
	v_lshlrev_b32_e32 v70, 16, v111
	v_and_b32_e32 v71, 0xffff0000, v111
	v_pk_mul_f32 v[56:57], v[56:57], v[200:201]
	v_pk_mul_f32 v[58:59], v[58:59], v[200:201]
	v_pk_mul_f32 v[68:69], v[68:69], v[202:203]
	v_pk_mul_f32 v[70:71], v[70:71], v[202:203]
	v_lshlrev_b32_e32 v124, 16, v120
	v_and_b32_e32 v125, 0xffff0000, v120
	v_lshlrev_b32_e32 v126, 16, v121
	v_and_b32_e32 v127, 0xffff0000, v121
	v_lshlrev_b32_e32 v128, 16, v122
	v_and_b32_e32 v129, 0xffff0000, v122
	v_lshlrev_b32_e32 v130, 16, v123
	v_and_b32_e32 v131, 0xffff0000, v123
	v_pk_fma_f32 v[148:149], v[72:73], v[0:1], v[36:37]
	v_pk_fma_f32 v[150:151], v[74:75], v[2:3], v[38:39]
	v_pk_fma_f32 v[152:153], v[76:77], v[0:1], v[36:37]
	v_pk_fma_f32 v[154:155], v[78:79], v[2:3], v[38:39]
	v_pk_fma_f32 v[148:149], v[40:41], v[4:5], v[148:149]
	v_pk_fma_f32 v[150:151], v[42:43], v[6:7], v[150:151]
	v_pk_fma_f32 v[152:153], v[44:45], v[4:5], v[152:153]
	v_pk_fma_f32 v[154:155], v[46:47], v[6:7], v[154:155]
	v_pk_fma_f32 v[148:149], v[56:57], v[8:9], v[148:149]
	v_pk_fma_f32 v[150:151], v[58:59], v[10:11], v[150:151]
	v_pk_fma_f32 v[152:153], v[60:61], v[8:9], v[152:153]
	v_pk_fma_f32 v[154:155], v[62:63], v[10:11], v[154:155]
	v_pk_fma_f32 v[148:149], v[76:77], v[12:13], v[148:149]
	v_pk_fma_f32 v[150:151], v[78:79], v[14:15], v[150:151]
	v_pk_fma_f32 v[152:153], v[80:81], v[12:13], v[152:153]
	v_pk_fma_f32 v[154:155], v[82:83], v[14:15], v[154:155]
	v_pk_fma_f32 v[148:149], v[44:45], v[16:17], v[148:149]
; __device__ __forceinline__ unsigned cvt_pk_bf16(float lo, float hi) { unsigned r; asm volatile("v_cvt_pk_bf16_f32 %0, %1, %2" : "=v"(r) : "v"(lo), "v"(hi)); return r; }
; __device__ __forceinline__ float gelu_as(float v) {
;   const float av = fabsf(v); const float t = __builtin_amdgcn_rcpf(av * 0.2316418882f + 1.0f);
;   float q = t * 0.5307027145f + (-0.7265760135f); q = q * t + 0.7107068705f; q = q * t + (-0.142248368f); q = q * t + 0.127414796f; q = q * t;
;   const float e = __builtin_amdgcn_exp2f((v * v) * (-0.72134752044f));
;   const float m = v * (q * e);
;   return v < 0.f ? m : v - m;
; }
; __device__ __forceinline__ void phase_conv(KP p, int l, int tid) {
;     ...
;       for (int q = 0; q < CB; ++q) {
;         const int col = jb + q + 1;
; #pragma unroll
;         for (int di = 0; di < RB + 2; ++di) { const bool ok = rv[di] && (col < 64); unpack4(an[q][di], win[2][di]);
; #pragma unroll
;           for (int k = 0; k < 4; ++k) win[2][di][k] = ok ? win[2][di][k] : 0.f; }
; #pragma unroll
;         for (int rr = 0; rr < RB; ++rr) {
;           float uv[4]; unpack4(ur[q][rr], uv);
;           float o[4];
; #pragma unroll
;           for (int k = 0; k < 4; ++k) {
;             float a = bsv[k];
; #pragma unroll
;             for (int di = 0; di < 3; ++di)
; #pragma unroll
;               for (int dj = 0; dj < 3; ++dj) a += win[dj][rr + di][k] * w[di * 3 + dj][k];
;             o[k] = gelu_as(a) * uv[k];
;           }
;           u32x2 ow; ow.x = cvt_pk_bf16(o[0], o[1]); ow.y = cvt_pk_bf16(o[2], o[3]);
;           *(u32x2*)(G + (size_t)((r0 + rr) * 64 + jb + q) * DFF + c0) = ow;
;         }
; #pragma unroll
;         for (int di = 0; di < RB + 2; ++di)
; #pragma unroll
;           for (int k = 0; k < 4; ++k) { win[0][di][k] = win[1][di][k]; win[1][di][k] = win[2][di][k]; }
	v_pk_fma_f32 v[150:151], v[46:47], v[18:19], v[150:151]
	v_pk_fma_f32 v[152:153], v[48:49], v[16:17], v[152:153]
	v_pk_fma_f32 v[154:155], v[50:51], v[18:19], v[154:155]
	v_pk_fma_f32 v[148:149], v[60:61], v[20:21], v[148:149]
	v_pk_fma_f32 v[150:151], v[62:63], v[22:23], v[150:151]
	v_pk_fma_f32 v[152:153], v[64:65], v[20:21], v[152:153]
	v_pk_fma_f32 v[154:155], v[66:67], v[22:23], v[154:155]
	v_pk_fma_f32 v[148:149], v[80:81], v[24:25], v[148:149]
	v_pk_fma_f32 v[150:151], v[82:83], v[26:27], v[150:151]
	v_pk_fma_f32 v[152:153], v[84:85], v[24:25], v[152:153]
	v_pk_fma_f32 v[154:155], v[86:87], v[26:27], v[154:155]
	v_pk_fma_f32 v[148:149], v[48:49], v[28:29], v[148:149]
	v_pk_fma_f32 v[150:151], v[50:51], v[30:31], v[150:151]
	v_pk_fma_f32 v[152:153], v[52:53], v[28:29], v[152:153]
	v_pk_fma_f32 v[154:155], v[54:55], v[30:31], v[154:155]
	v_pk_fma_f32 v[148:149], v[64:65], v[32:33], v[148:149]
	v_pk_fma_f32 v[150:151], v[66:67], v[34:35], v[150:151]
	v_pk_fma_f32 v[152:153], v[68:69], v[32:33], v[152:153]
	v_pk_fma_f32 v[154:155], v[70:71], v[34:35], v[154:155]
	v_and_b32_e32 v156, 0x7fffffff, v148
	v_and_b32_e32 v157, 0x7fffffff, v149
	v_and_b32_e32 v158, 0x7fffffff, v150
	v_and_b32_e32 v159, 0x7fffffff, v151
	v_and_b32_e32 v160, 0x7fffffff, v152
	v_and_b32_e32 v161, 0x7fffffff, v153
	v_and_b32_e32 v162, 0x7fffffff, v154
	v_and_b32_e32 v163, 0x7fffffff, v155
	v_pk_fma_f32 v[164:165], v[156:157], v[184:185], v[186:187]
	v_pk_fma_f32 v[166:167], v[158:159], v[184:185], v[186:187]
	v_pk_fma_f32 v[168:169], v[160:161], v[184:185], v[186:187]
	v_pk_fma_f32 v[170:171], v[162:163], v[184:185], v[186:187]
	v_rcp_f32_e32 v164, v164
	v_rcp_f32_e32 v165, v165
	v_rcp_f32_e32 v166, v166
	v_rcp_f32_e32 v167, v167
	v_rcp_f32_e32 v168, v168
	v_rcp_f32_e32 v169, v169
	v_rcp_f32_e32 v170, v170
	v_rcp_f32_e32 v171, v171
	v_pk_fma_f32 v[172:173], v[164:165], v[188:189], v[190:191]
	v_pk_fma_f32 v[174:175], v[166:167], v[188:189], v[190:191]
	v_pk_fma_f32 v[176:177], v[168:169], v[188:189], v[190:191]
	v_pk_fma_f32 v[178:179], v[170:171], v[188:189], v[190:191]
	v_pk_fma_f32 v[172:173], v[172:173], v[164:165], v[192:193]
	v_pk_fma_f32 v[174:175], v[174:175], v[166:167], v[192:193]
	v_pk_fma_f32 v[176:177], v[176:177], v[168:169], v[192:193]
	v_pk_fma_f32 v[178:179], v[178:179], v[170:171], v[192:193]
	v_pk_fma_f32 v[172:173], v[172:173], v[164:165], v[194:195]
	v_pk_fma_f32 v[174:175], v[174:175], v[166:167], v[194:195]
	v_pk_fma_f32 v[176:177], v[176:177], v[168:169], v[194:195]
	v_pk_fma_f32 v[178:179], v[178:179], v[170:171], v[194:195]
	v_pk_fma_f32 v[172:173], v[172:173], v[164:165], v[196:197]
	v_pk_fma_f32 v[174:175], v[174:175], v[166:167], v[196:197]
	v_pk_fma_f32 v[176:177], v[176:177], v[168:169], v[196:197]
	v_pk_fma_f32 v[178:179], v[178:179], v[170:171], v[196:197]
	v_pk_mul_f32 v[172:173], v[172:173], v[164:165]
	v_pk_mul_f32 v[174:175], v[174:175], v[166:167]
	v_pk_mul_f32 v[176:177], v[176:177], v[168:169]
	v_pk_mul_f32 v[178:179], v[178:179], v[170:171]
	v_pk_mul_f32 v[164:165], v[148:149], v[148:149]
	v_pk_mul_f32 v[166:167], v[150:151], v[150:151]
	v_pk_mul_f32 v[168:169], v[152:153], v[152:153]
	v_pk_mul_f32 v[170:171], v[154:155], v[154:155]
	v_pk_mul_f32 v[164:165], v[164:165], v[198:199]
	v_pk_mul_f32 v[166:167], v[166:167], v[198:199]
	v_pk_mul_f32 v[168:169], v[168:169], v[198:199]
	v_pk_mul_f32 v[170:171], v[170:171], v[198:199]
	v_exp_f32_e32 v164, v164
	v_exp_f32_e32 v165, v165
	v_exp_f32_e32 v166, v166
	v_exp_f32_e32 v167, v167
	v_exp_f32_e32 v168, v168
	v_exp_f32_e32 v169, v169
	v_exp_f32_e32 v170, v170
	v_exp_f32_e32 v171, v171
	v_pk_mul_f32 v[172:173], v[172:173], v[164:165]
	v_pk_mul_f32 v[174:175], v[174:175], v[166:167]
	v_pk_mul_f32 v[176:177], v[176:177], v[168:169]
	v_pk_mul_f32 v[178:179], v[178:179], v[170:171]
	v_pk_mul_f32 v[172:173], v[156:157], v[172:173]
	v_pk_mul_f32 v[174:175], v[158:159], v[174:175]
	v_pk_mul_f32 v[176:177], v[160:161], v[176:177]
	v_pk_mul_f32 v[178:179], v[162:163], v[178:179]
	v_max_f32_e32 v164, 0, v148
	v_max_f32_e32 v165, 0, v149
	v_max_f32_e32 v166, 0, v150
	v_max_f32_e32 v167, 0, v151
	v_max_f32_e32 v168, 0, v152
	v_max_f32_e32 v169, 0, v153
	v_max_f32_e32 v170, 0, v154
	v_max_f32_e32 v171, 0, v155
	v_pk_add_f32 v[164:165], v[164:165], v[172:173] neg_lo:[0,1] neg_hi:[0,1]
	v_pk_add_f32 v[166:167], v[166:167], v[174:175] neg_lo:[0,1] neg_hi:[0,1]
	v_pk_add_f32 v[168:169], v[168:169], v[176:177] neg_lo:[0,1] neg_hi:[0,1]
	v_pk_add_f32 v[170:171], v[170:171], v[178:179] neg_lo:[0,1] neg_hi:[0,1]
	v_pk_mul_f32 v[164:165], v[164:165], v[124:125]
	v_pk_mul_f32 v[166:167], v[166:167], v[126:127]
	v_pk_mul_f32 v[168:169], v[168:169], v[128:129]
	v_pk_mul_f32 v[170:171], v[170:171], v[130:131]
	v_cvt_pk_bf16_f32 v156, v164, v165
	v_cvt_pk_bf16_f32 v157, v166, v167
	v_cvt_pk_bf16_f32 v158, v168, v169
	v_cvt_pk_bf16_f32 v159, v170, v171
	global_store_dwordx2 v220, v[156:157], s[10:11]
	global_store_dwordx2 v221, v[158:159], s[10:11]
	v_add_u32_e32 v210, 0x2c00, v210
	v_add_u32_e32 v211, 0x2c00, v210
	v_add_u32_e32 v212, v206, v211
	global_load_dwordx2 v[104:105], v212, s[6:7]
	v_add_u32_e32 v213, v207, v211
	global_load_dwordx2 v[106:107], v213, s[6:7]
	v_add_u32_e32 v214, v208, v211
	global_load_dwordx2 v[108:109], v214, s[6:7]
	v_add_u32_e32 v215, v209, v211
	global_load_dwordx2 v[110:111], v215, s[6:7]
	v_add_u32_e32 v220, v207, v210
	global_load_dwordx2 v[120:121], v220, s[8:9]
	v_add_u32_e32 v221, v208, v210
	global_load_dwordx2 v[122:123], v221, s[8:9]
	s_waitcnt vmcnt(16)
; __device__ __forceinline__ unsigned cvt_pk_bf16(float lo, float hi) { unsigned r; asm volatile("v_cvt_pk_bf16_f32 %0, %1, %2" : "=v"(r) : "v"(lo), "v"(hi)); return r; }
; __device__ __forceinline__ float gelu_as(float v) {
;   const float av = fabsf(v); const float t = __builtin_amdgcn_rcpf(av * 0.2316418882f + 1.0f);
;   float q = t * 0.5307027145f + (-0.7265760135f); q = q * t + 0.7107068705f; q = q * t + (-0.142248368f); q = q * t + 0.127414796f; q = q * t;
;   const float e = __builtin_amdgcn_exp2f((v * v) * (-0.72134752044f));
;   const float m = v * (q * e);
;   return v < 0.f ? m : v - m;
; }
; __device__ __forceinline__ void phase_conv(KP p, int l, int tid) {
;     ...
;       for (int q = 0; q < CB; ++q) {
;         const int col = jb + q + 1;
; #pragma unroll
;         for (int di = 0; di < RB + 2; ++di) { const bool ok = rv[di] && (col < 64); unpack4(an[q][di], win[2][di]);
; #pragma unroll
;           for (int k = 0; k < 4; ++k) win[2][di][k] = ok ? win[2][di][k] : 0.f; }
; #pragma unroll
;         for (int rr = 0; rr < RB; ++rr) {
;           float uv[4]; unpack4(ur[q][rr], uv);
;           float o[4];
; #pragma unroll
;           for (int k = 0; k < 4; ++k) {
;             float a = bsv[k];
; #pragma unroll
;             for (int di = 0; di < 3; ++di)
; #pragma unroll
;               for (int dj = 0; dj < 3; ++dj) a += win[dj][rr + di][k] * w[di * 3 + dj][k];
;             o[k] = gelu_as(a) * uv[k];
;           }
;           u32x2 ow; ow.x = cvt_pk_bf16(o[0], o[1]); ow.y = cvt_pk_bf16(o[2], o[3]);
;           *(u32x2*)(G + (size_t)((r0 + rr) * 64 + jb + q) * DFF + c0) = ow;
;         }
; #pragma unroll
;         for (int di = 0; di < RB + 2; ++di)
; #pragma unroll
;           for (int k = 0; k < 4; ++k) { win[0][di][k] = win[1][di][k]; win[1][di][k] = win[2][di][k]; }
	v_lshlrev_b32_e32 v72, 16, v88
	v_and_b32_e32 v73, 0xffff0000, v88
	v_lshlrev_b32_e32 v74, 16, v89
	v_and_b32_e32 v75, 0xffff0000, v89
	v_lshlrev_b32_e32 v76, 16, v90
	v_and_b32_e32 v77, 0xffff0000, v90
	v_lshlrev_b32_e32 v78, 16, v91
	v_and_b32_e32 v79, 0xffff0000, v91
	v_lshlrev_b32_e32 v80, 16, v92
	v_and_b32_e32 v81, 0xffff0000, v92
	v_lshlrev_b32_e32 v82, 16, v93
	v_and_b32_e32 v83, 0xffff0000, v93
	v_lshlrev_b32_e32 v84, 16, v94
	v_and_b32_e32 v85, 0xffff0000, v94
	v_lshlrev_b32_e32 v86, 16, v95
	v_and_b32_e32 v87, 0xffff0000, v95
	v_pk_mul_f32 v[72:73], v[72:73], v[200:201]
	v_pk_mul_f32 v[74:75], v[74:75], v[200:201]
	v_pk_mul_f32 v[84:85], v[84:85], v[202:203]
	v_pk_mul_f32 v[86:87], v[86:87], v[202:203]
	v_lshlrev_b32_e32 v124, 16, v112
	v_and_b32_e32 v125, 0xffff0000, v112
	v_lshlrev_b32_e32 v126, 16, v113
	v_and_b32_e32 v127, 0xffff0000, v113
	v_lshlrev_b32_e32 v128, 16, v114
	v_and_b32_e32 v129, 0xffff0000, v114
	v_lshlrev_b32_e32 v130, 16, v115
	v_and_b32_e32 v131, 0xffff0000, v115
	v_pk_fma_f32 v[148:149], v[40:41], v[0:1], v[36:37]
	v_pk_fma_f32 v[150:151], v[42:43], v[2:3], v[38:39]
	v_pk_fma_f32 v[152:153], v[44:45], v[0:1], v[36:37]
	v_pk_fma_f32 v[154:155], v[46:47], v[2:3], v[38:39]
	v_pk_fma_f32 v[148:149], v[56:57], v[4:5], v[148:149]
	v_pk_fma_f32 v[150:151], v[58:59], v[6:7], v[150:151]
	v_pk_fma_f32 v[152:153], v[60:61], v[4:5], v[152:153]
	v_pk_fma_f32 v[154:155], v[62:63], v[6:7], v[154:155]
	v_pk_fma_f32 v[148:149], v[72:73], v[8:9], v[148:149]
	v_pk_fma_f32 v[150:151], v[74:75], v[10:11], v[150:151]
	v_pk_fma_f32 v[152:153], v[76:77], v[8:9], v[152:153]
	v_pk_fma_f32 v[154:155], v[78:79], v[10:11], v[154:155]
	v_pk_fma_f32 v[148:149], v[44:45], v[12:13], v[148:149]
	v_pk_fma_f32 v[150:151], v[46:47], v[14:15], v[150:151]
	v_pk_fma_f32 v[152:153], v[48:49], v[12:13], v[152:153]
	v_pk_fma_f32 v[154:155], v[50:51], v[14:15], v[154:155]
	v_pk_fma_f32 v[148:149], v[60:61], v[16:17], v[148:149]
	v_pk_fma_f32 v[150:151], v[62:63], v[18:19], v[150:151]
	v_pk_fma_f32 v[152:153], v[64:65], v[16:17], v[152:153]
	v_pk_fma_f32 v[154:155], v[66:67], v[18:19], v[154:155]
	v_pk_fma_f32 v[148:149], v[76:77], v[20:21], v[148:149]
	v_pk_fma_f32 v[150:151], v[78:79], v[22:23], v[150:151]
	v_pk_fma_f32 v[152:153], v[80:81], v[20:21], v[152:153]
	v_pk_fma_f32 v[154:155], v[82:83], v[22:23], v[154:155]
	v_pk_fma_f32 v[148:149], v[48:49], v[24:25], v[148:149]
	v_pk_fma_f32 v[150:151], v[50:51], v[26:27], v[150:151]
	v_pk_fma_f32 v[152:153], v[52:53], v[24:25], v[152:153]
	v_pk_fma_f32 v[154:155], v[54:55], v[26:27], v[154:155]
	v_pk_fma_f32 v[148:149], v[64:65], v[28:29], v[148:149]
	v_pk_fma_f32 v[150:151], v[66:67], v[30:31], v[150:151]
	v_pk_fma_f32 v[152:153], v[68:69], v[28:29], v[152:153]
	v_pk_fma_f32 v[154:155], v[70:71], v[30:31], v[154:155]
	v_pk_fma_f32 v[148:149], v[80:81], v[32:33], v[148:149]
	v_pk_fma_f32 v[150:151], v[82:83], v[34:35], v[150:151]
	v_pk_fma_f32 v[152:153], v[84:85], v[32:33], v[152:153]
	v_pk_fma_f32 v[154:155], v[86:87], v[34:35], v[154:155]
	v_and_b32_e32 v156, 0x7fffffff, v148
	v_and_b32_e32 v157, 0x7fffffff, v149
	v_and_b32_e32 v158, 0x7fffffff, v150
	v_and_b32_e32 v159, 0x7fffffff, v151
	v_and_b32_e32 v160, 0x7fffffff, v152
	v_and_b32_e32 v161, 0x7fffffff, v153
	v_and_b32_e32 v162, 0x7fffffff, v154
	v_and_b32_e32 v163, 0x7fffffff, v155
	v_pk_fma_f32 v[164:165], v[156:157], v[184:185], v[186:187]
	v_pk_fma_f32 v[166:167], v[158:159], v[184:185], v[186:187]
	v_pk_fma_f32 v[168:169], v[160:161], v[184:185], v[186:187]
	v_pk_fma_f32 v[170:171], v[162:163], v[184:185], v[186:187]
	v_rcp_f32_e32 v164, v164
	v_rcp_f32_e32 v165, v165
	v_rcp_f32_e32 v166, v166
	v_rcp_f32_e32 v167, v167
	v_rcp_f32_e32 v168, v168
	v_rcp_f32_e32 v169, v169
	v_rcp_f32_e32 v170, v170
	v_rcp_f32_e32 v171, v171
	v_pk_fma_f32 v[172:173], v[164:165], v[188:189], v[190:191]
	v_pk_fma_f32 v[174:175], v[166:167], v[188:189], v[190:191]
	v_pk_fma_f32 v[176:177], v[168:169], v[188:189], v[190:191]
	v_pk_fma_f32 v[178:179], v[170:171], v[188:189], v[190:191]
	v_pk_fma_f32 v[172:173], v[172:173], v[164:165], v[192:193]
	v_pk_fma_f32 v[174:175], v[174:175], v[166:167], v[192:193]
	v_pk_fma_f32 v[176:177], v[176:177], v[168:169], v[192:193]
	v_pk_fma_f32 v[178:179], v[178:179], v[170:171], v[192:193]
	v_pk_fma_f32 v[172:173], v[172:173], v[164:165], v[194:195]
	v_pk_fma_f32 v[174:175], v[174:175], v[166:167], v[194:195]
	v_pk_fma_f32 v[176:177], v[176:177], v[168:169], v[194:195]
	v_pk_fma_f32 v[178:179], v[178:179], v[170:171], v[194:195]
	v_pk_fma_f32 v[172:173], v[172:173], v[164:165], v[196:197]
	v_pk_fma_f32 v[174:175], v[174:175], v[166:167], v[196:197]
	v_pk_fma_f32 v[176:177], v[176:177], v[168:169], v[196:197]
	v_pk_fma_f32 v[178:179], v[178:179], v[170:171], v[196:197]
	v_pk_mul_f32 v[172:173], v[172:173], v[164:165]
	v_pk_mul_f32 v[174:175], v[174:175], v[166:167]
	v_pk_mul_f32 v[176:177], v[176:177], v[168:169]
	v_pk_mul_f32 v[178:179], v[178:179], v[170:171]
	v_pk_mul_f32 v[164:165], v[148:149], v[148:149]
	v_pk_mul_f32 v[166:167], v[150:151], v[150:151]
	v_pk_mul_f32 v[168:169], v[152:153], v[152:153]
	v_pk_mul_f32 v[170:171], v[154:155], v[154:155]
	v_pk_mul_f32 v[164:165], v[164:165], v[198:199]
	v_pk_mul_f32 v[166:167], v[166:167], v[198:199]
	v_pk_mul_f32 v[168:169], v[168:169], v[198:199]
	v_pk_mul_f32 v[170:171], v[170:171], v[198:199]
	v_exp_f32_e32 v164, v164
	v_exp_f32_e32 v165, v165
	v_exp_f32_e32 v166, v166
	v_exp_f32_e32 v167, v167
	v_exp_f32_e32 v168, v168
	v_exp_f32_e32 v169, v169
	v_exp_f32_e32 v170, v170
	v_exp_f32_e32 v171, v171
	v_pk_mul_f32 v[172:173], v[172:173], v[164:165]
	v_pk_mul_f32 v[174:175], v[174:175], v[166:167]
; __device__ __forceinline__ unsigned cvt_pk_bf16(float lo, float hi) { unsigned r; asm volatile("v_cvt_pk_bf16_f32 %0, %1, %2" : "=v"(r) : "v"(lo), "v"(hi)); return r; }
; __device__ __forceinline__ float gelu_as(float v) {
;   const float av = fabsf(v); const float t = __builtin_amdgcn_rcpf(av * 0.2316418882f + 1.0f);
;   float q = t * 0.5307027145f + (-0.7265760135f); q = q * t + 0.7107068705f; q = q * t + (-0.142248368f); q = q * t + 0.127414796f; q = q * t;
;   const float e = __builtin_amdgcn_exp2f((v * v) * (-0.72134752044f));
;   const float m = v * (q * e);
;   return v < 0.f ? m : v - m;
; }
; __device__ __forceinline__ void phase_conv(KP p, int l, int tid) {
;     ...
;       for (int q = 0; q < CB; ++q) {
;         const int col = jb + q + 1;
; #pragma unroll
;         for (int di = 0; di < RB + 2; ++di) { const bool ok = rv[di] && (col < 64); unpack4(an[q][di], win[2][di]);
; #pragma unroll
;           for (int k = 0; k < 4; ++k) win[2][di][k] = ok ? win[2][di][k] : 0.f; }
; #pragma unroll
;         for (int rr = 0; rr < RB; ++rr) {
;           float uv[4]; unpack4(ur[q][rr], uv);
;           float o[4];
; #pragma unroll
;           for (int k = 0; k < 4; ++k) {
;             float a = bsv[k];
; #pragma unroll
;             for (int di = 0; di < 3; ++di)
; #pragma unroll
;               for (int dj = 0; dj < 3; ++dj) a += win[dj][rr + di][k] * w[di * 3 + dj][k];
;             o[k] = gelu_as(a) * uv[k];
;           }
;           u32x2 ow; ow.x = cvt_pk_bf16(o[0], o[1]); ow.y = cvt_pk_bf16(o[2], o[3]);
;           *(u32x2*)(G + (size_t)((r0 + rr) * 64 + jb + q) * DFF + c0) = ow;
;         }
; #pragma unroll
;         for (int di = 0; di < RB + 2; ++di)
; #pragma unroll
;           for (int k = 0; k < 4; ++k) { win[0][di][k] = win[1][di][k]; win[1][di][k] = win[2][di][k]; }
	v_pk_mul_f32 v[176:177], v[176:177], v[168:169]
	v_pk_mul_f32 v[178:179], v[178:179], v[170:171]
	v_pk_mul_f32 v[172:173], v[156:157], v[172:173]
	v_pk_mul_f32 v[174:175], v[158:159], v[174:175]
	v_pk_mul_f32 v[176:177], v[160:161], v[176:177]
	v_pk_mul_f32 v[178:179], v[162:163], v[178:179]
	v_max_f32_e32 v164, 0, v148
	v_max_f32_e32 v165, 0, v149
	v_max_f32_e32 v166, 0, v150
	v_max_f32_e32 v167, 0, v151
	v_max_f32_e32 v168, 0, v152
	v_max_f32_e32 v169, 0, v153
	v_max_f32_e32 v170, 0, v154
	v_max_f32_e32 v171, 0, v155
	v_pk_add_f32 v[164:165], v[164:165], v[172:173] neg_lo:[0,1] neg_hi:[0,1]
	v_pk_add_f32 v[166:167], v[166:167], v[174:175] neg_lo:[0,1] neg_hi:[0,1]
	v_pk_add_f32 v[168:169], v[168:169], v[176:177] neg_lo:[0,1] neg_hi:[0,1]
	v_pk_add_f32 v[170:171], v[170:171], v[178:179] neg_lo:[0,1] neg_hi:[0,1]
	v_pk_mul_f32 v[164:165], v[164:165], v[124:125]
	v_pk_mul_f32 v[166:167], v[166:167], v[126:127]
	v_pk_mul_f32 v[168:169], v[168:169], v[128:129]
	v_pk_mul_f32 v[170:171], v[170:171], v[130:131]
	v_cvt_pk_bf16_f32 v156, v164, v165
	v_cvt_pk_bf16_f32 v157, v166, v167
	v_cvt_pk_bf16_f32 v158, v168, v169
	v_cvt_pk_bf16_f32 v159, v170, v171
	global_store_dwordx2 v216, v[156:157], s[10:11]
	global_store_dwordx2 v217, v[158:159], s[10:11]
	v_add_u32_e32 v210, 0x2c00, v210
	v_add_u32_e32 v211, 0x2c00, v210
	v_add_u32_e32 v212, v206, v211
	global_load_dwordx2 v[88:89], v212, s[6:7]
	v_add_u32_e32 v213, v207, v211
	global_load_dwordx2 v[90:91], v213, s[6:7]
	v_add_u32_e32 v214, v208, v211
	global_load_dwordx2 v[92:93], v214, s[6:7]
	v_add_u32_e32 v215, v209, v211
	global_load_dwordx2 v[94:95], v215, s[6:7]
	v_add_u32_e32 v216, v207, v210
	global_load_dwordx2 v[112:113], v216, s[8:9]
	v_add_u32_e32 v217, v208, v210
	global_load_dwordx2 v[114:115], v217, s[8:9]
	s_waitcnt vmcnt(16)
	v_lshlrev_b32_e32 v40, 16, v96
	v_and_b32_e32 v41, 0xffff0000, v96
	v_lshlrev_b32_e32 v42, 16, v97
	v_and_b32_e32 v43, 0xffff0000, v97
	v_lshlrev_b32_e32 v44, 16, v98
	v_and_b32_e32 v45, 0xffff0000, v98
	v_lshlrev_b32_e32 v46, 16, v99
	v_and_b32_e32 v47, 0xffff0000, v99
	v_lshlrev_b32_e32 v48, 16, v100
	v_and_b32_e32 v49, 0xffff0000, v100
	v_lshlrev_b32_e32 v50, 16, v101
	v_and_b32_e32 v51, 0xffff0000, v101
	v_lshlrev_b32_e32 v52, 16, v102
	v_and_b32_e32 v53, 0xffff0000, v102
	v_lshlrev_b32_e32 v54, 16, v103
	v_and_b32_e32 v55, 0xffff0000, v103
	v_pk_mul_f32 v[40:41], v[40:41], v[200:201]
	v_pk_mul_f32 v[42:43], v[42:43], v[200:201]
	v_pk_mul_f32 v[52:53], v[52:53], v[202:203]
	v_pk_mul_f32 v[54:55], v[54:55], v[202:203]
	v_lshlrev_b32_e32 v124, 16, v116
	v_and_b32_e32 v125, 0xffff0000, v116
	v_lshlrev_b32_e32 v126, 16, v117
	v_and_b32_e32 v127, 0xffff0000, v117
	v_lshlrev_b32_e32 v128, 16, v118
	v_and_b32_e32 v129, 0xffff0000, v118
	v_lshlrev_b32_e32 v130, 16, v119
	v_and_b32_e32 v131, 0xffff0000, v119
	v_pk_fma_f32 v[148:149], v[56:57], v[0:1], v[36:37]
	v_pk_fma_f32 v[150:151], v[58:59], v[2:3], v[38:39]
	v_pk_fma_f32 v[152:153], v[60:61], v[0:1], v[36:37]
	v_pk_fma_f32 v[154:155], v[62:63], v[2:3], v[38:39]
	v_pk_fma_f32 v[148:149], v[72:73], v[4:5], v[148:149]
	v_pk_fma_f32 v[150:151], v[74:75], v[6:7], v[150:151]
	v_pk_fma_f32 v[152:153], v[76:77], v[4:5], v[152:153]
	v_pk_fma_f32 v[154:155], v[78:79], v[6:7], v[154:155]
	v_pk_fma_f32 v[148:149], v[40:41], v[8:9], v[148:149]
	v_pk_fma_f32 v[150:151], v[42:43], v[10:11], v[150:151]
	v_pk_fma_f32 v[152:153], v[44:45], v[8:9], v[152:153]
	v_pk_fma_f32 v[154:155], v[46:47], v[10:11], v[154:155]
	v_pk_fma_f32 v[148:149], v[60:61], v[12:13], v[148:149]
	v_pk_fma_f32 v[150:151], v[62:63], v[14:15], v[150:151]
	v_pk_fma_f32 v[152:153], v[64:65], v[12:13], v[152:153]
	v_pk_fma_f32 v[154:155], v[66:67], v[14:15], v[154:155]
	v_pk_fma_f32 v[148:149], v[76:77], v[16:17], v[148:149]
	v_pk_fma_f32 v[150:151], v[78:79], v[18:19], v[150:151]
	v_pk_fma_f32 v[152:153], v[80:81], v[16:17], v[152:153]
	v_pk_fma_f32 v[154:155], v[82:83], v[18:19], v[154:155]
	v_pk_fma_f32 v[148:149], v[44:45], v[20:21], v[148:149]
	v_pk_fma_f32 v[150:151], v[46:47], v[22:23], v[150:151]
	v_pk_fma_f32 v[152:153], v[48:49], v[20:21], v[152:153]
	v_pk_fma_f32 v[154:155], v[50:51], v[22:23], v[154:155]
	v_pk_fma_f32 v[148:149], v[64:65], v[24:25], v[148:149]
	v_pk_fma_f32 v[150:151], v[66:67], v[26:27], v[150:151]
	v_pk_fma_f32 v[152:153], v[68:69], v[24:25], v[152:153]
	v_pk_fma_f32 v[154:155], v[70:71], v[26:27], v[154:155]
	v_pk_fma_f32 v[148:149], v[80:81], v[28:29], v[148:149]
	v_pk_fma_f32 v[150:151], v[82:83], v[30:31], v[150:151]
	v_pk_fma_f32 v[152:153], v[84:85], v[28:29], v[152:153]
	v_pk_fma_f32 v[154:155], v[86:87], v[30:31], v[154:155]
	v_pk_fma_f32 v[148:149], v[48:49], v[32:33], v[148:149]
	v_pk_fma_f32 v[150:151], v[50:51], v[34:35], v[150:151]
	v_pk_fma_f32 v[152:153], v[52:53], v[32:33], v[152:153]
	v_pk_fma_f32 v[154:155], v[54:55], v[34:35], v[154:155]
	v_and_b32_e32 v156, 0x7fffffff, v148
	v_and_b32_e32 v157, 0x7fffffff, v149
	v_and_b32_e32 v158, 0x7fffffff, v150
	v_and_b32_e32 v159, 0x7fffffff, v151
	v_and_b32_e32 v160, 0x7fffffff, v152
	v_and_b32_e32 v161, 0x7fffffff, v153
	v_and_b32_e32 v162, 0x7fffffff, v154
	v_and_b32_e32 v163, 0x7fffffff, v155
	v_pk_fma_f32 v[164:165], v[156:157], v[184:185], v[186:187]
	v_pk_fma_f32 v[166:167], v[158:159], v[184:185], v[186:187]
	v_pk_fma_f32 v[168:169], v[160:161], v[184:185], v[186:187]
	v_pk_fma_f32 v[170:171], v[162:163], v[184:185], v[186:187]
	v_rcp_f32_e32 v164, v164
	v_rcp_f32_e32 v165, v165
	v_rcp_f32_e32 v166, v166
	v_rcp_f32_e32 v167, v167
	v_rcp_f32_e32 v168, v168
	v_rcp_f32_e32 v169, v169
	v_rcp_f32_e32 v170, v170
	v_rcp_f32_e32 v171, v171
; __device__ __forceinline__ unsigned cvt_pk_bf16(float lo, float hi) { unsigned r; asm volatile("v_cvt_pk_bf16_f32 %0, %1, %2" : "=v"(r) : "v"(lo), "v"(hi)); return r; }
; __device__ __forceinline__ float gelu_as(float v) {
;   const float av = fabsf(v); const float t = __builtin_amdgcn_rcpf(av * 0.2316418882f + 1.0f);
;   float q = t * 0.5307027145f + (-0.7265760135f); q = q * t + 0.7107068705f; q = q * t + (-0.142248368f); q = q * t + 0.127414796f; q = q * t;
;   const float e = __builtin_amdgcn_exp2f((v * v) * (-0.72134752044f));
;   const float m = v * (q * e);
;   return v < 0.f ? m : v - m;
; }
; __device__ __forceinline__ void phase_conv(KP p, int l, int tid) {
;     ...
;       for (int q = 0; q < CB; ++q) {
;         const int col = jb + q + 1;
; #pragma unroll
;         for (int di = 0; di < RB + 2; ++di) { const bool ok = rv[di] && (col < 64); unpack4(an[q][di], win[2][di]);
; #pragma unroll
;           for (int k = 0; k < 4; ++k) win[2][di][k] = ok ? win[2][di][k] : 0.f; }
; #pragma unroll
;         for (int rr = 0; rr < RB; ++rr) {
;           float uv[4]; unpack4(ur[q][rr], uv);
;           float o[4];
; #pragma unroll
;           for (int k = 0; k < 4; ++k) {
;             float a = bsv[k];
; #pragma unroll
;             for (int di = 0; di < 3; ++di)
; #pragma unroll
;               for (int dj = 0; dj < 3; ++dj) a += win[dj][rr + di][k] * w[di * 3 + dj][k];
;             o[k] = gelu_as(a) * uv[k];
;           }
;           u32x2 ow; ow.x = cvt_pk_bf16(o[0], o[1]); ow.y = cvt_pk_bf16(o[2], o[3]);
;           *(u32x2*)(G + (size_t)((r0 + rr) * 64 + jb + q) * DFF + c0) = ow;
;         }
; #pragma unroll
;         for (int di = 0; di < RB + 2; ++di)
; #pragma unroll
;           for (int k = 0; k < 4; ++k) { win[0][di][k] = win[1][di][k]; win[1][di][k] = win[2][di][k]; }
	v_pk_fma_f32 v[172:173], v[164:165], v[188:189], v[190:191]
	v_pk_fma_f32 v[174:175], v[166:167], v[188:189], v[190:191]
	v_pk_fma_f32 v[176:177], v[168:169], v[188:189], v[190:191]
	v_pk_fma_f32 v[178:179], v[170:171], v[188:189], v[190:191]
	v_pk_fma_f32 v[172:173], v[172:173], v[164:165], v[192:193]
	v_pk_fma_f32 v[174:175], v[174:175], v[166:167], v[192:193]
	v_pk_fma_f32 v[176:177], v[176:177], v[168:169], v[192:193]
	v_pk_fma_f32 v[178:179], v[178:179], v[170:171], v[192:193]
	v_pk_fma_f32 v[172:173], v[172:173], v[164:165], v[194:195]
	v_pk_fma_f32 v[174:175], v[174:175], v[166:167], v[194:195]
	v_pk_fma_f32 v[176:177], v[176:177], v[168:169], v[194:195]
	v_pk_fma_f32 v[178:179], v[178:179], v[170:171], v[194:195]
	v_pk_fma_f32 v[172:173], v[172:173], v[164:165], v[196:197]
	v_pk_fma_f32 v[174:175], v[174:175], v[166:167], v[196:197]
	v_pk_fma_f32 v[176:177], v[176:177], v[168:169], v[196:197]
	v_pk_fma_f32 v[178:179], v[178:179], v[170:171], v[196:197]
	v_pk_mul_f32 v[172:173], v[172:173], v[164:165]
	v_pk_mul_f32 v[174:175], v[174:175], v[166:167]
	v_pk_mul_f32 v[176:177], v[176:177], v[168:169]
	v_pk_mul_f32 v[178:179], v[178:179], v[170:171]
	v_pk_mul_f32 v[164:165], v[148:149], v[148:149]
	v_pk_mul_f32 v[166:167], v[150:151], v[150:151]
	v_pk_mul_f32 v[168:169], v[152:153], v[152:153]
	v_pk_mul_f32 v[170:171], v[154:155], v[154:155]
	v_pk_mul_f32 v[164:165], v[164:165], v[198:199]
	v_pk_mul_f32 v[166:167], v[166:167], v[198:199]
	v_pk_mul_f32 v[168:169], v[168:169], v[198:199]
	v_pk_mul_f32 v[170:171], v[170:171], v[198:199]
	v_exp_f32_e32 v164, v164
	v_exp_f32_e32 v165, v165
	v_exp_f32_e32 v166, v166
	v_exp_f32_e32 v167, v167
	v_exp_f32_e32 v168, v168
	v_exp_f32_e32 v169, v169
	v_exp_f32_e32 v170, v170
	v_exp_f32_e32 v171, v171
	v_pk_mul_f32 v[172:173], v[172:173], v[164:165]
	v_pk_mul_f32 v[174:175], v[174:175], v[166:167]
	v_pk_mul_f32 v[176:177], v[176:177], v[168:169]
	v_pk_mul_f32 v[178:179], v[178:179], v[170:171]
	v_pk_mul_f32 v[172:173], v[156:157], v[172:173]
	v_pk_mul_f32 v[174:175], v[158:159], v[174:175]
	v_pk_mul_f32 v[176:177], v[160:161], v[176:177]
	v_pk_mul_f32 v[178:179], v[162:163], v[178:179]
	v_max_f32_e32 v164, 0, v148
	v_max_f32_e32 v165, 0, v149
	v_max_f32_e32 v166, 0, v150
	v_max_f32_e32 v167, 0, v151
	v_max_f32_e32 v168, 0, v152
	v_max_f32_e32 v169, 0, v153
	v_max_f32_e32 v170, 0, v154
	v_max_f32_e32 v171, 0, v155
	v_pk_add_f32 v[164:165], v[164:165], v[172:173] neg_lo:[0,1] neg_hi:[0,1]
	v_pk_add_f32 v[166:167], v[166:167], v[174:175] neg_lo:[0,1] neg_hi:[0,1]
	v_pk_add_f32 v[168:169], v[168:169], v[176:177] neg_lo:[0,1] neg_hi:[0,1]
	v_pk_add_f32 v[170:171], v[170:171], v[178:179] neg_lo:[0,1] neg_hi:[0,1]
	v_pk_mul_f32 v[164:165], v[164:165], v[124:125]
	v_pk_mul_f32 v[166:167], v[166:167], v[126:127]
	v_pk_mul_f32 v[168:169], v[168:169], v[128:129]
	v_pk_mul_f32 v[170:171], v[170:171], v[130:131]
	v_cvt_pk_bf16_f32 v156, v164, v165
	v_cvt_pk_bf16_f32 v157, v166, v167
	v_cvt_pk_bf16_f32 v158, v168, v169
	v_cvt_pk_bf16_f32 v159, v170, v171
	global_store_dwordx2 v218, v[156:157], s[10:11]
	global_store_dwordx2 v219, v[158:159], s[10:11]
	v_add_u32_e32 v210, 0x2c00, v210
	v_add_u32_e32 v211, 0x2c00, v210
	v_add_u32_e32 v212, v206, v211
	global_load_dwordx2 v[96:97], v212, s[6:7]
	v_add_u32_e32 v213, v207, v211
	global_load_dwordx2 v[98:99], v213, s[6:7]
	v_add_u32_e32 v214, v208, v211
	global_load_dwordx2 v[100:101], v214, s[6:7]
	v_add_u32_e32 v215, v209, v211
	global_load_dwordx2 v[102:103], v215, s[6:7]
	v_add_u32_e32 v218, v207, v210
	global_load_dwordx2 v[116:117], v218, s[8:9]
	v_add_u32_e32 v219, v208, v210
	global_load_dwordx2 v[118:119], v219, s[8:9]
	s_waitcnt vmcnt(16)
	v_lshlrev_b32_e32 v56, 16, v104
	v_and_b32_e32 v57, 0xffff0000, v104
	v_lshlrev_b32_e32 v58, 16, v105
	v_and_b32_e32 v59, 0xffff0000, v105
	v_lshlrev_b32_e32 v60, 16, v106
	v_and_b32_e32 v61, 0xffff0000, v106
	v_lshlrev_b32_e32 v62, 16, v107
	v_and_b32_e32 v63, 0xffff0000, v107
	v_lshlrev_b32_e32 v64, 16, v108
	v_and_b32_e32 v65, 0xffff0000, v108
	v_lshlrev_b32_e32 v66, 16, v109
	v_and_b32_e32 v67, 0xffff0000, v109
	v_lshlrev_b32_e32 v68, 16, v110
	v_and_b32_e32 v69, 0xffff0000, v110
	v_lshlrev_b32_e32 v70, 16, v111
	v_and_b32_e32 v71, 0xffff0000, v111
	v_pk_mul_f32 v[56:57], v[56:57], v[200:201]
	v_pk_mul_f32 v[58:59], v[58:59], v[200:201]
	v_pk_mul_f32 v[68:69], v[68:69], v[202:203]
	v_pk_mul_f32 v[70:71], v[70:71], v[202:203]
	v_lshlrev_b32_e32 v124, 16, v120
	v_and_b32_e32 v125, 0xffff0000, v120
	v_lshlrev_b32_e32 v126, 16, v121
	v_and_b32_e32 v127, 0xffff0000, v121
	v_lshlrev_b32_e32 v128, 16, v122
	v_and_b32_e32 v129, 0xffff0000, v122
	v_lshlrev_b32_e32 v130, 16, v123
	v_and_b32_e32 v131, 0xffff0000, v123
	v_pk_fma_f32 v[148:149], v[72:73], v[0:1], v[36:37]
	v_pk_fma_f32 v[150:151], v[74:75], v[2:3], v[38:39]
	v_pk_fma_f32 v[152:153], v[76:77], v[0:1], v[36:37]
	v_pk_fma_f32 v[154:155], v[78:79], v[2:3], v[38:39]
	v_pk_fma_f32 v[148:149], v[40:41], v[4:5], v[148:149]
	v_pk_fma_f32 v[150:151], v[42:43], v[6:7], v[150:151]
	v_pk_fma_f32 v[152:153], v[44:45], v[4:5], v[152:153]
	v_pk_fma_f32 v[154:155], v[46:47], v[6:7], v[154:155]
	v_pk_fma_f32 v[148:149], v[56:57], v[8:9], v[148:149]
	v_pk_fma_f32 v[150:151], v[58:59], v[10:11], v[150:151]
	v_pk_fma_f32 v[152:153], v[60:61], v[8:9], v[152:153]
	v_pk_fma_f32 v[154:155], v[62:63], v[10:11], v[154:155]
	v_pk_fma_f32 v[148:149], v[76:77], v[12:13], v[148:149]
	v_pk_fma_f32 v[150:151], v[78:79], v[14:15], v[150:151]
	v_pk_fma_f32 v[152:153], v[80:81], v[12:13], v[152:153]
	v_pk_fma_f32 v[154:155], v[82:83], v[14:15], v[154:155]
	v_pk_fma_f32 v[148:149], v[44:45], v[16:17], v[148:149]
; __device__ __forceinline__ unsigned cvt_pk_bf16(float lo, float hi) { unsigned r; asm volatile("v_cvt_pk_bf16_f32 %0, %1, %2" : "=v"(r) : "v"(lo), "v"(hi)); return r; }
; __device__ __forceinline__ float gelu_as(float v) {
;   const float av = fabsf(v); const float t = __builtin_amdgcn_rcpf(av * 0.2316418882f + 1.0f);
;   float q = t * 0.5307027145f + (-0.7265760135f); q = q * t + 0.7107068705f; q = q * t + (-0.142248368f); q = q * t + 0.127414796f; q = q * t;
;   const float e = __builtin_amdgcn_exp2f((v * v) * (-0.72134752044f));
;   const float m = v * (q * e);
;   return v < 0.f ? m : v - m;
; }
; __device__ __forceinline__ void phase_conv(KP p, int l, int tid) {
;     ...
;       for (int q = 0; q < CB; ++q) {
;         const int col = jb + q + 1;
; #pragma unroll
;         for (int di = 0; di < RB + 2; ++di) { const bool ok = rv[di] && (col < 64); unpack4(an[q][di], win[2][di]);
; #pragma unroll
;           for (int k = 0; k < 4; ++k) win[2][di][k] = ok ? win[2][di][k] : 0.f; }
; #pragma unroll
;         for (int rr = 0; rr < RB; ++rr) {
;           float uv[4]; unpack4(ur[q][rr], uv);
;           float o[4];
; #pragma unroll
;           for (int k = 0; k < 4; ++k) {
;             float a = bsv[k];
; #pragma unroll
;             for (int di = 0; di < 3; ++di)
; #pragma unroll
;               for (int dj = 0; dj < 3; ++dj) a += win[dj][rr + di][k] * w[di * 3 + dj][k];
;             o[k] = gelu_as(a) * uv[k];
;           }
;           u32x2 ow; ow.x = cvt_pk_bf16(o[0], o[1]); ow.y = cvt_pk_bf16(o[2], o[3]);
;           *(u32x2*)(G + (size_t)((r0 + rr) * 64 + jb + q) * DFF + c0) = ow;
;         }
; #pragma unroll
;         for (int di = 0; di < RB + 2; ++di)
; #pragma unroll
;           for (int k = 0; k < 4; ++k) { win[0][di][k] = win[1][di][k]; win[1][di][k] = win[2][di][k]; }
	v_pk_fma_f32 v[150:151], v[46:47], v[18:19], v[150:151]
	v_pk_fma_f32 v[152:153], v[48:49], v[16:17], v[152:153]
	v_pk_fma_f32 v[154:155], v[50:51], v[18:19], v[154:155]
	v_pk_fma_f32 v[148:149], v[60:61], v[20:21], v[148:149]
	v_pk_fma_f32 v[150:151], v[62:63], v[22:23], v[150:151]
	v_pk_fma_f32 v[152:153], v[64:65], v[20:21], v[152:153]
	v_pk_fma_f32 v[154:155], v[66:67], v[22:23], v[154:155]
	v_pk_fma_f32 v[148:149], v[80:81], v[24:25], v[148:149]
	v_pk_fma_f32 v[150:151], v[82:83], v[26:27], v[150:151]
	v_pk_fma_f32 v[152:153], v[84:85], v[24:25], v[152:153]
	v_pk_fma_f32 v[154:155], v[86:87], v[26:27], v[154:155]
	v_pk_fma_f32 v[148:149], v[48:49], v[28:29], v[148:149]
	v_pk_fma_f32 v[150:151], v[50:51], v[30:31], v[150:151]
	v_pk_fma_f32 v[152:153], v[52:53], v[28:29], v[152:153]
	v_pk_fma_f32 v[154:155], v[54:55], v[30:31], v[154:155]
	v_pk_fma_f32 v[148:149], v[64:65], v[32:33], v[148:149]
	v_pk_fma_f32 v[150:151], v[66:67], v[34:35], v[150:151]
	v_pk_fma_f32 v[152:153], v[68:69], v[32:33], v[152:153]
	v_pk_fma_f32 v[154:155], v[70:71], v[34:35], v[154:155]
	v_and_b32_e32 v156, 0x7fffffff, v148
	v_and_b32_e32 v157, 0x7fffffff, v149
	v_and_b32_e32 v158, 0x7fffffff, v150
	v_and_b32_e32 v159, 0x7fffffff, v151
	v_and_b32_e32 v160, 0x7fffffff, v152
	v_and_b32_e32 v161, 0x7fffffff, v153
	v_and_b32_e32 v162, 0x7fffffff, v154
	v_and_b32_e32 v163, 0x7fffffff, v155
	v_pk_fma_f32 v[164:165], v[156:157], v[184:185], v[186:187]
	v_pk_fma_f32 v[166:167], v[158:159], v[184:185], v[186:187]
	v_pk_fma_f32 v[168:169], v[160:161], v[184:185], v[186:187]
	v_pk_fma_f32 v[170:171], v[162:163], v[184:185], v[186:187]
	v_rcp_f32_e32 v164, v164
	v_rcp_f32_e32 v165, v165
	v_rcp_f32_e32 v166, v166
	v_rcp_f32_e32 v167, v167
	v_rcp_f32_e32 v168, v168
	v_rcp_f32_e32 v169, v169
	v_rcp_f32_e32 v170, v170
	v_rcp_f32_e32 v171, v171
	v_pk_fma_f32 v[172:173], v[164:165], v[188:189], v[190:191]
	v_pk_fma_f32 v[174:175], v[166:167], v[188:189], v[190:191]
	v_pk_fma_f32 v[176:177], v[168:169], v[188:189], v[190:191]
	v_pk_fma_f32 v[178:179], v[170:171], v[188:189], v[190:191]
	v_pk_fma_f32 v[172:173], v[172:173], v[164:165], v[192:193]
	v_pk_fma_f32 v[174:175], v[174:175], v[166:167], v[192:193]
	v_pk_fma_f32 v[176:177], v[176:177], v[168:169], v[192:193]
	v_pk_fma_f32 v[178:179], v[178:179], v[170:171], v[192:193]
	v_pk_fma_f32 v[172:173], v[172:173], v[164:165], v[194:195]
	v_pk_fma_f32 v[174:175], v[174:175], v[166:167], v[194:195]
	v_pk_fma_f32 v[176:177], v[176:177], v[168:169], v[194:195]
	v_pk_fma_f32 v[178:179], v[178:179], v[170:171], v[194:195]
	v_pk_fma_f32 v[172:173], v[172:173], v[164:165], v[196:197]
	v_pk_fma_f32 v[174:175], v[174:175], v[166:167], v[196:197]
	v_pk_fma_f32 v[176:177], v[176:177], v[168:169], v[196:197]
	v_pk_fma_f32 v[178:179], v[178:179], v[170:171], v[196:197]
	v_pk_mul_f32 v[172:173], v[172:173], v[164:165]
	v_pk_mul_f32 v[174:175], v[174:175], v[166:167]
	v_pk_mul_f32 v[176:177], v[176:177], v[168:169]
	v_pk_mul_f32 v[178:179], v[178:179], v[170:171]
	v_pk_mul_f32 v[164:165], v[148:149], v[148:149]
	v_pk_mul_f32 v[166:167], v[150:151], v[150:151]
	v_pk_mul_f32 v[168:169], v[152:153], v[152:153]
	v_pk_mul_f32 v[170:171], v[154:155], v[154:155]
	v_pk_mul_f32 v[164:165], v[164:165], v[198:199]
	v_pk_mul_f32 v[166:167], v[166:167], v[198:199]
	v_pk_mul_f32 v[168:169], v[168:169], v[198:199]
	v_pk_mul_f32 v[170:171], v[170:171], v[198:199]
	v_exp_f32_e32 v164, v164
	v_exp_f32_e32 v165, v165
	v_exp_f32_e32 v166, v166
	v_exp_f32_e32 v167, v167
	v_exp_f32_e32 v168, v168
	v_exp_f32_e32 v169, v169
	v_exp_f32_e32 v170, v170
	v_exp_f32_e32 v171, v171
	v_pk_mul_f32 v[172:173], v[172:173], v[164:165]
	v_pk_mul_f32 v[174:175], v[174:175], v[166:167]
	v_pk_mul_f32 v[176:177], v[176:177], v[168:169]
	v_pk_mul_f32 v[178:179], v[178:179], v[170:171]
	v_pk_mul_f32 v[172:173], v[156:157], v[172:173]
	v_pk_mul_f32 v[174:175], v[158:159], v[174:175]
	v_pk_mul_f32 v[176:177], v[160:161], v[176:177]
	v_pk_mul_f32 v[178:179], v[162:163], v[178:179]
	v_max_f32_e32 v164, 0, v148
	v_max_f32_e32 v165, 0, v149
	v_max_f32_e32 v166, 0, v150
	v_max_f32_e32 v167, 0, v151
	v_max_f32_e32 v168, 0, v152
	v_max_f32_e32 v169, 0, v153
	v_max_f32_e32 v170, 0, v154
	v_max_f32_e32 v171, 0, v155
	v_pk_add_f32 v[164:165], v[164:165], v[172:173] neg_lo:[0,1] neg_hi:[0,1]
	v_pk_add_f32 v[166:167], v[166:167], v[174:175] neg_lo:[0,1] neg_hi:[0,1]
	v_pk_add_f32 v[168:169], v[168:169], v[176:177] neg_lo:[0,1] neg_hi:[0,1]
	v_pk_add_f32 v[170:171], v[170:171], v[178:179] neg_lo:[0,1] neg_hi:[0,1]
	v_pk_mul_f32 v[164:165], v[164:165], v[124:125]
	v_pk_mul_f32 v[166:167], v[166:167], v[126:127]
	v_pk_mul_f32 v[168:169], v[168:169], v[128:129]
	v_pk_mul_f32 v[170:171], v[170:171], v[130:131]
	v_cvt_pk_bf16_f32 v156, v164, v165
	v_cvt_pk_bf16_f32 v157, v166, v167
	v_cvt_pk_bf16_f32 v158, v168, v169
	v_cvt_pk_bf16_f32 v159, v170, v171
	global_store_dwordx2 v220, v[156:157], s[10:11]
	global_store_dwordx2 v221, v[158:159], s[10:11]
	v_add_u32_e32 v210, 0x2c00, v210
	v_add_u32_e32 v211, 0x2c00, v210
	v_add_u32_e32 v212, v206, v211
	global_load_dwordx2 v[104:105], v212, s[6:7]
	v_add_u32_e32 v213, v207, v211
	global_load_dwordx2 v[106:107], v213, s[6:7]
	v_add_u32_e32 v214, v208, v211
	global_load_dwordx2 v[108:109], v214, s[6:7]
	v_add_u32_e32 v215, v209, v211
	global_load_dwordx2 v[110:111], v215, s[6:7]
	v_add_u32_e32 v220, v207, v210
	global_load_dwordx2 v[120:121], v220, s[8:9]
	v_add_u32_e32 v221, v208, v210
	global_load_dwordx2 v[122:123], v221, s[8:9]
	s_waitcnt vmcnt(16)
; __device__ __forceinline__ unsigned cvt_pk_bf16(float lo, float hi) { unsigned r; asm volatile("v_cvt_pk_bf16_f32 %0, %1, %2" : "=v"(r) : "v"(lo), "v"(hi)); return r; }
; __device__ __forceinline__ float gelu_as(float v) {
;   const float av = fabsf(v); const float t = __builtin_amdgcn_rcpf(av * 0.2316418882f + 1.0f);
;   float q = t * 0.5307027145f + (-0.7265760135f); q = q * t + 0.7107068705f; q = q * t + (-0.142248368f); q = q * t + 0.127414796f; q = q * t;
;   const float e = __builtin_amdgcn_exp2f((v * v) * (-0.72134752044f));
;   const float m = v * (q * e);
;   return v < 0.f ? m : v - m;
; }
; __device__ __forceinline__ void phase_conv(KP p, int l, int tid) {
;     ...
;       for (int q = 0; q < CB; ++q) {
;         const int col = jb + q + 1;
; #pragma unroll
;         for (int di = 0; di < RB + 2; ++di) { const bool ok = rv[di] && (col < 64); unpack4(an[q][di], win[2][di]);
; #pragma unroll
;           for (int k = 0; k < 4; ++k) win[2][di][k] = ok ? win[2][di][k] : 0.f; }
; #pragma unroll
;         for (int rr = 0; rr < RB; ++rr) {
;           float uv[4]; unpack4(ur[q][rr], uv);
;           float o[4];
; #pragma unroll
;           for (int k = 0; k < 4; ++k) {
;             float a = bsv[k];
; #pragma unroll
;             for (int di = 0; di < 3; ++di)
; #pragma unroll
;               for (int dj = 0; dj < 3; ++dj) a += win[dj][rr + di][k] * w[di * 3 + dj][k];
;             o[k] = gelu_as(a) * uv[k];
;           }
;           u32x2 ow; ow.x = cvt_pk_bf16(o[0], o[1]); ow.y = cvt_pk_bf16(o[2], o[3]);
;           *(u32x2*)(G + (size_t)((r0 + rr) * 64 + jb + q) * DFF + c0) = ow;
;         }
; #pragma unroll
;         for (int di = 0; di < RB + 2; ++di)
; #pragma unroll
;           for (int k = 0; k < 4; ++k) { win[0][di][k] = win[1][di][k]; win[1][di][k] = win[2][di][k]; }
	v_lshlrev_b32_e32 v72, 16, v88
	v_and_b32_e32 v73, 0xffff0000, v88
	v_lshlrev_b32_e32 v74, 16, v89
	v_and_b32_e32 v75, 0xffff0000, v89
	v_lshlrev_b32_e32 v76, 16, v90
	v_and_b32_e32 v77, 0xffff0000, v90
	v_lshlrev_b32_e32 v78, 16, v91
	v_and_b32_e32 v79, 0xffff0000, v91
	v_lshlrev_b32_e32 v80, 16, v92
	v_and_b32_e32 v81, 0xffff0000, v92
	v_lshlrev_b32_e32 v82, 16, v93
	v_and_b32_e32 v83, 0xffff0000, v93
	v_lshlrev_b32_e32 v84, 16, v94
	v_and_b32_e32 v85, 0xffff0000, v94
	v_lshlrev_b32_e32 v86, 16, v95
	v_and_b32_e32 v87, 0xffff0000, v95
	v_pk_mul_f32 v[72:73], v[72:73], v[200:201]
	v_pk_mul_f32 v[74:75], v[74:75], v[200:201]
	v_pk_mul_f32 v[84:85], v[84:85], v[202:203]
	v_pk_mul_f32 v[86:87], v[86:87], v[202:203]
	v_lshlrev_b32_e32 v124, 16, v112
	v_and_b32_e32 v125, 0xffff0000, v112
	v_lshlrev_b32_e32 v126, 16, v113
	v_and_b32_e32 v127, 0xffff0000, v113
	v_lshlrev_b32_e32 v128, 16, v114
	v_and_b32_e32 v129, 0xffff0000, v114
	v_lshlrev_b32_e32 v130, 16, v115
	v_and_b32_e32 v131, 0xffff0000, v115
	v_pk_fma_f32 v[148:149], v[40:41], v[0:1], v[36:37]
	v_pk_fma_f32 v[150:151], v[42:43], v[2:3], v[38:39]
	v_pk_fma_f32 v[152:153], v[44:45], v[0:1], v[36:37]
	v_pk_fma_f32 v[154:155], v[46:47], v[2:3], v[38:39]
	v_pk_fma_f32 v[148:149], v[56:57], v[4:5], v[148:149]
	v_pk_fma_f32 v[150:151], v[58:59], v[6:7], v[150:151]
	v_pk_fma_f32 v[152:153], v[60:61], v[4:5], v[152:153]
	v_pk_fma_f32 v[154:155], v[62:63], v[6:7], v[154:155]
	v_pk_fma_f32 v[148:149], v[72:73], v[8:9], v[148:149]
	v_pk_fma_f32 v[150:151], v[74:75], v[10:11], v[150:151]
	v_pk_fma_f32 v[152:153], v[76:77], v[8:9], v[152:153]
	v_pk_fma_f32 v[154:155], v[78:79], v[10:11], v[154:155]
	v_pk_fma_f32 v[148:149], v[44:45], v[12:13], v[148:149]
	v_pk_fma_f32 v[150:151], v[46:47], v[14:15], v[150:151]
	v_pk_fma_f32 v[152:153], v[48:49], v[12:13], v[152:153]
	v_pk_fma_f32 v[154:155], v[50:51], v[14:15], v[154:155]
	v_pk_fma_f32 v[148:149], v[60:61], v[16:17], v[148:149]
	v_pk_fma_f32 v[150:151], v[62:63], v[18:19], v[150:151]
	v_pk_fma_f32 v[152:153], v[64:65], v[16:17], v[152:153]
	v_pk_fma_f32 v[154:155], v[66:67], v[18:19], v[154:155]
	v_pk_fma_f32 v[148:149], v[76:77], v[20:21], v[148:149]
	v_pk_fma_f32 v[150:151], v[78:79], v[22:23], v[150:151]
	v_pk_fma_f32 v[152:153], v[80:81], v[20:21], v[152:153]
	v_pk_fma_f32 v[154:155], v[82:83], v[22:23], v[154:155]
	v_pk_fma_f32 v[148:149], v[48:49], v[24:25], v[148:149]
	v_pk_fma_f32 v[150:151], v[50:51], v[26:27], v[150:151]
	v_pk_fma_f32 v[152:153], v[52:53], v[24:25], v[152:153]
	v_pk_fma_f32 v[154:155], v[54:55], v[26:27], v[154:155]
	v_pk_fma_f32 v[148:149], v[64:65], v[28:29], v[148:149]
	v_pk_fma_f32 v[150:151], v[66:67], v[30:31], v[150:151]
	v_pk_fma_f32 v[152:153], v[68:69], v[28:29], v[152:153]
	v_pk_fma_f32 v[154:155], v[70:71], v[30:31], v[154:155]
	v_pk_fma_f32 v[148:149], v[80:81], v[32:33], v[148:149]
	v_pk_fma_f32 v[150:151], v[82:83], v[34:35], v[150:151]
	v_pk_fma_f32 v[152:153], v[84:85], v[32:33], v[152:153]
	v_pk_fma_f32 v[154:155], v[86:87], v[34:35], v[154:155]
	v_and_b32_e32 v156, 0x7fffffff, v148
	v_and_b32_e32 v157, 0x7fffffff, v149
	v_and_b32_e32 v158, 0x7fffffff, v150
	v_and_b32_e32 v159, 0x7fffffff, v151
	v_and_b32_e32 v160, 0x7fffffff, v152
	v_and_b32_e32 v161, 0x7fffffff, v153
	v_and_b32_e32 v162, 0x7fffffff, v154
	v_and_b32_e32 v163, 0x7fffffff, v155
	v_pk_fma_f32 v[164:165], v[156:157], v[184:185], v[186:187]
	v_pk_fma_f32 v[166:167], v[158:159], v[184:185], v[186:187]
	v_pk_fma_f32 v[168:169], v[160:161], v[184:185], v[186:187]
	v_pk_fma_f32 v[170:171], v[162:163], v[184:185], v[186:187]
	v_rcp_f32_e32 v164, v164
	v_rcp_f32_e32 v165, v165
	v_rcp_f32_e32 v166, v166
	v_rcp_f32_e32 v167, v167
	v_rcp_f32_e32 v168, v168
	v_rcp_f32_e32 v169, v169
	v_rcp_f32_e32 v170, v170
	v_rcp_f32_e32 v171, v171
	v_pk_fma_f32 v[172:173], v[164:165], v[188:189], v[190:191]
	v_pk_fma_f32 v[174:175], v[166:167], v[188:189], v[190:191]
	v_pk_fma_f32 v[176:177], v[168:169], v[188:189], v[190:191]
	v_pk_fma_f32 v[178:179], v[170:171], v[188:189], v[190:191]
	v_pk_fma_f32 v[172:173], v[172:173], v[164:165], v[192:193]
	v_pk_fma_f32 v[174:175], v[174:175], v[166:167], v[192:193]
	v_pk_fma_f32 v[176:177], v[176:177], v[168:169], v[192:193]
	v_pk_fma_f32 v[178:179], v[178:179], v[170:171], v[192:193]
	v_pk_fma_f32 v[172:173], v[172:173], v[164:165], v[194:195]
	v_pk_fma_f32 v[174:175], v[174:175], v[166:167], v[194:195]
	v_pk_fma_f32 v[176:177], v[176:177], v[168:169], v[194:195]
	v_pk_fma_f32 v[178:179], v[178:179], v[170:171], v[194:195]
	v_pk_fma_f32 v[172:173], v[172:173], v[164:165], v[196:197]
	v_pk_fma_f32 v[174:175], v[174:175], v[166:167], v[196:197]
	v_pk_fma_f32 v[176:177], v[176:177], v[168:169], v[196:197]
	v_pk_fma_f32 v[178:179], v[178:179], v[170:171], v[196:197]
	v_pk_mul_f32 v[172:173], v[172:173], v[164:165]
	v_pk_mul_f32 v[174:175], v[174:175], v[166:167]
	v_pk_mul_f32 v[176:177], v[176:177], v[168:169]
	v_pk_mul_f32 v[178:179], v[178:179], v[170:171]
	v_pk_mul_f32 v[164:165], v[148:149], v[148:149]
	v_pk_mul_f32 v[166:167], v[150:151], v[150:151]
	v_pk_mul_f32 v[168:169], v[152:153], v[152:153]
	v_pk_mul_f32 v[170:171], v[154:155], v[154:155]
	v_pk_mul_f32 v[164:165], v[164:165], v[198:199]
	v_pk_mul_f32 v[166:167], v[166:167], v[198:199]
	v_pk_mul_f32 v[168:169], v[168:169], v[198:199]
	v_pk_mul_f32 v[170:171], v[170:171], v[198:199]
	v_exp_f32_e32 v164, v164
	v_exp_f32_e32 v165, v165
	v_exp_f32_e32 v166, v166
	v_exp_f32_e32 v167, v167
	v_exp_f32_e32 v168, v168
	v_exp_f32_e32 v169, v169
	v_exp_f32_e32 v170, v170
	v_exp_f32_e32 v171, v171
	v_pk_mul_f32 v[172:173], v[172:173], v[164:165]
	v_pk_mul_f32 v[174:175], v[174:175], v[166:167]
; __device__ __forceinline__ unsigned cvt_pk_bf16(float lo, float hi) { unsigned r; asm volatile("v_cvt_pk_bf16_f32 %0, %1, %2" : "=v"(r) : "v"(lo), "v"(hi)); return r; }
; __device__ __forceinline__ float gelu_as(float v) {
;   const float av = fabsf(v); const float t = __builtin_amdgcn_rcpf(av * 0.2316418882f + 1.0f);
;   float q = t * 0.5307027145f + (-0.7265760135f); q = q * t + 0.7107068705f; q = q * t + (-0.142248368f); q = q * t + 0.127414796f; q = q * t;
;   const float e = __builtin_amdgcn_exp2f((v * v) * (-0.72134752044f));
;   const float m = v * (q * e);
;   return v < 0.f ? m : v - m;
; }
; __device__ __forceinline__ void phase_conv(KP p, int l, int tid) {
;     ...
;       for (int q = 0; q < CB; ++q) {
;         const int col = jb + q + 1;
; #pragma unroll
;         for (int di = 0; di < RB + 2; ++di) { const bool ok = rv[di] && (col < 64); unpack4(an[q][di], win[2][di]);
; #pragma unroll
;           for (int k = 0; k < 4; ++k) win[2][di][k] = ok ? win[2][di][k] : 0.f; }
; #pragma unroll
;         for (int rr = 0; rr < RB; ++rr) {
;           float uv[4]; unpack4(ur[q][rr], uv);
;           float o[4];
; #pragma unroll
;           for (int k = 0; k < 4; ++k) {
;             float a = bsv[k];
; #pragma unroll
;             for (int di = 0; di < 3; ++di)
; #pragma unroll
;               for (int dj = 0; dj < 3; ++dj) a += win[dj][rr + di][k] * w[di * 3 + dj][k];
;             o[k] = gelu_as(a) * uv[k];
;           }
;           u32x2 ow; ow.x = cvt_pk_bf16(o[0], o[1]); ow.y = cvt_pk_bf16(o[2], o[3]);
;           *(u32x2*)(G + (size_t)((r0 + rr) * 64 + jb + q) * DFF + c0) = ow;
;         }
; #pragma unroll
;         for (int di = 0; di < RB + 2; ++di)
; #pragma unroll
;           for (int k = 0; k < 4; ++k) { win[0][di][k] = win[1][di][k]; win[1][di][k] = win[2][di][k]; }
	v_pk_mul_f32 v[176:177], v[176:177], v[168:169]
	v_pk_mul_f32 v[178:179], v[178:179], v[170:171]
	v_pk_mul_f32 v[172:173], v[156:157], v[172:173]
	v_pk_mul_f32 v[174:175], v[158:159], v[174:175]
	v_pk_mul_f32 v[176:177], v[160:161], v[176:177]
	v_pk_mul_f32 v[178:179], v[162:163], v[178:179]
	v_max_f32_e32 v164, 0, v148
	v_max_f32_e32 v165, 0, v149
	v_max_f32_e32 v166, 0, v150
	v_max_f32_e32 v167, 0, v151
	v_max_f32_e32 v168, 0, v152
	v_max_f32_e32 v169, 0, v153
	v_max_f32_e32 v170, 0, v154
	v_max_f32_e32 v171, 0, v155
	v_pk_add_f32 v[164:165], v[164:165], v[172:173] neg_lo:[0,1] neg_hi:[0,1]
	v_pk_add_f32 v[166:167], v[166:167], v[174:175] neg_lo:[0,1] neg_hi:[0,1]
	v_pk_add_f32 v[168:169], v[168:169], v[176:177] neg_lo:[0,1] neg_hi:[0,1]
	v_pk_add_f32 v[170:171], v[170:171], v[178:179] neg_lo:[0,1] neg_hi:[0,1]
	v_pk_mul_f32 v[164:165], v[164:165], v[124:125]
	v_pk_mul_f32 v[166:167], v[166:167], v[126:127]
	v_pk_mul_f32 v[168:169], v[168:169], v[128:129]
	v_pk_mul_f32 v[170:171], v[170:171], v[130:131]
	v_cvt_pk_bf16_f32 v156, v164, v165
	v_cvt_pk_bf16_f32 v157, v166, v167
	v_cvt_pk_bf16_f32 v158, v168, v169
	v_cvt_pk_bf16_f32 v159, v170, v171
	global_store_dwordx2 v216, v[156:157], s[10:11]
	global_store_dwordx2 v217, v[158:159], s[10:11]
	v_add_u32_e32 v210, 0x2c00, v210
	v_add_u32_e32 v211, 0x2c00, v210
	v_add_u32_e32 v212, v206, v211
	global_load_dwordx2 v[88:89], v212, s[6:7]
	v_add_u32_e32 v213, v207, v211
	global_load_dwordx2 v[90:91], v213, s[6:7]
	v_add_u32_e32 v214, v208, v211
	global_load_dwordx2 v[92:93], v214, s[6:7]
	v_add_u32_e32 v215, v209, v211
	global_load_dwordx2 v[94:95], v215, s[6:7]
	v_add_u32_e32 v216, v207, v210
	global_load_dwordx2 v[112:113], v216, s[8:9]
	v_add_u32_e32 v217, v208, v210
	global_load_dwordx2 v[114:115], v217, s[8:9]
	s_waitcnt vmcnt(16)
	v_lshlrev_b32_e32 v40, 16, v96
	v_and_b32_e32 v41, 0xffff0000, v96
	v_lshlrev_b32_e32 v42, 16, v97
	v_and_b32_e32 v43, 0xffff0000, v97
	v_lshlrev_b32_e32 v44, 16, v98
	v_and_b32_e32 v45, 0xffff0000, v98
	v_lshlrev_b32_e32 v46, 16, v99
	v_and_b32_e32 v47, 0xffff0000, v99
	v_lshlrev_b32_e32 v48, 16, v100
	v_and_b32_e32 v49, 0xffff0000, v100
	v_lshlrev_b32_e32 v50, 16, v101
	v_and_b32_e32 v51, 0xffff0000, v101
	v_lshlrev_b32_e32 v52, 16, v102
	v_and_b32_e32 v53, 0xffff0000, v102
	v_lshlrev_b32_e32 v54, 16, v103
	v_and_b32_e32 v55, 0xffff0000, v103
	v_pk_mul_f32 v[40:41], v[40:41], v[200:201]
	v_pk_mul_f32 v[42:43], v[42:43], v[200:201]
	v_pk_mul_f32 v[52:53], v[52:53], v[202:203]
	v_pk_mul_f32 v[54:55], v[54:55], v[202:203]
	v_lshlrev_b32_e32 v124, 16, v116
	v_and_b32_e32 v125, 0xffff0000, v116
	v_lshlrev_b32_e32 v126, 16, v117
	v_and_b32_e32 v127, 0xffff0000, v117
	v_lshlrev_b32_e32 v128, 16, v118
	v_and_b32_e32 v129, 0xffff0000, v118
	v_lshlrev_b32_e32 v130, 16, v119
	v_and_b32_e32 v131, 0xffff0000, v119
	v_pk_fma_f32 v[148:149], v[56:57], v[0:1], v[36:37]
	v_pk_fma_f32 v[150:151], v[58:59], v[2:3], v[38:39]
	v_pk_fma_f32 v[152:153], v[60:61], v[0:1], v[36:37]
	v_pk_fma_f32 v[154:155], v[62:63], v[2:3], v[38:39]
	v_pk_fma_f32 v[148:149], v[72:73], v[4:5], v[148:149]
	v_pk_fma_f32 v[150:151], v[74:75], v[6:7], v[150:151]
	v_pk_fma_f32 v[152:153], v[76:77], v[4:5], v[152:153]
	v_pk_fma_f32 v[154:155], v[78:79], v[6:7], v[154:155]
	v_pk_fma_f32 v[148:149], v[40:41], v[8:9], v[148:149]
	v_pk_fma_f32 v[150:151], v[42:43], v[10:11], v[150:151]
	v_pk_fma_f32 v[152:153], v[44:45], v[8:9], v[152:153]
	v_pk_fma_f32 v[154:155], v[46:47], v[10:11], v[154:155]
	v_pk_fma_f32 v[148:149], v[60:61], v[12:13], v[148:149]
	v_pk_fma_f32 v[150:151], v[62:63], v[14:15], v[150:151]
	v_pk_fma_f32 v[152:153], v[64:65], v[12:13], v[152:153]
	v_pk_fma_f32 v[154:155], v[66:67], v[14:15], v[154:155]
	v_pk_fma_f32 v[148:149], v[76:77], v[16:17], v[148:149]
	v_pk_fma_f32 v[150:151], v[78:79], v[18:19], v[150:151]
	v_pk_fma_f32 v[152:153], v[80:81], v[16:17], v[152:153]
	v_pk_fma_f32 v[154:155], v[82:83], v[18:19], v[154:155]
	v_pk_fma_f32 v[148:149], v[44:45], v[20:21], v[148:149]
	v_pk_fma_f32 v[150:151], v[46:47], v[22:23], v[150:151]
	v_pk_fma_f32 v[152:153], v[48:49], v[20:21], v[152:153]
	v_pk_fma_f32 v[154:155], v[50:51], v[22:23], v[154:155]
	v_pk_fma_f32 v[148:149], v[64:65], v[24:25], v[148:149]
	v_pk_fma_f32 v[150:151], v[66:67], v[26:27], v[150:151]
	v_pk_fma_f32 v[152:153], v[68:69], v[24:25], v[152:153]
	v_pk_fma_f32 v[154:155], v[70:71], v[26:27], v[154:155]
	v_pk_fma_f32 v[148:149], v[80:81], v[28:29], v[148:149]
	v_pk_fma_f32 v[150:151], v[82:83], v[30:31], v[150:151]
	v_pk_fma_f32 v[152:153], v[84:85], v[28:29], v[152:153]
	v_pk_fma_f32 v[154:155], v[86:87], v[30:31], v[154:155]
	v_pk_fma_f32 v[148:149], v[48:49], v[32:33], v[148:149]
	v_pk_fma_f32 v[150:151], v[50:51], v[34:35], v[150:151]
	v_pk_fma_f32 v[152:153], v[52:53], v[32:33], v[152:153]
	v_pk_fma_f32 v[154:155], v[54:55], v[34:35], v[154:155]
	v_and_b32_e32 v156, 0x7fffffff, v148
	v_and_b32_e32 v157, 0x7fffffff, v149
	v_and_b32_e32 v158, 0x7fffffff, v150
	v_and_b32_e32 v159, 0x7fffffff, v151
	v_and_b32_e32 v160, 0x7fffffff, v152
	v_and_b32_e32 v161, 0x7fffffff, v153
	v_and_b32_e32 v162, 0x7fffffff, v154
	v_and_b32_e32 v163, 0x7fffffff, v155
	v_pk_fma_f32 v[164:165], v[156:157], v[184:185], v[186:187]
	v_pk_fma_f32 v[166:167], v[158:159], v[184:185], v[186:187]
	v_pk_fma_f32 v[168:169], v[160:161], v[184:185], v[186:187]
	v_pk_fma_f32 v[170:171], v[162:163], v[184:185], v[186:187]
	v_rcp_f32_e32 v164, v164
	v_rcp_f32_e32 v165, v165
	v_rcp_f32_e32 v166, v166
	v_rcp_f32_e32 v167, v167
	v_rcp_f32_e32 v168, v168
	v_rcp_f32_e32 v169, v169
	v_rcp_f32_e32 v170, v170
	v_rcp_f32_e32 v171, v171
; __device__ __forceinline__ unsigned cvt_pk_bf16(float lo, float hi) { unsigned r; asm volatile("v_cvt_pk_bf16_f32 %0, %1, %2" : "=v"(r) : "v"(lo), "v"(hi)); return r; }
; __device__ __forceinline__ float gelu_as(float v) {
;   const float av = fabsf(v); const float t = __builtin_amdgcn_rcpf(av * 0.2316418882f + 1.0f);
;   float q = t * 0.5307027145f + (-0.7265760135f); q = q * t + 0.7107068705f; q = q * t + (-0.142248368f); q = q * t + 0.127414796f; q = q * t;
;   const float e = __builtin_amdgcn_exp2f((v * v) * (-0.72134752044f));
;   const float m = v * (q * e);
;   return v < 0.f ? m : v - m;
; }
; __device__ __forceinline__ void phase_conv(KP p, int l, int tid) {
;     ...
;       for (int q = 0; q < CB; ++q) {
;         const int col = jb + q + 1;
; #pragma unroll
;         for (int di = 0; di < RB + 2; ++di) { const bool ok = rv[di] && (col < 64); unpack4(an[q][di], win[2][di]);
; #pragma unroll
;           for (int k = 0; k < 4; ++k) win[2][di][k] = ok ? win[2][di][k] : 0.f; }
; #pragma unroll
;         for (int rr = 0; rr < RB; ++rr) {
;           float uv[4]; unpack4(ur[q][rr], uv);
;           float o[4];
; #pragma unroll
;           for (int k = 0; k < 4; ++k) {
;             float a = bsv[k];
; #pragma unroll
;             for (int di = 0; di < 3; ++di)
; #pragma unroll
;               for (int dj = 0; dj < 3; ++dj) a += win[dj][rr + di][k] * w[di * 3 + dj][k];
;             o[k] = gelu_as(a) * uv[k];
;           }
;           u32x2 ow; ow.x = cvt_pk_bf16(o[0], o[1]); ow.y = cvt_pk_bf16(o[2], o[3]);
;           *(u32x2*)(G + (size_t)((r0 + rr) * 64 + jb + q) * DFF + c0) = ow;
;         }
; #pragma unroll
;         for (int di = 0; di < RB + 2; ++di)
; #pragma unroll
;           for (int k = 0; k < 4; ++k) { win[0][di][k] = win[1][di][k]; win[1][di][k] = win[2][di][k]; }
	v_pk_fma_f32 v[172:173], v[164:165], v[188:189], v[190:191]
	v_pk_fma_f32 v[174:175], v[166:167], v[188:189], v[190:191]
	v_pk_fma_f32 v[176:177], v[168:169], v[188:189], v[190:191]
	v_pk_fma_f32 v[178:179], v[170:171], v[188:189], v[190:191]
	v_pk_fma_f32 v[172:173], v[172:173], v[164:165], v[192:193]
	v_pk_fma_f32 v[174:175], v[174:175], v[166:167], v[192:193]
	v_pk_fma_f32 v[176:177], v[176:177], v[168:169], v[192:193]
	v_pk_fma_f32 v[178:179], v[178:179], v[170:171], v[192:193]
	v_pk_fma_f32 v[172:173], v[172:173], v[164:165], v[194:195]
	v_pk_fma_f32 v[174:175], v[174:175], v[166:167], v[194:195]
	v_pk_fma_f32 v[176:177], v[176:177], v[168:169], v[194:195]
	v_pk_fma_f32 v[178:179], v[178:179], v[170:171], v[194:195]
	v_pk_fma_f32 v[172:173], v[172:173], v[164:165], v[196:197]
	v_pk_fma_f32 v[174:175], v[174:175], v[166:167], v[196:197]
	v_pk_fma_f32 v[176:177], v[176:177], v[168:169], v[196:197]
	v_pk_fma_f32 v[178:179], v[178:179], v[170:171], v[196:197]
	v_pk_mul_f32 v[172:173], v[172:173], v[164:165]
	v_pk_mul_f32 v[174:175], v[174:175], v[166:167]
	v_pk_mul_f32 v[176:177], v[176:177], v[168:169]
	v_pk_mul_f32 v[178:179], v[178:179], v[170:171]
	v_pk_mul_f32 v[164:165], v[148:149], v[148:149]
	v_pk_mul_f32 v[166:167], v[150:151], v[150:151]
	v_pk_mul_f32 v[168:169], v[152:153], v[152:153]
	v_pk_mul_f32 v[170:171], v[154:155], v[154:155]
	v_pk_mul_f32 v[164:165], v[164:165], v[198:199]
	v_pk_mul_f32 v[166:167], v[166:167], v[198:199]
	v_pk_mul_f32 v[168:169], v[168:169], v[198:199]
	v_pk_mul_f32 v[170:171], v[170:171], v[198:199]
	v_exp_f32_e32 v164, v164
	v_exp_f32_e32 v165, v165
	v_exp_f32_e32 v166, v166
	v_exp_f32_e32 v167, v167
	v_exp_f32_e32 v168, v168
	v_exp_f32_e32 v169, v169
	v_exp_f32_e32 v170, v170
	v_exp_f32_e32 v171, v171
	v_pk_mul_f32 v[172:173], v[172:173], v[164:165]
	v_pk_mul_f32 v[174:175], v[174:175], v[166:167]
	v_pk_mul_f32 v[176:177], v[176:177], v[168:169]
	v_pk_mul_f32 v[178:179], v[178:179], v[170:171]
	v_pk_mul_f32 v[172:173], v[156:157], v[172:173]
	v_pk_mul_f32 v[174:175], v[158:159], v[174:175]
	v_pk_mul_f32 v[176:177], v[160:161], v[176:177]
	v_pk_mul_f32 v[178:179], v[162:163], v[178:179]
	v_max_f32_e32 v164, 0, v148
	v_max_f32_e32 v165, 0, v149
	v_max_f32_e32 v166, 0, v150
	v_max_f32_e32 v167, 0, v151
	v_max_f32_e32 v168, 0, v152
	v_max_f32_e32 v169, 0, v153
	v_max_f32_e32 v170, 0, v154
	v_max_f32_e32 v171, 0, v155
	v_pk_add_f32 v[164:165], v[164:165], v[172:173] neg_lo:[0,1] neg_hi:[0,1]
	v_pk_add_f32 v[166:167], v[166:167], v[174:175] neg_lo:[0,1] neg_hi:[0,1]
	v_pk_add_f32 v[168:169], v[168:169], v[176:177] neg_lo:[0,1] neg_hi:[0,1]
	v_pk_add_f32 v[170:171], v[170:171], v[178:179] neg_lo:[0,1] neg_hi:[0,1]
	v_pk_mul_f32 v[164:165], v[164:165], v[124:125]
	v_pk_mul_f32 v[166:167], v[166:167], v[126:127]
	v_pk_mul_f32 v[168:169], v[168:169], v[128:129]
	v_pk_mul_f32 v[170:171], v[170:171], v[130:131]
	v_cvt_pk_bf16_f32 v156, v164, v165
	v_cvt_pk_bf16_f32 v157, v166, v167
	v_cvt_pk_bf16_f32 v158, v168, v169
	v_cvt_pk_bf16_f32 v159, v170, v171
	global_store_dwordx2 v218, v[156:157], s[10:11]
	global_store_dwordx2 v219, v[158:159], s[10:11]
	v_add_u32_e32 v210, 0x2c00, v210
	v_add_u32_e32 v211, 0x2c00, v210
	v_add_u32_e32 v212, v206, v211
	global_load_dwordx2 v[96:97], v212, s[6:7]
	v_add_u32_e32 v213, v207, v211
	global_load_dwordx2 v[98:99], v213, s[6:7]
	v_add_u32_e32 v214, v208, v211
	global_load_dwordx2 v[100:101], v214, s[6:7]
	v_add_u32_e32 v215, v209, v211
	global_load_dwordx2 v[102:103], v215, s[6:7]
	v_add_u32_e32 v218, v207, v210
	global_load_dwordx2 v[116:117], v218, s[8:9]
	v_add_u32_e32 v219, v208, v210
	global_load_dwordx2 v[118:119], v219, s[8:9]
	s_waitcnt vmcnt(16)
	v_lshlrev_b32_e32 v56, 16, v104
	v_and_b32_e32 v57, 0xffff0000, v104
	v_lshlrev_b32_e32 v58, 16, v105
	v_and_b32_e32 v59, 0xffff0000, v105
	v_lshlrev_b32_e32 v60, 16, v106
	v_and_b32_e32 v61, 0xffff0000, v106
	v_lshlrev_b32_e32 v62, 16, v107
	v_and_b32_e32 v63, 0xffff0000, v107
	v_lshlrev_b32_e32 v64, 16, v108
	v_and_b32_e32 v65, 0xffff0000, v108
	v_lshlrev_b32_e32 v66, 16, v109
	v_and_b32_e32 v67, 0xffff0000, v109
	v_lshlrev_b32_e32 v68, 16, v110
	v_and_b32_e32 v69, 0xffff0000, v110
	v_lshlrev_b32_e32 v70, 16, v111
	v_and_b32_e32 v71, 0xffff0000, v111
	v_pk_mul_f32 v[56:57], v[56:57], v[200:201]
	v_pk_mul_f32 v[58:59], v[58:59], v[200:201]
	v_pk_mul_f32 v[68:69], v[68:69], v[202:203]
	v_pk_mul_f32 v[70:71], v[70:71], v[202:203]
	v_lshlrev_b32_e32 v124, 16, v120
	v_and_b32_e32 v125, 0xffff0000, v120
	v_lshlrev_b32_e32 v126, 16, v121
	v_and_b32_e32 v127, 0xffff0000, v121
	v_lshlrev_b32_e32 v128, 16, v122
	v_and_b32_e32 v129, 0xffff0000, v122
	v_lshlrev_b32_e32 v130, 16, v123
	v_and_b32_e32 v131, 0xffff0000, v123
	v_pk_fma_f32 v[148:149], v[72:73], v[0:1], v[36:37]
	v_pk_fma_f32 v[150:151], v[74:75], v[2:3], v[38:39]
	v_pk_fma_f32 v[152:153], v[76:77], v[0:1], v[36:37]
	v_pk_fma_f32 v[154:155], v[78:79], v[2:3], v[38:39]
	v_pk_fma_f32 v[148:149], v[40:41], v[4:5], v[148:149]
	v_pk_fma_f32 v[150:151], v[42:43], v[6:7], v[150:151]
	v_pk_fma_f32 v[152:153], v[44:45], v[4:5], v[152:153]
	v_pk_fma_f32 v[154:155], v[46:47], v[6:7], v[154:155]
	v_pk_fma_f32 v[148:149], v[56:57], v[8:9], v[148:149]
	v_pk_fma_f32 v[150:151], v[58:59], v[10:11], v[150:151]
	v_pk_fma_f32 v[152:153], v[60:61], v[8:9], v[152:153]
	v_pk_fma_f32 v[154:155], v[62:63], v[10:11], v[154:155]
	v_pk_fma_f32 v[148:149], v[76:77], v[12:13], v[148:149]
	v_pk_fma_f32 v[150:151], v[78:79], v[14:15], v[150:151]
	v_pk_fma_f32 v[152:153], v[80:81], v[12:13], v[152:153]
	v_pk_fma_f32 v[154:155], v[82:83], v[14:15], v[154:155]
	v_pk_fma_f32 v[148:149], v[44:45], v[16:17], v[148:149]
; __device__ __forceinline__ unsigned cvt_pk_bf16(float lo, float hi) { unsigned r; asm volatile("v_cvt_pk_bf16_f32 %0, %1, %2" : "=v"(r) : "v"(lo), "v"(hi)); return r; }
; __device__ __forceinline__ float gelu_as(float v) {
;   const float av = fabsf(v); const float t = __builtin_amdgcn_rcpf(av * 0.2316418882f + 1.0f);
;   float q = t * 0.5307027145f + (-0.7265760135f); q = q * t + 0.7107068705f; q = q * t + (-0.142248368f); q = q * t + 0.127414796f; q = q * t;
;   const float e = __builtin_amdgcn_exp2f((v * v) * (-0.72134752044f));
;   const float m = v * (q * e);
;   return v < 0.f ? m : v - m;
; }
; __device__ __forceinline__ void phase_conv(KP p, int l, int tid) {
;     ...
;       for (int q = 0; q < CB; ++q) {
;         const int col = jb + q + 1;
; #pragma unroll
;         for (int di = 0; di < RB + 2; ++di) { const bool ok = rv[di] && (col < 64); unpack4(an[q][di], win[2][di]);
; #pragma unroll
;           for (int k = 0; k < 4; ++k) win[2][di][k] = ok ? win[2][di][k] : 0.f; }
; #pragma unroll
;         for (int rr = 0; rr < RB; ++rr) {
;           float uv[4]; unpack4(ur[q][rr], uv);
;           float o[4];
; #pragma unroll
;           for (int k = 0; k < 4; ++k) {
;             float a = bsv[k];
; #pragma unroll
;             for (int di = 0; di < 3; ++di)
; #pragma unroll
;               for (int dj = 0; dj < 3; ++dj) a += win[dj][rr + di][k] * w[di * 3 + dj][k];
;             o[k] = gelu_as(a) * uv[k];
;           }
;           u32x2 ow; ow.x = cvt_pk_bf16(o[0], o[1]); ow.y = cvt_pk_bf16(o[2], o[3]);
;           *(u32x2*)(G + (size_t)((r0 + rr) * 64 + jb + q) * DFF + c0) = ow;
;         }
; #pragma unroll
;         for (int di = 0; di < RB + 2; ++di)
; #pragma unroll
;           for (int k = 0; k < 4; ++k) { win[0][di][k] = win[1][di][k]; win[1][di][k] = win[2][di][k]; }
	v_pk_fma_f32 v[150:151], v[46:47], v[18:19], v[150:151]
	v_pk_fma_f32 v[152:153], v[48:49], v[16:17], v[152:153]
	v_pk_fma_f32 v[154:155], v[50:51], v[18:19], v[154:155]
	v_pk_fma_f32 v[148:149], v[60:61], v[20:21], v[148:149]
	v_pk_fma_f32 v[150:151], v[62:63], v[22:23], v[150:151]
	v_pk_fma_f32 v[152:153], v[64:65], v[20:21], v[152:153]
	v_pk_fma_f32 v[154:155], v[66:67], v[22:23], v[154:155]
	v_pk_fma_f32 v[148:149], v[80:81], v[24:25], v[148:149]
	v_pk_fma_f32 v[150:151], v[82:83], v[26:27], v[150:151]
	v_pk_fma_f32 v[152:153], v[84:85], v[24:25], v[152:153]
	v_pk_fma_f32 v[154:155], v[86:87], v[26:27], v[154:155]
	v_pk_fma_f32 v[148:149], v[48:49], v[28:29], v[148:149]
	v_pk_fma_f32 v[150:151], v[50:51], v[30:31], v[150:151]
	v_pk_fma_f32 v[152:153], v[52:53], v[28:29], v[152:153]
	v_pk_fma_f32 v[154:155], v[54:55], v[30:31], v[154:155]
	v_pk_fma_f32 v[148:149], v[64:65], v[32:33], v[148:149]
	v_pk_fma_f32 v[150:151], v[66:67], v[34:35], v[150:151]
	v_pk_fma_f32 v[152:153], v[68:69], v[32:33], v[152:153]
	v_pk_fma_f32 v[154:155], v[70:71], v[34:35], v[154:155]
	v_and_b32_e32 v156, 0x7fffffff, v148
	v_and_b32_e32 v157, 0x7fffffff, v149
	v_and_b32_e32 v158, 0x7fffffff, v150
	v_and_b32_e32 v159, 0x7fffffff, v151
	v_and_b32_e32 v160, 0x7fffffff, v152
	v_and_b32_e32 v161, 0x7fffffff, v153
	v_and_b32_e32 v162, 0x7fffffff, v154
	v_and_b32_e32 v163, 0x7fffffff, v155
	v_pk_fma_f32 v[164:165], v[156:157], v[184:185], v[186:187]
	v_pk_fma_f32 v[166:167], v[158:159], v[184:185], v[186:187]
	v_pk_fma_f32 v[168:169], v[160:161], v[184:185], v[186:187]
	v_pk_fma_f32 v[170:171], v[162:163], v[184:185], v[186:187]
	v_rcp_f32_e32 v164, v164
	v_rcp_f32_e32 v165, v165
	v_rcp_f32_e32 v166, v166
	v_rcp_f32_e32 v167, v167
	v_rcp_f32_e32 v168, v168
	v_rcp_f32_e32 v169, v169
	v_rcp_f32_e32 v170, v170
	v_rcp_f32_e32 v171, v171
	v_pk_fma_f32 v[172:173], v[164:165], v[188:189], v[190:191]
	v_pk_fma_f32 v[174:175], v[166:167], v[188:189], v[190:191]
	v_pk_fma_f32 v[176:177], v[168:169], v[188:189], v[190:191]
	v_pk_fma_f32 v[178:179], v[170:171], v[188:189], v[190:191]
	v_pk_fma_f32 v[172:173], v[172:173], v[164:165], v[192:193]
	v_pk_fma_f32 v[174:175], v[174:175], v[166:167], v[192:193]
	v_pk_fma_f32 v[176:177], v[176:177], v[168:169], v[192:193]
	v_pk_fma_f32 v[178:179], v[178:179], v[170:171], v[192:193]
	v_pk_fma_f32 v[172:173], v[172:173], v[164:165], v[194:195]
	v_pk_fma_f32 v[174:175], v[174:175], v[166:167], v[194:195]
	v_pk_fma_f32 v[176:177], v[176:177], v[168:169], v[194:195]
	v_pk_fma_f32 v[178:179], v[178:179], v[170:171], v[194:195]
	v_pk_fma_f32 v[172:173], v[172:173], v[164:165], v[196:197]
	v_pk_fma_f32 v[174:175], v[174:175], v[166:167], v[196:197]
	v_pk_fma_f32 v[176:177], v[176:177], v[168:169], v[196:197]
	v_pk_fma_f32 v[178:179], v[178:179], v[170:171], v[196:197]
	v_pk_mul_f32 v[172:173], v[172:173], v[164:165]
	v_pk_mul_f32 v[174:175], v[174:175], v[166:167]
	v_pk_mul_f32 v[176:177], v[176:177], v[168:169]
	v_pk_mul_f32 v[178:179], v[178:179], v[170:171]
	v_pk_mul_f32 v[164:165], v[148:149], v[148:149]
	v_pk_mul_f32 v[166:167], v[150:151], v[150:151]
	v_pk_mul_f32 v[168:169], v[152:153], v[152:153]
	v_pk_mul_f32 v[170:171], v[154:155], v[154:155]
	v_pk_mul_f32 v[164:165], v[164:165], v[198:199]
	v_pk_mul_f32 v[166:167], v[166:167], v[198:199]
	v_pk_mul_f32 v[168:169], v[168:169], v[198:199]
	v_pk_mul_f32 v[170:171], v[170:171], v[198:199]
	v_exp_f32_e32 v164, v164
	v_exp_f32_e32 v165, v165
	v_exp_f32_e32 v166, v166
	v_exp_f32_e32 v167, v167
	v_exp_f32_e32 v168, v168
	v_exp_f32_e32 v169, v169
	v_exp_f32_e32 v170, v170
	v_exp_f32_e32 v171, v171
	v_pk_mul_f32 v[172:173], v[172:173], v[164:165]
	v_pk_mul_f32 v[174:175], v[174:175], v[166:167]
	v_pk_mul_f32 v[176:177], v[176:177], v[168:169]
	v_pk_mul_f32 v[178:179], v[178:179], v[170:171]
	v_pk_mul_f32 v[172:173], v[156:157], v[172:173]
	v_pk_mul_f32 v[174:175], v[158:159], v[174:175]
	v_pk_mul_f32 v[176:177], v[160:161], v[176:177]
	v_pk_mul_f32 v[178:179], v[162:163], v[178:179]
	v_max_f32_e32 v164, 0, v148
	v_max_f32_e32 v165, 0, v149
	v_max_f32_e32 v166, 0, v150
	v_max_f32_e32 v167, 0, v151
	v_max_f32_e32 v168, 0, v152
	v_max_f32_e32 v169, 0, v153
	v_max_f32_e32 v170, 0, v154
	v_max_f32_e32 v171, 0, v155
	v_pk_add_f32 v[164:165], v[164:165], v[172:173] neg_lo:[0,1] neg_hi:[0,1]
	v_pk_add_f32 v[166:167], v[166:167], v[174:175] neg_lo:[0,1] neg_hi:[0,1]
	v_pk_add_f32 v[168:169], v[168:169], v[176:177] neg_lo:[0,1] neg_hi:[0,1]
	v_pk_add_f32 v[170:171], v[170:171], v[178:179] neg_lo:[0,1] neg_hi:[0,1]
	v_pk_mul_f32 v[164:165], v[164:165], v[124:125]
	v_pk_mul_f32 v[166:167], v[166:167], v[126:127]
	v_pk_mul_f32 v[168:169], v[168:169], v[128:129]
	v_pk_mul_f32 v[170:171], v[170:171], v[130:131]
	v_cvt_pk_bf16_f32 v156, v164, v165
	v_cvt_pk_bf16_f32 v157, v166, v167
	v_cvt_pk_bf16_f32 v158, v168, v169
	v_cvt_pk_bf16_f32 v159, v170, v171
	global_store_dwordx2 v220, v[156:157], s[10:11]
	global_store_dwordx2 v221, v[158:159], s[10:11]
	v_add_u32_e32 v210, 0x2c00, v210
	v_add_u32_e32 v211, 0x2c00, v210
	v_add_u32_e32 v212, v206, v211
	global_load_dwordx2 v[104:105], v212, s[6:7]
	v_add_u32_e32 v213, v207, v211
	global_load_dwordx2 v[106:107], v213, s[6:7]
	v_add_u32_e32 v214, v208, v211
	global_load_dwordx2 v[108:109], v214, s[6:7]
	v_add_u32_e32 v215, v209, v211
	global_load_dwordx2 v[110:111], v215, s[6:7]
	v_add_u32_e32 v220, v207, v210
	global_load_dwordx2 v[120:121], v220, s[8:9]
	v_add_u32_e32 v221, v208, v210
	global_load_dwordx2 v[122:123], v221, s[8:9]
	s_waitcnt vmcnt(16)
; __device__ __forceinline__ unsigned cvt_pk_bf16(float lo, float hi) { unsigned r; asm volatile("v_cvt_pk_bf16_f32 %0, %1, %2" : "=v"(r) : "v"(lo), "v"(hi)); return r; }
; __device__ __forceinline__ float gelu_as(float v) {
;   const float av = fabsf(v); const float t = __builtin_amdgcn_rcpf(av * 0.2316418882f + 1.0f);
;   float q = t * 0.5307027145f + (-0.7265760135f); q = q * t + 0.7107068705f; q = q * t + (-0.142248368f); q = q * t + 0.127414796f; q = q * t;
;   const float e = __builtin_amdgcn_exp2f((v * v) * (-0.72134752044f));
;   const float m = v * (q * e);
;   return v < 0.f ? m : v - m;
; }
; __device__ __forceinline__ void phase_conv(KP p, int l, int tid) {
;     ...
;       for (int q = 0; q < CB; ++q) {
;         const int col = jb + q + 1;
; #pragma unroll
;         for (int di = 0; di < RB + 2; ++di) { const bool ok = rv[di] && (col < 64); unpack4(an[q][di], win[2][di]);
; #pragma unroll
;           for (int k = 0; k < 4; ++k) win[2][di][k] = ok ? win[2][di][k] : 0.f; }
; #pragma unroll
;         for (int rr = 0; rr < RB; ++rr) {
;           float uv[4]; unpack4(ur[q][rr], uv);
;           float o[4];
; #pragma unroll
;           for (int k = 0; k < 4; ++k) {
;             float a = bsv[k];
; #pragma unroll
;             for (int di = 0; di < 3; ++di)
; #pragma unroll
;               for (int dj = 0; dj < 3; ++dj) a += win[dj][rr + di][k] * w[di * 3 + dj][k];
;             o[k] = gelu_as(a) * uv[k];
;           }
;           u32x2 ow; ow.x = cvt_pk_bf16(o[0], o[1]); ow.y = cvt_pk_bf16(o[2], o[3]);
;           *(u32x2*)(G + (size_t)((r0 + rr) * 64 + jb + q) * DFF + c0) = ow;
;         }
; #pragma unroll
;         for (int di = 0; di < RB + 2; ++di)
; #pragma unroll
;           for (int k = 0; k < 4; ++k) { win[0][di][k] = win[1][di][k]; win[1][di][k] = win[2][di][k]; }
	v_lshlrev_b32_e32 v72, 16, v88
	v_and_b32_e32 v73, 0xffff0000, v88
	v_lshlrev_b32_e32 v74, 16, v89
	v_and_b32_e32 v75, 0xffff0000, v89
	v_lshlrev_b32_e32 v76, 16, v90
	v_and_b32_e32 v77, 0xffff0000, v90
	v_lshlrev_b32_e32 v78, 16, v91
	v_and_b32_e32 v79, 0xffff0000, v91
	v_lshlrev_b32_e32 v80, 16, v92
	v_and_b32_e32 v81, 0xffff0000, v92
	v_lshlrev_b32_e32 v82, 16, v93
	v_and_b32_e32 v83, 0xffff0000, v93
	v_lshlrev_b32_e32 v84, 16, v94
	v_and_b32_e32 v85, 0xffff0000, v94
	v_lshlrev_b32_e32 v86, 16, v95
	v_and_b32_e32 v87, 0xffff0000, v95
	v_pk_mul_f32 v[72:73], v[72:73], v[200:201]
	v_pk_mul_f32 v[74:75], v[74:75], v[200:201]
	v_pk_mul_f32 v[84:85], v[84:85], v[202:203]
	v_pk_mul_f32 v[86:87], v[86:87], v[202:203]
	v_lshlrev_b32_e32 v124, 16, v112
	v_and_b32_e32 v125, 0xffff0000, v112
	v_lshlrev_b32_e32 v126, 16, v113
	v_and_b32_e32 v127, 0xffff0000, v113
	v_lshlrev_b32_e32 v128, 16, v114
	v_and_b32_e32 v129, 0xffff0000, v114
	v_lshlrev_b32_e32 v130, 16, v115
	v_and_b32_e32 v131, 0xffff0000, v115
	v_pk_fma_f32 v[148:149], v[40:41], v[0:1], v[36:37]
	v_pk_fma_f32 v[150:151], v[42:43], v[2:3], v[38:39]
	v_pk_fma_f32 v[152:153], v[44:45], v[0:1], v[36:37]
	v_pk_fma_f32 v[154:155], v[46:47], v[2:3], v[38:39]
	v_pk_fma_f32 v[148:149], v[56:57], v[4:5], v[148:149]
	v_pk_fma_f32 v[150:151], v[58:59], v[6:7], v[150:151]
	v_pk_fma_f32 v[152:153], v[60:61], v[4:5], v[152:153]
	v_pk_fma_f32 v[154:155], v[62:63], v[6:7], v[154:155]
	v_pk_fma_f32 v[148:149], v[72:73], v[8:9], v[148:149]
	v_pk_fma_f32 v[150:151], v[74:75], v[10:11], v[150:151]
	v_pk_fma_f32 v[152:153], v[76:77], v[8:9], v[152:153]
	v_pk_fma_f32 v[154:155], v[78:79], v[10:11], v[154:155]
	v_pk_fma_f32 v[148:149], v[44:45], v[12:13], v[148:149]
	v_pk_fma_f32 v[150:151], v[46:47], v[14:15], v[150:151]
	v_pk_fma_f32 v[152:153], v[48:49], v[12:13], v[152:153]
	v_pk_fma_f32 v[154:155], v[50:51], v[14:15], v[154:155]
	v_pk_fma_f32 v[148:149], v[60:61], v[16:17], v[148:149]
	v_pk_fma_f32 v[150:151], v[62:63], v[18:19], v[150:151]
	v_pk_fma_f32 v[152:153], v[64:65], v[16:17], v[152:153]
	v_pk_fma_f32 v[154:155], v[66:67], v[18:19], v[154:155]
	v_pk_fma_f32 v[148:149], v[76:77], v[20:21], v[148:149]
	v_pk_fma_f32 v[150:151], v[78:79], v[22:23], v[150:151]
	v_pk_fma_f32 v[152:153], v[80:81], v[20:21], v[152:153]
	v_pk_fma_f32 v[154:155], v[82:83], v[22:23], v[154:155]
	v_pk_fma_f32 v[148:149], v[48:49], v[24:25], v[148:149]
	v_pk_fma_f32 v[150:151], v[50:51], v[26:27], v[150:151]
	v_pk_fma_f32 v[152:153], v[52:53], v[24:25], v[152:153]
	v_pk_fma_f32 v[154:155], v[54:55], v[26:27], v[154:155]
	v_pk_fma_f32 v[148:149], v[64:65], v[28:29], v[148:149]
	v_pk_fma_f32 v[150:151], v[66:67], v[30:31], v[150:151]
	v_pk_fma_f32 v[152:153], v[68:69], v[28:29], v[152:153]
	v_pk_fma_f32 v[154:155], v[70:71], v[30:31], v[154:155]
	v_pk_fma_f32 v[148:149], v[80:81], v[32:33], v[148:149]
	v_pk_fma_f32 v[150:151], v[82:83], v[34:35], v[150:151]
	v_pk_fma_f32 v[152:153], v[84:85], v[32:33], v[152:153]
	v_pk_fma_f32 v[154:155], v[86:87], v[34:35], v[154:155]
	v_and_b32_e32 v156, 0x7fffffff, v148
	v_and_b32_e32 v157, 0x7fffffff, v149
	v_and_b32_e32 v158, 0x7fffffff, v150
	v_and_b32_e32 v159, 0x7fffffff, v151
	v_and_b32_e32 v160, 0x7fffffff, v152
	v_and_b32_e32 v161, 0x7fffffff, v153
	v_and_b32_e32 v162, 0x7fffffff, v154
	v_and_b32_e32 v163, 0x7fffffff, v155
	v_pk_fma_f32 v[164:165], v[156:157], v[184:185], v[186:187]
	v_pk_fma_f32 v[166:167], v[158:159], v[184:185], v[186:187]
	v_pk_fma_f32 v[168:169], v[160:161], v[184:185], v[186:187]
	v_pk_fma_f32 v[170:171], v[162:163], v[184:185], v[186:187]
	v_rcp_f32_e32 v164, v164
	v_rcp_f32_e32 v165, v165
	v_rcp_f32_e32 v166, v166
	v_rcp_f32_e32 v167, v167
	v_rcp_f32_e32 v168, v168
	v_rcp_f32_e32 v169, v169
	v_rcp_f32_e32 v170, v170
	v_rcp_f32_e32 v171, v171
	v_pk_fma_f32 v[172:173], v[164:165], v[188:189], v[190:191]
	v_pk_fma_f32 v[174:175], v[166:167], v[188:189], v[190:191]
	v_pk_fma_f32 v[176:177], v[168:169], v[188:189], v[190:191]
	v_pk_fma_f32 v[178:179], v[170:171], v[188:189], v[190:191]
	v_pk_fma_f32 v[172:173], v[172:173], v[164:165], v[192:193]
	v_pk_fma_f32 v[174:175], v[174:175], v[166:167], v[192:193]
	v_pk_fma_f32 v[176:177], v[176:177], v[168:169], v[192:193]
	v_pk_fma_f32 v[178:179], v[178:179], v[170:171], v[192:193]
	v_pk_fma_f32 v[172:173], v[172:173], v[164:165], v[194:195]
	v_pk_fma_f32 v[174:175], v[174:175], v[166:167], v[194:195]
	v_pk_fma_f32 v[176:177], v[176:177], v[168:169], v[194:195]
	v_pk_fma_f32 v[178:179], v[178:179], v[170:171], v[194:195]
	v_pk_fma_f32 v[172:173], v[172:173], v[164:165], v[196:197]
	v_pk_fma_f32 v[174:175], v[174:175], v[166:167], v[196:197]
	v_pk_fma_f32 v[176:177], v[176:177], v[168:169], v[196:197]
	v_pk_fma_f32 v[178:179], v[178:179], v[170:171], v[196:197]
	v_pk_mul_f32 v[172:173], v[172:173], v[164:165]
	v_pk_mul_f32 v[174:175], v[174:175], v[166:167]
	v_pk_mul_f32 v[176:177], v[176:177], v[168:169]
	v_pk_mul_f32 v[178:179], v[178:179], v[170:171]
	v_pk_mul_f32 v[164:165], v[148:149], v[148:149]
	v_pk_mul_f32 v[166:167], v[150:151], v[150:151]
	v_pk_mul_f32 v[168:169], v[152:153], v[152:153]
	v_pk_mul_f32 v[170:171], v[154:155], v[154:155]
	v_pk_mul_f32 v[164:165], v[164:165], v[198:199]
	v_pk_mul_f32 v[166:167], v[166:167], v[198:199]
	v_pk_mul_f32 v[168:169], v[168:169], v[198:199]
	v_pk_mul_f32 v[170:171], v[170:171], v[198:199]
	v_exp_f32_e32 v164, v164
	v_exp_f32_e32 v165, v165
	v_exp_f32_e32 v166, v166
	v_exp_f32_e32 v167, v167
	v_exp_f32_e32 v168, v168
	v_exp_f32_e32 v169, v169
	v_exp_f32_e32 v170, v170
	v_exp_f32_e32 v171, v171
	v_pk_mul_f32 v[172:173], v[172:173], v[164:165]
	v_pk_mul_f32 v[174:175], v[174:175], v[166:167]
; __device__ __forceinline__ unsigned cvt_pk_bf16(float lo, float hi) { unsigned r; asm volatile("v_cvt_pk_bf16_f32 %0, %1, %2" : "=v"(r) : "v"(lo), "v"(hi)); return r; }
; __device__ __forceinline__ float gelu_as(float v) {
;   const float av = fabsf(v); const float t = __builtin_amdgcn_rcpf(av * 0.2316418882f + 1.0f);
;   float q = t * 0.5307027145f + (-0.7265760135f); q = q * t + 0.7107068705f; q = q * t + (-0.142248368f); q = q * t + 0.127414796f; q = q * t;
;   const float e = __builtin_amdgcn_exp2f((v * v) * (-0.72134752044f));
;   const float m = v * (q * e);
;   return v < 0.f ? m : v - m;
; }
; __device__ __forceinline__ void phase_conv(KP p, int l, int tid) {
;     ...
;       for (int q = 0; q < CB; ++q) { const int col = jb + q + 1; const int cl = col > 63 ? 63 : col;
;     ...
;       for (int q = 0; q < CB; ++q) {
;         const int col = jb + q + 1;
; #pragma unroll
;         for (int di = 0; di < RB + 2; ++di) { const bool ok = rv[di] && (col < 64); unpack4(an[q][di], win[2][di]);
; #pragma unroll
;           for (int k = 0; k < 4; ++k) win[2][di][k] = ok ? win[2][di][k] : 0.f; }
; #pragma unroll
;         for (int rr = 0; rr < RB; ++rr) {
;           float uv[4]; unpack4(ur[q][rr], uv);
;           float o[4];
; #pragma unroll
;           for (int k = 0; k < 4; ++k) {
;             float a = bsv[k];
; #pragma unroll
;             for (int di = 0; di < 3; ++di)
; #pragma unroll
;               for (int dj = 0; dj < 3; ++dj) a += win[dj][rr + di][k] * w[di * 3 + dj][k];
;             o[k] = gelu_as(a) * uv[k];
;           }
;           u32x2 ow; ow.x = cvt_pk_bf16(o[0], o[1]); ow.y = cvt_pk_bf16(o[2], o[3]);
;           *(u32x2*)(G + (size_t)((r0 + rr) * 64 + jb + q) * DFF + c0) = ow;
;         }
; #pragma unroll
;         for (int di = 0; di < RB + 2; ++di)
; #pragma unroll
;           for (int k = 0; k < 4; ++k) { win[0][di][k] = win[1][di][k]; win[1][di][k] = win[2][di][k]; }
	v_pk_mul_f32 v[176:177], v[176:177], v[168:169]
	v_pk_mul_f32 v[178:179], v[178:179], v[170:171]
	v_pk_mul_f32 v[172:173], v[156:157], v[172:173]
	v_pk_mul_f32 v[174:175], v[158:159], v[174:175]
	v_pk_mul_f32 v[176:177], v[160:161], v[176:177]
	v_pk_mul_f32 v[178:179], v[162:163], v[178:179]
	v_max_f32_e32 v164, 0, v148
	v_max_f32_e32 v165, 0, v149
	v_max_f32_e32 v166, 0, v150
	v_max_f32_e32 v167, 0, v151
	v_max_f32_e32 v168, 0, v152
	v_max_f32_e32 v169, 0, v153
	v_max_f32_e32 v170, 0, v154
	v_max_f32_e32 v171, 0, v155
	v_pk_add_f32 v[164:165], v[164:165], v[172:173] neg_lo:[0,1] neg_hi:[0,1]
	v_pk_add_f32 v[166:167], v[166:167], v[174:175] neg_lo:[0,1] neg_hi:[0,1]
	v_pk_add_f32 v[168:169], v[168:169], v[176:177] neg_lo:[0,1] neg_hi:[0,1]
	v_pk_add_f32 v[170:171], v[170:171], v[178:179] neg_lo:[0,1] neg_hi:[0,1]
	v_pk_mul_f32 v[164:165], v[164:165], v[124:125]
	v_pk_mul_f32 v[166:167], v[166:167], v[126:127]
	v_pk_mul_f32 v[168:169], v[168:169], v[128:129]
	v_pk_mul_f32 v[170:171], v[170:171], v[130:131]
	v_cvt_pk_bf16_f32 v156, v164, v165
	v_cvt_pk_bf16_f32 v157, v166, v167
	v_cvt_pk_bf16_f32 v158, v168, v169
	v_cvt_pk_bf16_f32 v159, v170, v171
	global_store_dwordx2 v216, v[156:157], s[10:11]
	global_store_dwordx2 v217, v[158:159], s[10:11]
	v_add_u32_e32 v210, 0x2c00, v210
	v_add_u32_e32 v211, 0x2c00, v210
	v_min_u32_e32 v211, 0xad400, v211
	v_add_u32_e32 v212, v206, v211
	global_load_dwordx2 v[88:89], v212, s[6:7]
	v_add_u32_e32 v213, v207, v211
	global_load_dwordx2 v[90:91], v213, s[6:7]
	v_add_u32_e32 v214, v208, v211
	global_load_dwordx2 v[92:93], v214, s[6:7]
	v_add_u32_e32 v215, v209, v211
	global_load_dwordx2 v[94:95], v215, s[6:7]
	v_add_u32_e32 v216, v207, v210
	global_load_dwordx2 v[112:113], v216, s[8:9]
	v_add_u32_e32 v217, v208, v210
	global_load_dwordx2 v[114:115], v217, s[8:9]
	s_waitcnt vmcnt(16)
	v_lshlrev_b32_e32 v40, 16, v96
	v_and_b32_e32 v41, 0xffff0000, v96
	v_lshlrev_b32_e32 v42, 16, v97
	v_and_b32_e32 v43, 0xffff0000, v97
	v_lshlrev_b32_e32 v44, 16, v98
	v_and_b32_e32 v45, 0xffff0000, v98
	v_lshlrev_b32_e32 v46, 16, v99
	v_and_b32_e32 v47, 0xffff0000, v99
	v_lshlrev_b32_e32 v48, 16, v100
	v_and_b32_e32 v49, 0xffff0000, v100
	v_lshlrev_b32_e32 v50, 16, v101
	v_and_b32_e32 v51, 0xffff0000, v101
	v_lshlrev_b32_e32 v52, 16, v102
	v_and_b32_e32 v53, 0xffff0000, v102
	v_lshlrev_b32_e32 v54, 16, v103
	v_and_b32_e32 v55, 0xffff0000, v103
	v_pk_mul_f32 v[40:41], v[40:41], v[200:201]
	v_pk_mul_f32 v[42:43], v[42:43], v[200:201]
	v_pk_mul_f32 v[52:53], v[52:53], v[202:203]
	v_pk_mul_f32 v[54:55], v[54:55], v[202:203]
	v_lshlrev_b32_e32 v124, 16, v116
	v_and_b32_e32 v125, 0xffff0000, v116
	v_lshlrev_b32_e32 v126, 16, v117
	v_and_b32_e32 v127, 0xffff0000, v117
	v_lshlrev_b32_e32 v128, 16, v118
	v_and_b32_e32 v129, 0xffff0000, v118
	v_lshlrev_b32_e32 v130, 16, v119
	v_and_b32_e32 v131, 0xffff0000, v119
	v_pk_fma_f32 v[148:149], v[56:57], v[0:1], v[36:37]
	v_pk_fma_f32 v[150:151], v[58:59], v[2:3], v[38:39]
	v_pk_fma_f32 v[152:153], v[60:61], v[0:1], v[36:37]
	v_pk_fma_f32 v[154:155], v[62:63], v[2:3], v[38:39]
	v_pk_fma_f32 v[148:149], v[72:73], v[4:5], v[148:149]
	v_pk_fma_f32 v[150:151], v[74:75], v[6:7], v[150:151]
	v_pk_fma_f32 v[152:153], v[76:77], v[4:5], v[152:153]
	v_pk_fma_f32 v[154:155], v[78:79], v[6:7], v[154:155]
	v_pk_fma_f32 v[148:149], v[40:41], v[8:9], v[148:149]
	v_pk_fma_f32 v[150:151], v[42:43], v[10:11], v[150:151]
	v_pk_fma_f32 v[152:153], v[44:45], v[8:9], v[152:153]
	v_pk_fma_f32 v[154:155], v[46:47], v[10:11], v[154:155]
	v_pk_fma_f32 v[148:149], v[60:61], v[12:13], v[148:149]
	v_pk_fma_f32 v[150:151], v[62:63], v[14:15], v[150:151]
	v_pk_fma_f32 v[152:153], v[64:65], v[12:13], v[152:153]
	v_pk_fma_f32 v[154:155], v[66:67], v[14:15], v[154:155]
	v_pk_fma_f32 v[148:149], v[76:77], v[16:17], v[148:149]
	v_pk_fma_f32 v[150:151], v[78:79], v[18:19], v[150:151]
	v_pk_fma_f32 v[152:153], v[80:81], v[16:17], v[152:153]
	v_pk_fma_f32 v[154:155], v[82:83], v[18:19], v[154:155]
	v_pk_fma_f32 v[148:149], v[44:45], v[20:21], v[148:149]
	v_pk_fma_f32 v[150:151], v[46:47], v[22:23], v[150:151]
	v_pk_fma_f32 v[152:153], v[48:49], v[20:21], v[152:153]
	v_pk_fma_f32 v[154:155], v[50:51], v[22:23], v[154:155]
	v_pk_fma_f32 v[148:149], v[64:65], v[24:25], v[148:149]
	v_pk_fma_f32 v[150:151], v[66:67], v[26:27], v[150:151]
	v_pk_fma_f32 v[152:153], v[68:69], v[24:25], v[152:153]
	v_pk_fma_f32 v[154:155], v[70:71], v[26:27], v[154:155]
	v_pk_fma_f32 v[148:149], v[80:81], v[28:29], v[148:149]
	v_pk_fma_f32 v[150:151], v[82:83], v[30:31], v[150:151]
	v_pk_fma_f32 v[152:153], v[84:85], v[28:29], v[152:153]
	v_pk_fma_f32 v[154:155], v[86:87], v[30:31], v[154:155]
	v_pk_fma_f32 v[148:149], v[48:49], v[32:33], v[148:149]
	v_pk_fma_f32 v[150:151], v[50:51], v[34:35], v[150:151]
	v_pk_fma_f32 v[152:153], v[52:53], v[32:33], v[152:153]
	v_pk_fma_f32 v[154:155], v[54:55], v[34:35], v[154:155]
	v_and_b32_e32 v156, 0x7fffffff, v148
	v_and_b32_e32 v157, 0x7fffffff, v149
	v_and_b32_e32 v158, 0x7fffffff, v150
	v_and_b32_e32 v159, 0x7fffffff, v151
	v_and_b32_e32 v160, 0x7fffffff, v152
	v_and_b32_e32 v161, 0x7fffffff, v153
	v_and_b32_e32 v162, 0x7fffffff, v154
	v_and_b32_e32 v163, 0x7fffffff, v155
	v_pk_fma_f32 v[164:165], v[156:157], v[184:185], v[186:187]
	v_pk_fma_f32 v[166:167], v[158:159], v[184:185], v[186:187]
	v_pk_fma_f32 v[168:169], v[160:161], v[184:185], v[186:187]
	v_pk_fma_f32 v[170:171], v[162:163], v[184:185], v[186:187]
	v_rcp_f32_e32 v164, v164
	v_rcp_f32_e32 v165, v165
	v_rcp_f32_e32 v166, v166
	v_rcp_f32_e32 v167, v167
	v_rcp_f32_e32 v168, v168
	v_rcp_f32_e32 v169, v169
	v_rcp_f32_e32 v170, v170
	v_rcp_f32_e32 v171, v171
; __device__ __forceinline__ unsigned cvt_pk_bf16(float lo, float hi) { unsigned r; asm volatile("v_cvt_pk_bf16_f32 %0, %1, %2" : "=v"(r) : "v"(lo), "v"(hi)); return r; }
; __device__ __forceinline__ float gelu_as(float v) {
;   const float av = fabsf(v); const float t = __builtin_amdgcn_rcpf(av * 0.2316418882f + 1.0f);
;   float q = t * 0.5307027145f + (-0.7265760135f); q = q * t + 0.7107068705f; q = q * t + (-0.142248368f); q = q * t + 0.127414796f; q = q * t;
;   const float e = __builtin_amdgcn_exp2f((v * v) * (-0.72134752044f));
;   const float m = v * (q * e);
;   return v < 0.f ? m : v - m;
; }
; __device__ __forceinline__ void phase_conv(KP p, int l, int tid) {
;     ...
;       for (int q = 0; q < CB; ++q) {
;         const int col = jb + q + 1;
; #pragma unroll
;         for (int di = 0; di < RB + 2; ++di) { const bool ok = rv[di] && (col < 64); unpack4(an[q][di], win[2][di]);
; #pragma unroll
;           for (int k = 0; k < 4; ++k) win[2][di][k] = ok ? win[2][di][k] : 0.f; }
; #pragma unroll
;         for (int rr = 0; rr < RB; ++rr) {
;           float uv[4]; unpack4(ur[q][rr], uv);
;           float o[4];
; #pragma unroll
;           for (int k = 0; k < 4; ++k) {
;             float a = bsv[k];
; #pragma unroll
;             for (int di = 0; di < 3; ++di)
; #pragma unroll
;               for (int dj = 0; dj < 3; ++dj) a += win[dj][rr + di][k] * w[di * 3 + dj][k];
;             o[k] = gelu_as(a) * uv[k];
;           }
;           u32x2 ow; ow.x = cvt_pk_bf16(o[0], o[1]); ow.y = cvt_pk_bf16(o[2], o[3]);
;           *(u32x2*)(G + (size_t)((r0 + rr) * 64 + jb + q) * DFF + c0) = ow;
;         }
; #pragma unroll
;         for (int di = 0; di < RB + 2; ++di)
; #pragma unroll
;           for (int k = 0; k < 4; ++k) { win[0][di][k] = win[1][di][k]; win[1][di][k] = win[2][di][k]; }
	v_pk_fma_f32 v[172:173], v[164:165], v[188:189], v[190:191]
	v_pk_fma_f32 v[174:175], v[166:167], v[188:189], v[190:191]
	v_pk_fma_f32 v[176:177], v[168:169], v[188:189], v[190:191]
	v_pk_fma_f32 v[178:179], v[170:171], v[188:189], v[190:191]
	v_pk_fma_f32 v[172:173], v[172:173], v[164:165], v[192:193]
	v_pk_fma_f32 v[174:175], v[174:175], v[166:167], v[192:193]
	v_pk_fma_f32 v[176:177], v[176:177], v[168:169], v[192:193]
	v_pk_fma_f32 v[178:179], v[178:179], v[170:171], v[192:193]
	v_pk_fma_f32 v[172:173], v[172:173], v[164:165], v[194:195]
	v_pk_fma_f32 v[174:175], v[174:175], v[166:167], v[194:195]
	v_pk_fma_f32 v[176:177], v[176:177], v[168:169], v[194:195]
	v_pk_fma_f32 v[178:179], v[178:179], v[170:171], v[194:195]
	v_pk_fma_f32 v[172:173], v[172:173], v[164:165], v[196:197]
	v_pk_fma_f32 v[174:175], v[174:175], v[166:167], v[196:197]
	v_pk_fma_f32 v[176:177], v[176:177], v[168:169], v[196:197]
	v_pk_fma_f32 v[178:179], v[178:179], v[170:171], v[196:197]
	v_pk_mul_f32 v[172:173], v[172:173], v[164:165]
	v_pk_mul_f32 v[174:175], v[174:175], v[166:167]
	v_pk_mul_f32 v[176:177], v[176:177], v[168:169]
	v_pk_mul_f32 v[178:179], v[178:179], v[170:171]
	v_pk_mul_f32 v[164:165], v[148:149], v[148:149]
	v_pk_mul_f32 v[166:167], v[150:151], v[150:151]
	v_pk_mul_f32 v[168:169], v[152:153], v[152:153]
	v_pk_mul_f32 v[170:171], v[154:155], v[154:155]
	v_pk_mul_f32 v[164:165], v[164:165], v[198:199]
	v_pk_mul_f32 v[166:167], v[166:167], v[198:199]
	v_pk_mul_f32 v[168:169], v[168:169], v[198:199]
	v_pk_mul_f32 v[170:171], v[170:171], v[198:199]
	v_exp_f32_e32 v164, v164
	v_exp_f32_e32 v165, v165
	v_exp_f32_e32 v166, v166
	v_exp_f32_e32 v167, v167
	v_exp_f32_e32 v168, v168
	v_exp_f32_e32 v169, v169
	v_exp_f32_e32 v170, v170
	v_exp_f32_e32 v171, v171
	v_pk_mul_f32 v[172:173], v[172:173], v[164:165]
	v_pk_mul_f32 v[174:175], v[174:175], v[166:167]
	v_pk_mul_f32 v[176:177], v[176:177], v[168:169]
	v_pk_mul_f32 v[178:179], v[178:179], v[170:171]
	v_pk_mul_f32 v[172:173], v[156:157], v[172:173]
	v_pk_mul_f32 v[174:175], v[158:159], v[174:175]
	v_pk_mul_f32 v[176:177], v[160:161], v[176:177]
	v_pk_mul_f32 v[178:179], v[162:163], v[178:179]
	v_max_f32_e32 v164, 0, v148
	v_max_f32_e32 v165, 0, v149
	v_max_f32_e32 v166, 0, v150
	v_max_f32_e32 v167, 0, v151
	v_max_f32_e32 v168, 0, v152
	v_max_f32_e32 v169, 0, v153
	v_max_f32_e32 v170, 0, v154
	v_max_f32_e32 v171, 0, v155
	v_pk_add_f32 v[164:165], v[164:165], v[172:173] neg_lo:[0,1] neg_hi:[0,1]
	v_pk_add_f32 v[166:167], v[166:167], v[174:175] neg_lo:[0,1] neg_hi:[0,1]
	v_pk_add_f32 v[168:169], v[168:169], v[176:177] neg_lo:[0,1] neg_hi:[0,1]
	v_pk_add_f32 v[170:171], v[170:171], v[178:179] neg_lo:[0,1] neg_hi:[0,1]
	v_pk_mul_f32 v[164:165], v[164:165], v[124:125]
	v_pk_mul_f32 v[166:167], v[166:167], v[126:127]
	v_pk_mul_f32 v[168:169], v[168:169], v[128:129]
	v_pk_mul_f32 v[170:171], v[170:171], v[130:131]
	v_cvt_pk_bf16_f32 v156, v164, v165
	v_cvt_pk_bf16_f32 v157, v166, v167
	v_cvt_pk_bf16_f32 v158, v168, v169
	v_cvt_pk_bf16_f32 v159, v170, v171
	global_store_dwordx2 v218, v[156:157], s[10:11]
	global_store_dwordx2 v219, v[158:159], s[10:11]
	s_waitcnt vmcnt(10)
	v_lshlrev_b32_e32 v56, 16, v104
	v_and_b32_e32 v57, 0xffff0000, v104
	v_lshlrev_b32_e32 v58, 16, v105
	v_and_b32_e32 v59, 0xffff0000, v105
	v_lshlrev_b32_e32 v60, 16, v106
	v_and_b32_e32 v61, 0xffff0000, v106
	v_lshlrev_b32_e32 v62, 16, v107
	v_and_b32_e32 v63, 0xffff0000, v107
	v_lshlrev_b32_e32 v64, 16, v108
	v_and_b32_e32 v65, 0xffff0000, v108
	v_lshlrev_b32_e32 v66, 16, v109
	v_and_b32_e32 v67, 0xffff0000, v109
	v_lshlrev_b32_e32 v68, 16, v110
	v_and_b32_e32 v69, 0xffff0000, v110
	v_lshlrev_b32_e32 v70, 16, v111
	v_and_b32_e32 v71, 0xffff0000, v111
	v_pk_mul_f32 v[56:57], v[56:57], v[200:201]
	v_pk_mul_f32 v[58:59], v[58:59], v[200:201]
	v_pk_mul_f32 v[68:69], v[68:69], v[202:203]
	v_pk_mul_f32 v[70:71], v[70:71], v[202:203]
	v_lshlrev_b32_e32 v124, 16, v120
	v_and_b32_e32 v125, 0xffff0000, v120
	v_lshlrev_b32_e32 v126, 16, v121
	v_and_b32_e32 v127, 0xffff0000, v121
	v_lshlrev_b32_e32 v128, 16, v122
	v_and_b32_e32 v129, 0xffff0000, v122
	v_lshlrev_b32_e32 v130, 16, v123
	v_and_b32_e32 v131, 0xffff0000, v123
	v_pk_fma_f32 v[148:149], v[72:73], v[0:1], v[36:37]
	v_pk_fma_f32 v[150:151], v[74:75], v[2:3], v[38:39]
	v_pk_fma_f32 v[152:153], v[76:77], v[0:1], v[36:37]
	v_pk_fma_f32 v[154:155], v[78:79], v[2:3], v[38:39]
	v_pk_fma_f32 v[148:149], v[40:41], v[4:5], v[148:149]
	v_pk_fma_f32 v[150:151], v[42:43], v[6:7], v[150:151]
	v_pk_fma_f32 v[152:153], v[44:45], v[4:5], v[152:153]
	v_pk_fma_f32 v[154:155], v[46:47], v[6:7], v[154:155]
	v_pk_fma_f32 v[148:149], v[56:57], v[8:9], v[148:149]
	v_pk_fma_f32 v[150:151], v[58:59], v[10:11], v[150:151]
	v_pk_fma_f32 v[152:153], v[60:61], v[8:9], v[152:153]
	v_pk_fma_f32 v[154:155], v[62:63], v[10:11], v[154:155]
	v_pk_fma_f32 v[148:149], v[76:77], v[12:13], v[148:149]
	v_pk_fma_f32 v[150:151], v[78:79], v[14:15], v[150:151]
	v_pk_fma_f32 v[152:153], v[80:81], v[12:13], v[152:153]
	v_pk_fma_f32 v[154:155], v[82:83], v[14:15], v[154:155]
	v_pk_fma_f32 v[148:149], v[44:45], v[16:17], v[148:149]
	v_pk_fma_f32 v[150:151], v[46:47], v[18:19], v[150:151]
	v_pk_fma_f32 v[152:153], v[48:49], v[16:17], v[152:153]
	v_pk_fma_f32 v[154:155], v[50:51], v[18:19], v[154:155]
	v_pk_fma_f32 v[148:149], v[60:61], v[20:21], v[148:149]
	v_pk_fma_f32 v[150:151], v[62:63], v[22:23], v[150:151]
	v_pk_fma_f32 v[152:153], v[64:65], v[20:21], v[152:153]
	v_pk_fma_f32 v[154:155], v[66:67], v[22:23], v[154:155]
	v_pk_fma_f32 v[148:149], v[80:81], v[24:25], v[148:149]
	v_pk_fma_f32 v[150:151], v[82:83], v[26:27], v[150:151]
; __device__ __forceinline__ unsigned cvt_pk_bf16(float lo, float hi) { unsigned r; asm volatile("v_cvt_pk_bf16_f32 %0, %1, %2" : "=v"(r) : "v"(lo), "v"(hi)); return r; }
; __device__ __forceinline__ float gelu_as(float v) {
;   const float av = fabsf(v); const float t = __builtin_amdgcn_rcpf(av * 0.2316418882f + 1.0f);
;   float q = t * 0.5307027145f + (-0.7265760135f); q = q * t + 0.7107068705f; q = q * t + (-0.142248368f); q = q * t + 0.127414796f; q = q * t;
;   const float e = __builtin_amdgcn_exp2f((v * v) * (-0.72134752044f));
;   const float m = v * (q * e);
;   return v < 0.f ? m : v - m;
; }
; __device__ __forceinline__ void phase_conv(KP p, int l, int tid) {
;     ...
;       for (int q = 0; q < CB; ++q) {
;         const int col = jb + q + 1;
; #pragma unroll
;         for (int di = 0; di < RB + 2; ++di) { const bool ok = rv[di] && (col < 64); unpack4(an[q][di], win[2][di]);
; #pragma unroll
;           for (int k = 0; k < 4; ++k) win[2][di][k] = ok ? win[2][di][k] : 0.f; }
; #pragma unroll
;         for (int rr = 0; rr < RB; ++rr) {
;           float uv[4]; unpack4(ur[q][rr], uv);
;           float o[4];
; #pragma unroll
;           for (int k = 0; k < 4; ++k) {
;             float a = bsv[k];
; #pragma unroll
;             for (int di = 0; di < 3; ++di)
; #pragma unroll
;               for (int dj = 0; dj < 3; ++dj) a += win[dj][rr + di][k] * w[di * 3 + dj][k];
;             o[k] = gelu_as(a) * uv[k];
;           }
;           u32x2 ow; ow.x = cvt_pk_bf16(o[0], o[1]); ow.y = cvt_pk_bf16(o[2], o[3]);
;           *(u32x2*)(G + (size_t)((r0 + rr) * 64 + jb + q) * DFF + c0) = ow;
;         }
; #pragma unroll
;         for (int di = 0; di < RB + 2; ++di)
; #pragma unroll
;           for (int k = 0; k < 4; ++k) { win[0][di][k] = win[1][di][k]; win[1][di][k] = win[2][di][k]; }
	v_pk_fma_f32 v[152:153], v[84:85], v[24:25], v[152:153]
	v_pk_fma_f32 v[154:155], v[86:87], v[26:27], v[154:155]
	v_pk_fma_f32 v[148:149], v[48:49], v[28:29], v[148:149]
	v_pk_fma_f32 v[150:151], v[50:51], v[30:31], v[150:151]
	v_pk_fma_f32 v[152:153], v[52:53], v[28:29], v[152:153]
	v_pk_fma_f32 v[154:155], v[54:55], v[30:31], v[154:155]
	v_pk_fma_f32 v[148:149], v[64:65], v[32:33], v[148:149]
	v_pk_fma_f32 v[150:151], v[66:67], v[34:35], v[150:151]
	v_pk_fma_f32 v[152:153], v[68:69], v[32:33], v[152:153]
	v_pk_fma_f32 v[154:155], v[70:71], v[34:35], v[154:155]
	v_and_b32_e32 v156, 0x7fffffff, v148
	v_and_b32_e32 v157, 0x7fffffff, v149
	v_and_b32_e32 v158, 0x7fffffff, v150
	v_and_b32_e32 v159, 0x7fffffff, v151
	v_and_b32_e32 v160, 0x7fffffff, v152
	v_and_b32_e32 v161, 0x7fffffff, v153
	v_and_b32_e32 v162, 0x7fffffff, v154
	v_and_b32_e32 v163, 0x7fffffff, v155
	v_pk_fma_f32 v[164:165], v[156:157], v[184:185], v[186:187]
	v_pk_fma_f32 v[166:167], v[158:159], v[184:185], v[186:187]
	v_pk_fma_f32 v[168:169], v[160:161], v[184:185], v[186:187]
	v_pk_fma_f32 v[170:171], v[162:163], v[184:185], v[186:187]
	v_rcp_f32_e32 v164, v164
	v_rcp_f32_e32 v165, v165
	v_rcp_f32_e32 v166, v166
	v_rcp_f32_e32 v167, v167
	v_rcp_f32_e32 v168, v168
	v_rcp_f32_e32 v169, v169
	v_rcp_f32_e32 v170, v170
	v_rcp_f32_e32 v171, v171
	v_pk_fma_f32 v[172:173], v[164:165], v[188:189], v[190:191]
	v_pk_fma_f32 v[174:175], v[166:167], v[188:189], v[190:191]
	v_pk_fma_f32 v[176:177], v[168:169], v[188:189], v[190:191]
	v_pk_fma_f32 v[178:179], v[170:171], v[188:189], v[190:191]
	v_pk_fma_f32 v[172:173], v[172:173], v[164:165], v[192:193]
	v_pk_fma_f32 v[174:175], v[174:175], v[166:167], v[192:193]
	v_pk_fma_f32 v[176:177], v[176:177], v[168:169], v[192:193]
	v_pk_fma_f32 v[178:179], v[178:179], v[170:171], v[192:193]
	v_pk_fma_f32 v[172:173], v[172:173], v[164:165], v[194:195]
	v_pk_fma_f32 v[174:175], v[174:175], v[166:167], v[194:195]
	v_pk_fma_f32 v[176:177], v[176:177], v[168:169], v[194:195]
	v_pk_fma_f32 v[178:179], v[178:179], v[170:171], v[194:195]
	v_pk_fma_f32 v[172:173], v[172:173], v[164:165], v[196:197]
	v_pk_fma_f32 v[174:175], v[174:175], v[166:167], v[196:197]
	v_pk_fma_f32 v[176:177], v[176:177], v[168:169], v[196:197]
	v_pk_fma_f32 v[178:179], v[178:179], v[170:171], v[196:197]
	v_pk_mul_f32 v[172:173], v[172:173], v[164:165]
	v_pk_mul_f32 v[174:175], v[174:175], v[166:167]
	v_pk_mul_f32 v[176:177], v[176:177], v[168:169]
	v_pk_mul_f32 v[178:179], v[178:179], v[170:171]
	v_pk_mul_f32 v[164:165], v[148:149], v[148:149]
	v_pk_mul_f32 v[166:167], v[150:151], v[150:151]
	v_pk_mul_f32 v[168:169], v[152:153], v[152:153]
	v_pk_mul_f32 v[170:171], v[154:155], v[154:155]
	v_pk_mul_f32 v[164:165], v[164:165], v[198:199]
	v_pk_mul_f32 v[166:167], v[166:167], v[198:199]
	v_pk_mul_f32 v[168:169], v[168:169], v[198:199]
	v_pk_mul_f32 v[170:171], v[170:171], v[198:199]
	v_exp_f32_e32 v164, v164
	v_exp_f32_e32 v165, v165
	v_exp_f32_e32 v166, v166
	v_exp_f32_e32 v167, v167
	v_exp_f32_e32 v168, v168
	v_exp_f32_e32 v169, v169
	v_exp_f32_e32 v170, v170
	v_exp_f32_e32 v171, v171
	v_pk_mul_f32 v[172:173], v[172:173], v[164:165]
	v_pk_mul_f32 v[174:175], v[174:175], v[166:167]
	v_pk_mul_f32 v[176:177], v[176:177], v[168:169]
	v_pk_mul_f32 v[178:179], v[178:179], v[170:171]
	v_pk_mul_f32 v[172:173], v[156:157], v[172:173]
	v_pk_mul_f32 v[174:175], v[158:159], v[174:175]
	v_pk_mul_f32 v[176:177], v[160:161], v[176:177]
	v_pk_mul_f32 v[178:179], v[162:163], v[178:179]
	v_max_f32_e32 v164, 0, v148
	v_max_f32_e32 v165, 0, v149
	v_max_f32_e32 v166, 0, v150
	v_max_f32_e32 v167, 0, v151
	v_max_f32_e32 v168, 0, v152
	v_max_f32_e32 v169, 0, v153
	v_max_f32_e32 v170, 0, v154
	v_max_f32_e32 v171, 0, v155
	v_pk_add_f32 v[164:165], v[164:165], v[172:173] neg_lo:[0,1] neg_hi:[0,1]
	v_pk_add_f32 v[166:167], v[166:167], v[174:175] neg_lo:[0,1] neg_hi:[0,1]
	v_pk_add_f32 v[168:169], v[168:169], v[176:177] neg_lo:[0,1] neg_hi:[0,1]
	v_pk_add_f32 v[170:171], v[170:171], v[178:179] neg_lo:[0,1] neg_hi:[0,1]
	v_pk_mul_f32 v[164:165], v[164:165], v[124:125]
	v_pk_mul_f32 v[166:167], v[166:167], v[126:127]
	v_pk_mul_f32 v[168:169], v[168:169], v[128:129]
	v_pk_mul_f32 v[170:171], v[170:171], v[130:131]
	v_cvt_pk_bf16_f32 v156, v164, v165
	v_cvt_pk_bf16_f32 v157, v166, v167
	v_cvt_pk_bf16_f32 v158, v168, v169
	v_cvt_pk_bf16_f32 v159, v170, v171
	global_store_dwordx2 v220, v[156:157], s[10:11]
	global_store_dwordx2 v221, v[158:159], s[10:11]
	s_waitcnt vmcnt(4)
; __device__ __forceinline__ unsigned cvt_pk_bf16(float lo, float hi) { unsigned r; asm volatile("v_cvt_pk_bf16_f32 %0, %1, %2" : "=v"(r) : "v"(lo), "v"(hi)); return r; }
; __device__ __forceinline__ float gelu_as(float v) {
;   const float av = fabsf(v); const float t = __builtin_amdgcn_rcpf(av * 0.2316418882f + 1.0f);
;   float q = t * 0.5307027145f + (-0.7265760135f); q = q * t + 0.7107068705f; q = q * t + (-0.142248368f); q = q * t + 0.127414796f; q = q * t;
;   const float e = __builtin_amdgcn_exp2f((v * v) * (-0.72134752044f));
;   const float m = v * (q * e);
;   return v < 0.f ? m : v - m;
; }
; __device__ __forceinline__ void phase_conv(KP p, int l, int tid) {
;     ...
;       for (int q = 0; q < CB; ++q) {
;         const int col = jb + q + 1;
; #pragma unroll
;         for (int di = 0; di < RB + 2; ++di) { const bool ok = rv[di] && (col < 64); unpack4(an[q][di], win[2][di]);
; #pragma unroll
;           for (int k = 0; k < 4; ++k) win[2][di][k] = ok ? win[2][di][k] : 0.f; }
; #pragma unroll
;         for (int rr = 0; rr < RB; ++rr) {
;           float uv[4]; unpack4(ur[q][rr], uv);
;           float o[4];
; #pragma unroll
;           for (int k = 0; k < 4; ++k) {
;             float a = bsv[k];
; #pragma unroll
;             for (int di = 0; di < 3; ++di)
; #pragma unroll
;               for (int dj = 0; dj < 3; ++dj) a += win[dj][rr + di][k] * w[di * 3 + dj][k];
;             o[k] = gelu_as(a) * uv[k];
;           }
;           u32x2 ow; ow.x = cvt_pk_bf16(o[0], o[1]); ow.y = cvt_pk_bf16(o[2], o[3]);
;           *(u32x2*)(G + (size_t)((r0 + rr) * 64 + jb + q) * DFF + c0) = ow;
;         }
; #pragma unroll
;         for (int di = 0; di < RB + 2; ++di)
; #pragma unroll
;           for (int k = 0; k < 4; ++k) { win[0][di][k] = win[1][di][k]; win[1][di][k] = win[2][di][k]; }
	v_lshlrev_b32_e32 v72, 16, v88
	v_and_b32_e32 v73, 0xffff0000, v88
	v_lshlrev_b32_e32 v74, 16, v89
	v_and_b32_e32 v75, 0xffff0000, v89
	v_lshlrev_b32_e32 v76, 16, v90
	v_and_b32_e32 v77, 0xffff0000, v90
	v_lshlrev_b32_e32 v78, 16, v91
	v_and_b32_e32 v79, 0xffff0000, v91
	v_lshlrev_b32_e32 v80, 16, v92
	v_and_b32_e32 v81, 0xffff0000, v92
	v_lshlrev_b32_e32 v82, 16, v93
	v_and_b32_e32 v83, 0xffff0000, v93
	v_lshlrev_b32_e32 v84, 16, v94
	v_and_b32_e32 v85, 0xffff0000, v94
	v_lshlrev_b32_e32 v86, 16, v95
	v_and_b32_e32 v87, 0xffff0000, v95
	v_pk_mul_f32 v[72:73], v[72:73], v[200:201]
	v_pk_mul_f32 v[74:75], v[74:75], v[200:201]
	v_pk_mul_f32 v[84:85], v[84:85], v[202:203]
	v_pk_mul_f32 v[86:87], v[86:87], v[202:203]
	v_pk_mul_f32 v[72:73], v[72:73], v[204:205]
	v_pk_mul_f32 v[74:75], v[74:75], v[204:205]
	v_pk_mul_f32 v[76:77], v[76:77], v[204:205]
	v_pk_mul_f32 v[78:79], v[78:79], v[204:205]
	v_pk_mul_f32 v[80:81], v[80:81], v[204:205]
	v_pk_mul_f32 v[82:83], v[82:83], v[204:205]
	v_pk_mul_f32 v[84:85], v[84:85], v[204:205]
	v_pk_mul_f32 v[86:87], v[86:87], v[204:205]
	v_lshlrev_b32_e32 v124, 16, v112
	v_and_b32_e32 v125, 0xffff0000, v112
	v_lshlrev_b32_e32 v126, 16, v113
	v_and_b32_e32 v127, 0xffff0000, v113
	v_lshlrev_b32_e32 v128, 16, v114
	v_and_b32_e32 v129, 0xffff0000, v114
	v_lshlrev_b32_e32 v130, 16, v115
	v_and_b32_e32 v131, 0xffff0000, v115
	v_pk_fma_f32 v[148:149], v[40:41], v[0:1], v[36:37]
	v_pk_fma_f32 v[150:151], v[42:43], v[2:3], v[38:39]
	v_pk_fma_f32 v[152:153], v[44:45], v[0:1], v[36:37]
	v_pk_fma_f32 v[154:155], v[46:47], v[2:3], v[38:39]
	v_pk_fma_f32 v[148:149], v[56:57], v[4:5], v[148:149]
	v_pk_fma_f32 v[150:151], v[58:59], v[6:7], v[150:151]
	v_pk_fma_f32 v[152:153], v[60:61], v[4:5], v[152:153]
	v_pk_fma_f32 v[154:155], v[62:63], v[6:7], v[154:155]
	v_pk_fma_f32 v[148:149], v[72:73], v[8:9], v[148:149]
	v_pk_fma_f32 v[150:151], v[74:75], v[10:11], v[150:151]
	v_pk_fma_f32 v[152:153], v[76:77], v[8:9], v[152:153]
	v_pk_fma_f32 v[154:155], v[78:79], v[10:11], v[154:155]
	v_pk_fma_f32 v[148:149], v[44:45], v[12:13], v[148:149]
	v_pk_fma_f32 v[150:151], v[46:47], v[14:15], v[150:151]
	v_pk_fma_f32 v[152:153], v[48:49], v[12:13], v[152:153]
	v_pk_fma_f32 v[154:155], v[50:51], v[14:15], v[154:155]
	v_pk_fma_f32 v[148:149], v[60:61], v[16:17], v[148:149]
	v_pk_fma_f32 v[150:151], v[62:63], v[18:19], v[150:151]
	v_pk_fma_f32 v[152:153], v[64:65], v[16:17], v[152:153]
	v_pk_fma_f32 v[154:155], v[66:67], v[18:19], v[154:155]
	v_pk_fma_f32 v[148:149], v[76:77], v[20:21], v[148:149]
	v_pk_fma_f32 v[150:151], v[78:79], v[22:23], v[150:151]
	v_pk_fma_f32 v[152:153], v[80:81], v[20:21], v[152:153]
	v_pk_fma_f32 v[154:155], v[82:83], v[22:23], v[154:155]
	v_pk_fma_f32 v[148:149], v[48:49], v[24:25], v[148:149]
	v_pk_fma_f32 v[150:151], v[50:51], v[26:27], v[150:151]
	v_pk_fma_f32 v[152:153], v[52:53], v[24:25], v[152:153]
	v_pk_fma_f32 v[154:155], v[54:55], v[26:27], v[154:155]
	v_pk_fma_f32 v[148:149], v[64:65], v[28:29], v[148:149]
	v_pk_fma_f32 v[150:151], v[66:67], v[30:31], v[150:151]
	v_pk_fma_f32 v[152:153], v[68:69], v[28:29], v[152:153]
	v_pk_fma_f32 v[154:155], v[70:71], v[30:31], v[154:155]
	v_pk_fma_f32 v[148:149], v[80:81], v[32:33], v[148:149]
	v_pk_fma_f32 v[150:151], v[82:83], v[34:35], v[150:151]
	v_pk_fma_f32 v[152:153], v[84:85], v[32:33], v[152:153]
	v_pk_fma_f32 v[154:155], v[86:87], v[34:35], v[154:155]
	v_and_b32_e32 v156, 0x7fffffff, v148
	v_and_b32_e32 v157, 0x7fffffff, v149
	v_and_b32_e32 v158, 0x7fffffff, v150
	v_and_b32_e32 v159, 0x7fffffff, v151
	v_and_b32_e32 v160, 0x7fffffff, v152
	v_and_b32_e32 v161, 0x7fffffff, v153
	v_and_b32_e32 v162, 0x7fffffff, v154
	v_and_b32_e32 v163, 0x7fffffff, v155
	v_pk_fma_f32 v[164:165], v[156:157], v[184:185], v[186:187]
; __device__ __forceinline__ unsigned cvt_pk_bf16(float lo, float hi) { unsigned r; asm volatile("v_cvt_pk_bf16_f32 %0, %1, %2" : "=v"(r) : "v"(lo), "v"(hi)); return r; }
; __device__ __forceinline__ float gelu_as(float v) {
;   const float av = fabsf(v); const float t = __builtin_amdgcn_rcpf(av * 0.2316418882f + 1.0f);
;   float q = t * 0.5307027145f + (-0.7265760135f); q = q * t + 0.7107068705f; q = q * t + (-0.142248368f); q = q * t + 0.127414796f; q = q * t;
;   const float e = __builtin_amdgcn_exp2f((v * v) * (-0.72134752044f));
;   const float m = v * (q * e);
;   return v < 0.f ? m : v - m;
; }
; __device__ __forceinline__ void phase_conv(KP p, int l, int tid) {
;     ...
;   for (int it = blockIdx.x * NTH + tid; it < total; it += gridDim.x * NTH) {
;     ...
;       for (int q = 0; q < CB; ++q) {
;         const int col = jb + q + 1;
; #pragma unroll
;         for (int di = 0; di < RB + 2; ++di) { const bool ok = rv[di] && (col < 64); unpack4(an[q][di], win[2][di]);
; #pragma unroll
;           for (int k = 0; k < 4; ++k) win[2][di][k] = ok ? win[2][di][k] : 0.f; }
; #pragma unroll
;         for (int rr = 0; rr < RB; ++rr) {
;           float uv[4]; unpack4(ur[q][rr], uv);
;           float o[4];
; #pragma unroll
;           for (int k = 0; k < 4; ++k) {
;             float a = bsv[k];
; #pragma unroll
;             for (int di = 0; di < 3; ++di)
; #pragma unroll
;               for (int dj = 0; dj < 3; ++dj) a += win[dj][rr + di][k] * w[di * 3 + dj][k];
;             o[k] = gelu_as(a) * uv[k];
;           }
;           u32x2 ow; ow.x = cvt_pk_bf16(o[0], o[1]); ow.y = cvt_pk_bf16(o[2], o[3]);
;           *(u32x2*)(G + (size_t)((r0 + rr) * 64 + jb + q) * DFF + c0) = ow;
;         }
; #pragma unroll
;         for (int di = 0; di < RB + 2; ++di)
; #pragma unroll
;           for (int k = 0; k < 4; ++k) { win[0][di][k] = win[1][di][k]; win[1][di][k] = win[2][di][k]; }
	v_pk_fma_f32 v[166:167], v[158:159], v[184:185], v[186:187]
	v_pk_fma_f32 v[168:169], v[160:161], v[184:185], v[186:187]
	v_pk_fma_f32 v[170:171], v[162:163], v[184:185], v[186:187]
	v_rcp_f32_e32 v164, v164
	v_rcp_f32_e32 v165, v165
	v_rcp_f32_e32 v166, v166
	v_rcp_f32_e32 v167, v167
	v_rcp_f32_e32 v168, v168
	v_rcp_f32_e32 v169, v169
	v_rcp_f32_e32 v170, v170
	v_rcp_f32_e32 v171, v171
	v_pk_fma_f32 v[172:173], v[164:165], v[188:189], v[190:191]
	v_pk_fma_f32 v[174:175], v[166:167], v[188:189], v[190:191]
	v_pk_fma_f32 v[176:177], v[168:169], v[188:189], v[190:191]
	v_pk_fma_f32 v[178:179], v[170:171], v[188:189], v[190:191]
	v_pk_fma_f32 v[172:173], v[172:173], v[164:165], v[192:193]
	v_pk_fma_f32 v[174:175], v[174:175], v[166:167], v[192:193]
	v_pk_fma_f32 v[176:177], v[176:177], v[168:169], v[192:193]
	v_pk_fma_f32 v[178:179], v[178:179], v[170:171], v[192:193]
	v_pk_fma_f32 v[172:173], v[172:173], v[164:165], v[194:195]
	v_pk_fma_f32 v[174:175], v[174:175], v[166:167], v[194:195]
	v_pk_fma_f32 v[176:177], v[176:177], v[168:169], v[194:195]
	v_pk_fma_f32 v[178:179], v[178:179], v[170:171], v[194:195]
	v_pk_fma_f32 v[172:173], v[172:173], v[164:165], v[196:197]
	v_pk_fma_f32 v[174:175], v[174:175], v[166:167], v[196:197]
	v_pk_fma_f32 v[176:177], v[176:177], v[168:169], v[196:197]
	v_pk_fma_f32 v[178:179], v[178:179], v[170:171], v[196:197]
	v_pk_mul_f32 v[172:173], v[172:173], v[164:165]
	v_pk_mul_f32 v[174:175], v[174:175], v[166:167]
	v_pk_mul_f32 v[176:177], v[176:177], v[168:169]
	v_pk_mul_f32 v[178:179], v[178:179], v[170:171]
	v_pk_mul_f32 v[164:165], v[148:149], v[148:149]
	v_pk_mul_f32 v[166:167], v[150:151], v[150:151]
	v_pk_mul_f32 v[168:169], v[152:153], v[152:153]
	v_pk_mul_f32 v[170:171], v[154:155], v[154:155]
	v_pk_mul_f32 v[164:165], v[164:165], v[198:199]
	v_pk_mul_f32 v[166:167], v[166:167], v[198:199]
	v_pk_mul_f32 v[168:169], v[168:169], v[198:199]
	v_pk_mul_f32 v[170:171], v[170:171], v[198:199]
	v_exp_f32_e32 v164, v164
	v_exp_f32_e32 v165, v165
	v_exp_f32_e32 v166, v166
	v_exp_f32_e32 v167, v167
	v_exp_f32_e32 v168, v168
	v_exp_f32_e32 v169, v169
	v_exp_f32_e32 v170, v170
	v_exp_f32_e32 v171, v171
	v_pk_mul_f32 v[172:173], v[172:173], v[164:165]
	v_pk_mul_f32 v[174:175], v[174:175], v[166:167]
	v_pk_mul_f32 v[176:177], v[176:177], v[168:169]
	v_pk_mul_f32 v[178:179], v[178:179], v[170:171]
	v_pk_mul_f32 v[172:173], v[156:157], v[172:173]
	v_pk_mul_f32 v[174:175], v[158:159], v[174:175]
	v_pk_mul_f32 v[176:177], v[160:161], v[176:177]
	v_pk_mul_f32 v[178:179], v[162:163], v[178:179]
	v_max_f32_e32 v164, 0, v148
	v_max_f32_e32 v165, 0, v149
	v_max_f32_e32 v166, 0, v150
	v_max_f32_e32 v167, 0, v151
	v_max_f32_e32 v168, 0, v152
	v_max_f32_e32 v169, 0, v153
	v_max_f32_e32 v170, 0, v154
	v_max_f32_e32 v171, 0, v155
	v_pk_add_f32 v[164:165], v[164:165], v[172:173] neg_lo:[0,1] neg_hi:[0,1]
	v_pk_add_f32 v[166:167], v[166:167], v[174:175] neg_lo:[0,1] neg_hi:[0,1]
	v_pk_add_f32 v[168:169], v[168:169], v[176:177] neg_lo:[0,1] neg_hi:[0,1]
	v_pk_add_f32 v[170:171], v[170:171], v[178:179] neg_lo:[0,1] neg_hi:[0,1]
	v_pk_mul_f32 v[164:165], v[164:165], v[124:125]
	v_pk_mul_f32 v[166:167], v[166:167], v[126:127]
	v_pk_mul_f32 v[168:169], v[168:169], v[128:129]
	v_pk_mul_f32 v[170:171], v[170:171], v[130:131]
	v_cvt_pk_bf16_f32 v156, v164, v165
	v_cvt_pk_bf16_f32 v157, v166, v167
	v_cvt_pk_bf16_f32 v158, v168, v169
	v_cvt_pk_bf16_f32 v159, v170, v171
	global_store_dwordx2 v216, v[156:157], s[10:11]
	global_store_dwordx2 v217, v[158:159], s[10:11]
	v_add_u32_e32 v142, s73, v142
	s_mov_b32 s0, 0xaffff
	v_cmp_lt_i32_e32 vcc, s0, v142
	s_or_b64 s[28:29], vcc, s[28:29]
	s_andn2_b64 exec, exec, s[28:29]
	s_cbranch_execnz .Lcv_item
